# static s_setprio 1 for waves 0-3 at entry, all other s_setprio deleted (on v12)
# speedup vs baseline: 1.0113x; 1.0000x over previous
_Z6mk_fwd4Args:
	s_mov_b32 s100, 0
	s_mov_b32 s74, s2
	s_load_dword s2, s[0:1], 0x98
	s_load_dwordx4 s[76:79], s[0:1], 0x80
	s_load_dwordx2 s[52:53], s[0:1], 0x90
	s_add_u32 s4, s0, 0x90
	v_and_b32_e32 v171, 0x3ff, v0
	s_addc_u32 s5, s1, 0
	v_readfirstlane_b32 s48, v171
	v_cmp_gt_u32_e32 vcc, 2, v171
	s_waitcnt lgkmcnt(0)
	s_cmp_ge_u32 s48, 0x100
	s_cbranch_scc1 .Lmy_prio_done
	s_setprio 1
.Lmy_prio_done:
	v_writelane_b32 v246, s2, 0
	s_and_saveexec_b64 s[2:3], vcc
	v_lshl_add_u32 v1, v171, 2, 0
	v_add_u32_e32 v1, 0x20000, v1
	v_mov_b32_e32 v2, 0
	ds_write_b32 v1, v2
	s_or_b64 exec, exec, s[2:3]
	s_add_u32 s2, s76, 0x280000
	s_addc_u32 s3, s77, 0
	v_writelane_b32 v246, s2, 1
	s_sub_i32 s10, s79, s78
	s_cmp_lt_i32 s10, 2
	v_writelane_b32 v246, s3, 2
	s_mov_b32 s2, 0
	v_cmp_eq_u32_e32 vcc, 0, v171
	s_waitcnt lgkmcnt(0)
	s_barrier
	v_writelane_b32 v246, s2, 3
	s_cbranch_scc1 .LBB0_7
	s_getreg_b32 s2, hwreg(HW_REG_XCC_ID, 0, 4)
	s_and_b32 s2, s2, 15
	v_writelane_b32 v246, s2, 3
	s_and_saveexec_b64 s[2:3], vcc
	s_cbranch_execz .LBB0_6
	s_mov_b64 s[6:7], exec
	v_mbcnt_lo_u32_b32 v1, s6, 0
	v_mbcnt_hi_u32_b32 v1, s7, v1
	v_cmp_eq_u32_e32 vcc, 0, v1
	s_and_b64 s[8:9], exec, vcc
	s_mov_b64 exec, s[8:9]
	s_cbranch_execz .LBB0_6
	v_readlane_b32 s8, v246, 3
	s_bcnt1_i32_b64 s6, s[6:7]
	s_lshl_b32 s8, s8, 8
	v_mov_b32_e32 v2, s6
	v_readlane_b32 s6, v246, 1
	v_mov_b32_e32 v1, s8
	v_readlane_b32 s7, v246, 2
	s_nop 4
	global_atomic_add v1, v2, s[6:7] offset:1024
	v_readlane_b32 s8, v246, 3
	s_and_b32 s9, s74, 7
	s_lshl_b32 s9, s9, 2
	s_addk_i32 s9, 0x3700
	v_mov_b32_e32 v1, s9
	s_add_i32 s9, s8, 1
	v_mov_b32_e32 v2, s9
	s_sub_i32 s8, 16, s8
	v_mov_b32_e32 v3, s8
	global_atomic_umax v1, v2, s[6:7]
	global_atomic_umax v1, v3, s[6:7] offset:256

.LBB0_124:
	ds_read_b128 v[128:131], v161
	ds_read_b128 v[132:135], v161 offset:1024
	ds_read_b128 v[152:155], v161 offset:2048
	ds_read_b128 v[164:167], v161 offset:3072
	ds_read_b128 v[172:175], v162
	ds_read_b128 v[176:179], v162 offset:1024
	ds_read_b128 v[180:183], v162 offset:2048
	ds_read_b128 v[184:187], v162 offset:3072
	s_add_u32 s26, s2, 0xfffc0080
	s_addc_u32 s27, s3, -1
	s_cmp_eq_u32 s47, 12
	s_cselect_b32 s29, s5, s27
	s_cselect_b32 s28, s19, s26
	s_cselect_b32 s27, s17, s46
	s_cselect_b32 s26, s25, s33
	v_lshl_add_u64 v[156:157], s[2:3], 0, v[144:145]
	s_add_i32 m0, s34, 0xc000
	ds_read_b128 v[188:191], v163
	ds_read_b128 v[192:195], v163 offset:1024
	ds_read_b128 v[196:199], v163 offset:2048
	ds_read_b128 v[200:203], v163 offset:3072
	ds_read_b128 v[204:207], v163 offset:4096
	ds_read_b128 v[208:211], v163 offset:5120
	ds_read_b128 v[212:215], v163 offset:6144
	ds_read_b128 v[216:219], v163 offset:7168
	global_load_lds_dwordx4 v[156:157], off
	v_lshl_add_u64 v[156:157], s[2:3], 0, v[146:147]
	s_add_i32 m0, s34, 0xe000
	s_nop 0
	global_load_lds_dwordx4 v[156:157], off
	s_waitcnt vmcnt(8)
	s_waitcnt lgkmcnt(0)
	s_barrier
	s_waitcnt lgkmcnt(0)
	v_mfma_f32_16x16x32_bf16 v[124:127], v[128:131], v[188:191], v[124:127]
	v_mfma_f32_16x16x32_bf16 v[120:123], v[152:155], v[188:191], v[120:123]
	v_mfma_f32_16x16x32_bf16 v[108:111], v[128:131], v[196:199], v[108:111]
	v_mfma_f32_16x16x32_bf16 v[104:107], v[152:155], v[196:199], v[104:107]
	v_mfma_f32_16x16x32_bf16 v[92:95], v[128:131], v[204:207], v[92:95]
	v_mfma_f32_16x16x32_bf16 v[88:91], v[152:155], v[204:207], v[88:91]
	v_mfma_f32_16x16x32_bf16 v[76:79], v[128:131], v[212:215], v[76:79]
	v_mfma_f32_16x16x32_bf16 v[72:75], v[152:155], v[212:215], v[72:75]
	v_mfma_f32_16x16x32_bf16 v[124:127], v[132:135], v[192:195], v[124:127]
	v_mfma_f32_16x16x32_bf16 v[120:123], v[164:167], v[192:195], v[120:123]
	v_mfma_f32_16x16x32_bf16 v[108:111], v[132:135], v[200:203], v[108:111]
	v_mfma_f32_16x16x32_bf16 v[104:107], v[164:167], v[200:203], v[104:107]
	v_mfma_f32_16x16x32_bf16 v[92:95], v[132:135], v[208:211], v[92:95]
	v_mfma_f32_16x16x32_bf16 v[88:91], v[164:167], v[208:211], v[88:91]
	v_mfma_f32_16x16x32_bf16 v[76:79], v[132:135], v[216:219], v[76:79]
	v_mfma_f32_16x16x32_bf16 v[72:75], v[164:167], v[216:219], v[72:75]
	v_mfma_f32_16x16x32_bf16 v[116:119], v[172:175], v[188:191], v[116:119]
	v_mfma_f32_16x16x32_bf16 v[112:115], v[180:183], v[188:191], v[112:115]
	v_mfma_f32_16x16x32_bf16 v[100:103], v[172:175], v[196:199], v[100:103]
	v_mfma_f32_16x16x32_bf16 v[96:99], v[180:183], v[196:199], v[96:99]
	v_mfma_f32_16x16x32_bf16 v[84:87], v[172:175], v[204:207], v[84:87]
	v_mfma_f32_16x16x32_bf16 v[80:83], v[180:183], v[204:207], v[80:83]
	v_mfma_f32_16x16x32_bf16 v[68:71], v[172:175], v[212:215], v[68:71]
	v_mfma_f32_16x16x32_bf16 v[64:67], v[180:183], v[212:215], v[64:67]
	v_mfma_f32_16x16x32_bf16 v[116:119], v[176:179], v[192:195], v[116:119]
	v_mfma_f32_16x16x32_bf16 v[112:115], v[184:187], v[192:195], v[112:115]
	v_mfma_f32_16x16x32_bf16 v[100:103], v[176:179], v[200:203], v[100:103]
	v_mfma_f32_16x16x32_bf16 v[96:99], v[184:187], v[200:203], v[96:99]
	v_mfma_f32_16x16x32_bf16 v[84:87], v[176:179], v[208:211], v[84:87]
	v_mfma_f32_16x16x32_bf16 v[80:83], v[184:187], v[208:211], v[80:83]
	v_mfma_f32_16x16x32_bf16 v[68:71], v[176:179], v[216:219], v[68:71]
	v_mfma_f32_16x16x32_bf16 v[64:67], v[184:187], v[216:219], v[64:67]
	s_barrier
	s_add_i32 s49, s44, s31
	v_lshl_add_u64 v[156:157], s[26:27], 0, v[138:139]
	s_mov_b32 m0, s49
	ds_read_b128 v[188:191], v163 offset:16384
	ds_read_b128 v[192:195], v163 offset:17408
	ds_read_b128 v[196:199], v163 offset:18432
	ds_read_b128 v[200:203], v163 offset:19456
	ds_read_b128 v[204:207], v163 offset:20480
	ds_read_b128 v[208:211], v163 offset:21504
	ds_read_b128 v[212:215], v163 offset:22528
	ds_read_b128 v[216:219], v163 offset:23552
	global_load_lds_dwordx4 v[156:157], off
	s_add_i32 m0, s49, 0x2000
	s_add_u32 s50, s26, 0x40000
	v_lshl_add_u64 v[168:169], s[26:27], 0, v[142:143]
	s_addc_u32 s51, s27, 0
	s_add_i32 s49, s45, s31
	global_load_lds_dwordx4 v[168:169], off
	v_lshl_add_u64 v[220:221], s[50:51], 0, v[138:139]
	s_mov_b32 m0, s49
	v_lshl_add_u64 v[222:223], s[28:29], 0, v[140:141]
	global_load_lds_dwordx4 v[220:221], off
	v_lshl_add_u64 v[220:221], s[50:51], 0, v[142:143]
	s_add_i32 m0, s49, 0x2000
	s_nop 0
	global_load_lds_dwordx4 v[220:221], off
	v_lshl_add_u64 v[220:221], s[28:29], 0, v[136:137]
	s_mov_b32 m0, s34
	s_nop 0
	global_load_lds_dwordx4 v[220:221], off
	s_mov_b32 m0, s35
	s_nop 0
	global_load_lds_dwordx4 v[222:223], off
	s_waitcnt vmcnt(8)
	s_waitcnt lgkmcnt(0)
	s_barrier
	s_waitcnt lgkmcnt(0)
	v_mfma_f32_16x16x32_bf16 v[60:63], v[128:131], v[188:191], v[60:63]
	v_mfma_f32_16x16x32_bf16 v[56:59], v[152:155], v[188:191], v[56:59]
	v_mfma_f32_16x16x32_bf16 v[44:47], v[128:131], v[196:199], v[44:47]
	v_mfma_f32_16x16x32_bf16 v[40:43], v[152:155], v[196:199], v[40:43]
	v_mfma_f32_16x16x32_bf16 v[28:31], v[128:131], v[204:207], v[28:31]
	v_mfma_f32_16x16x32_bf16 v[24:27], v[152:155], v[204:207], v[24:27]
	v_mfma_f32_16x16x32_bf16 v[12:15], v[128:131], v[212:215], v[12:15]
	v_mfma_f32_16x16x32_bf16 v[8:11], v[152:155], v[212:215], v[8:11]
	v_mfma_f32_16x16x32_bf16 v[60:63], v[132:135], v[192:195], v[60:63]
	v_mfma_f32_16x16x32_bf16 v[56:59], v[164:167], v[192:195], v[56:59]
	v_mfma_f32_16x16x32_bf16 v[44:47], v[132:135], v[200:203], v[44:47]
	v_mfma_f32_16x16x32_bf16 v[40:43], v[164:167], v[200:203], v[40:43]
	v_mfma_f32_16x16x32_bf16 v[28:31], v[132:135], v[208:211], v[28:31]
	v_mfma_f32_16x16x32_bf16 v[24:27], v[164:167], v[208:211], v[24:27]
	v_mfma_f32_16x16x32_bf16 v[12:15], v[132:135], v[216:219], v[12:15]
	v_mfma_f32_16x16x32_bf16 v[8:11], v[164:167], v[216:219], v[8:11]
	v_mfma_f32_16x16x32_bf16 v[52:55], v[172:175], v[188:191], v[52:55]
	v_mfma_f32_16x16x32_bf16 v[48:51], v[180:183], v[188:191], v[48:51]
	v_mfma_f32_16x16x32_bf16 v[36:39], v[172:175], v[196:199], v[36:39]
	v_mfma_f32_16x16x32_bf16 v[32:35], v[180:183], v[196:199], v[32:35]
	v_mfma_f32_16x16x32_bf16 v[20:23], v[172:175], v[204:207], v[20:23]
	v_mfma_f32_16x16x32_bf16 v[16:19], v[180:183], v[204:207], v[16:19]
	v_mfma_f32_16x16x32_bf16 v[4:7], v[172:175], v[212:215], v[4:7]
	v_mfma_f32_16x16x32_bf16 v[0:3], v[180:183], v[212:215], v[0:3]
	v_mfma_f32_16x16x32_bf16 v[52:55], v[176:179], v[192:195], v[52:55]
	v_mfma_f32_16x16x32_bf16 v[48:51], v[184:187], v[192:195], v[48:51]
	v_mfma_f32_16x16x32_bf16 v[36:39], v[176:179], v[200:203], v[36:39]
	v_mfma_f32_16x16x32_bf16 v[32:35], v[184:187], v[200:203], v[32:35]
	v_mfma_f32_16x16x32_bf16 v[20:23], v[176:179], v[208:211], v[20:23]
	v_mfma_f32_16x16x32_bf16 v[16:19], v[184:187], v[208:211], v[16:19]
	v_mfma_f32_16x16x32_bf16 v[4:7], v[176:179], v[216:219], v[4:7]
	v_mfma_f32_16x16x32_bf16 v[0:3], v[184:187], v[216:219], v[0:3]
	s_barrier
	s_add_i32 s49, 0, 0x18000
	s_add_i32 s50, 0, 0x1c000
	v_add_u32_e32 v164, s49, v159
	v_add_u32_e32 v184, s50, v159
	ds_read_b128 v[128:131], v164
	ds_read_b128 v[132:135], v164 offset:1024
	ds_read_b128 v[152:155], v164 offset:2048
	ds_read_b128 v[164:167], v164 offset:3072
	ds_read_b128 v[172:175], v184
	ds_read_b128 v[176:179], v184 offset:1024
	ds_read_b128 v[180:183], v184 offset:2048
	ds_read_b128 v[184:187], v184 offset:3072
	s_add_u32 s28, s28, 0x40000
	s_addc_u32 s29, s29, 0
	s_mov_b32 m0, s36
	v_lshl_add_u64 v[224:225], s[28:29], 0, v[136:137]
	ds_read_b128 v[188:191], v163 offset:32768
	ds_read_b128 v[192:195], v163 offset:33792
	ds_read_b128 v[196:199], v163 offset:34816
	ds_read_b128 v[200:203], v163 offset:35840
	ds_read_b128 v[204:207], v163 offset:36864
	ds_read_b128 v[208:211], v163 offset:37888
	ds_read_b128 v[212:215], v163 offset:38912
	ds_read_b128 v[216:219], v163 offset:39936
	global_load_lds_dwordx4 v[224:225], off
	v_lshl_add_u64 v[224:225], s[28:29], 0, v[140:141]
	s_mov_b32 m0, s37
	s_nop 0
	global_load_lds_dwordx4 v[224:225], off
	s_waitcnt vmcnt(8)
	s_waitcnt lgkmcnt(0)
	s_barrier
	s_waitcnt lgkmcnt(0)
	v_mfma_f32_16x16x32_bf16 v[124:127], v[128:131], v[188:191], v[124:127]
	v_mfma_f32_16x16x32_bf16 v[120:123], v[152:155], v[188:191], v[120:123]
	v_mfma_f32_16x16x32_bf16 v[108:111], v[128:131], v[196:199], v[108:111]
	v_mfma_f32_16x16x32_bf16 v[104:107], v[152:155], v[196:199], v[104:107]
	v_mfma_f32_16x16x32_bf16 v[92:95], v[128:131], v[204:207], v[92:95]
	v_mfma_f32_16x16x32_bf16 v[88:91], v[152:155], v[204:207], v[88:91]
	v_mfma_f32_16x16x32_bf16 v[76:79], v[128:131], v[212:215], v[76:79]
	v_mfma_f32_16x16x32_bf16 v[72:75], v[152:155], v[212:215], v[72:75]
	v_mfma_f32_16x16x32_bf16 v[124:127], v[132:135], v[192:195], v[124:127]
	v_mfma_f32_16x16x32_bf16 v[120:123], v[164:167], v[192:195], v[120:123]
	v_mfma_f32_16x16x32_bf16 v[108:111], v[132:135], v[200:203], v[108:111]
	v_mfma_f32_16x16x32_bf16 v[104:107], v[164:167], v[200:203], v[104:107]
	v_mfma_f32_16x16x32_bf16 v[92:95], v[132:135], v[208:211], v[92:95]
	v_mfma_f32_16x16x32_bf16 v[88:91], v[164:167], v[208:211], v[88:91]
	v_mfma_f32_16x16x32_bf16 v[76:79], v[132:135], v[216:219], v[76:79]
	v_mfma_f32_16x16x32_bf16 v[72:75], v[164:167], v[216:219], v[72:75]
	v_mfma_f32_16x16x32_bf16 v[116:119], v[172:175], v[188:191], v[116:119]
	v_mfma_f32_16x16x32_bf16 v[112:115], v[180:183], v[188:191], v[112:115]
	v_mfma_f32_16x16x32_bf16 v[100:103], v[172:175], v[196:199], v[100:103]
	v_mfma_f32_16x16x32_bf16 v[96:99], v[180:183], v[196:199], v[96:99]
	v_mfma_f32_16x16x32_bf16 v[84:87], v[172:175], v[204:207], v[84:87]
	v_mfma_f32_16x16x32_bf16 v[80:83], v[180:183], v[204:207], v[80:83]
	v_mfma_f32_16x16x32_bf16 v[68:71], v[172:175], v[212:215], v[68:71]
	v_mfma_f32_16x16x32_bf16 v[64:67], v[180:183], v[212:215], v[64:67]
	v_mfma_f32_16x16x32_bf16 v[116:119], v[176:179], v[192:195], v[116:119]
	v_mfma_f32_16x16x32_bf16 v[112:115], v[184:187], v[192:195], v[112:115]
	v_mfma_f32_16x16x32_bf16 v[100:103], v[176:179], v[200:203], v[100:103]
	v_mfma_f32_16x16x32_bf16 v[96:99], v[184:187], v[200:203], v[96:99]
	v_mfma_f32_16x16x32_bf16 v[84:87], v[176:179], v[208:211], v[84:87]
	v_mfma_f32_16x16x32_bf16 v[80:83], v[184:187], v[208:211], v[80:83]
	v_mfma_f32_16x16x32_bf16 v[68:71], v[176:179], v[216:219], v[68:71]
	v_mfma_f32_16x16x32_bf16 v[64:67], v[184:187], v[216:219], v[64:67]
	s_barrier
	s_add_i32 s28, s49, s31
	v_lshl_add_u64 v[156:157], v[156:157], 0, s[10:11]
	s_mov_b32 m0, s28
	ds_read_b128 v[188:191], v163 offset:49152
	ds_read_b128 v[192:195], v163 offset:50176
	ds_read_b128 v[196:199], v163 offset:51200
	ds_read_b128 v[200:203], v163 offset:52224
	ds_read_b128 v[204:207], v163 offset:53248
	ds_read_b128 v[208:211], v163 offset:54272
	ds_read_b128 v[212:215], v163 offset:55296
	ds_read_b128 v[216:219], v163 offset:56320
	global_load_lds_dwordx4 v[156:157], off
	s_add_i32 m0, s28, 0x2000
	s_add_u32 s26, s26, 0x40080
	v_lshl_add_u64 v[156:157], v[168:169], 0, s[10:11]
	s_addc_u32 s27, s27, 0
	s_add_i32 s28, s50, s31
	global_load_lds_dwordx4 v[156:157], off
	v_lshl_add_u64 v[156:157], s[26:27], 0, v[138:139]
	s_mov_b32 m0, s28
	s_nop 0
	global_load_lds_dwordx4 v[156:157], off
	v_lshl_add_u64 v[156:157], s[26:27], 0, v[142:143]
	s_add_i32 m0, s28, 0x2000
	s_nop 0
	global_load_lds_dwordx4 v[156:157], off
	v_lshl_add_u64 v[156:157], v[220:221], 0, s[10:11]
	s_mov_b32 m0, s41
	s_nop 0
	global_load_lds_dwordx4 v[156:157], off
	v_lshl_add_u64 v[156:157], v[222:223], 0, s[10:11]
	s_mov_b32 m0, s42
	s_nop 0
	global_load_lds_dwordx4 v[156:157], off
	s_waitcnt vmcnt(8)
	s_waitcnt lgkmcnt(0)
	s_barrier
	s_waitcnt lgkmcnt(0)
	v_mfma_f32_16x16x32_bf16 v[60:63], v[128:131], v[188:191], v[60:63]
	v_mfma_f32_16x16x32_bf16 v[56:59], v[152:155], v[188:191], v[56:59]
	v_mfma_f32_16x16x32_bf16 v[44:47], v[128:131], v[196:199], v[44:47]
	v_mfma_f32_16x16x32_bf16 v[40:43], v[152:155], v[196:199], v[40:43]
	v_mfma_f32_16x16x32_bf16 v[28:31], v[128:131], v[204:207], v[28:31]
	v_mfma_f32_16x16x32_bf16 v[24:27], v[152:155], v[204:207], v[24:27]
	v_mfma_f32_16x16x32_bf16 v[12:15], v[128:131], v[212:215], v[12:15]
	v_mfma_f32_16x16x32_bf16 v[8:11], v[152:155], v[212:215], v[8:11]
	v_mfma_f32_16x16x32_bf16 v[60:63], v[132:135], v[192:195], v[60:63]
	v_mfma_f32_16x16x32_bf16 v[56:59], v[164:167], v[192:195], v[56:59]
	v_mfma_f32_16x16x32_bf16 v[44:47], v[132:135], v[200:203], v[44:47]
	v_mfma_f32_16x16x32_bf16 v[40:43], v[164:167], v[200:203], v[40:43]
	v_mfma_f32_16x16x32_bf16 v[28:31], v[132:135], v[208:211], v[28:31]
	v_mfma_f32_16x16x32_bf16 v[24:27], v[164:167], v[208:211], v[24:27]
	v_mfma_f32_16x16x32_bf16 v[12:15], v[132:135], v[216:219], v[12:15]
	v_mfma_f32_16x16x32_bf16 v[8:11], v[164:167], v[216:219], v[8:11]
	v_mfma_f32_16x16x32_bf16 v[52:55], v[172:175], v[188:191], v[52:55]
	v_mfma_f32_16x16x32_bf16 v[48:51], v[180:183], v[188:191], v[48:51]
	v_mfma_f32_16x16x32_bf16 v[36:39], v[172:175], v[196:199], v[36:39]
	v_mfma_f32_16x16x32_bf16 v[32:35], v[180:183], v[196:199], v[32:35]
	v_mfma_f32_16x16x32_bf16 v[20:23], v[172:175], v[204:207], v[20:23]
	v_mfma_f32_16x16x32_bf16 v[16:19], v[180:183], v[204:207], v[16:19]
	v_mfma_f32_16x16x32_bf16 v[4:7], v[172:175], v[212:215], v[4:7]
	v_mfma_f32_16x16x32_bf16 v[0:3], v[180:183], v[212:215], v[0:3]
	v_mfma_f32_16x16x32_bf16 v[52:55], v[176:179], v[192:195], v[52:55]
	v_mfma_f32_16x16x32_bf16 v[48:51], v[184:187], v[192:195], v[48:51]
	v_mfma_f32_16x16x32_bf16 v[36:39], v[176:179], v[200:203], v[36:39]
	v_mfma_f32_16x16x32_bf16 v[32:35], v[184:187], v[200:203], v[32:35]
	v_mfma_f32_16x16x32_bf16 v[20:23], v[176:179], v[208:211], v[20:23]
	v_mfma_f32_16x16x32_bf16 v[16:19], v[184:187], v[208:211], v[16:19]
	v_mfma_f32_16x16x32_bf16 v[4:7], v[176:179], v[216:219], v[4:7]
	v_mfma_f32_16x16x32_bf16 v[0:3], v[184:187], v[216:219], v[0:3]
	s_barrier
	s_add_i32 s47, s47, 2
	s_add_u32 s2, s2, 0x100
	s_addc_u32 s3, s3, 0
	s_add_u32 s33, s33, 0x100
	s_addc_u32 s46, s46, 0
	s_cmp_gt_u32 s47, 13
	s_cbranch_scc0 .LBB0_124
	s_and_b64 vcc, exec, s[12:13]
	s_cbranch_vccz .LBB0_127
	s_barrier

.LBB0_457:
	ds_read_b128 v[152:155], v148
	ds_read_b128 v[156:159], v148 offset:1024
	ds_read_b128 v[160:163], v148 offset:2048
	ds_read_b128 v[164:167], v148 offset:3072
	ds_read_b128 v[172:175], v149
	ds_read_b128 v[176:179], v149 offset:1024
	ds_read_b128 v[180:183], v149 offset:2048
	ds_read_b128 v[184:187], v149 offset:3072
	s_add_u32 s22, s20, 0xfffc0080
	s_addc_u32 s23, s21, -1
	s_cmp_eq_u32 s46, 12
	s_cselect_b32 s25, s13, s23
	s_cselect_b32 s24, s42, s22
	s_cselect_b32 s23, s11, s45
	s_cselect_b32 s22, s43, s44
	v_lshl_add_u64 v[168:169], s[20:21], 0, v[136:137]
	s_add_i32 m0, s19, 0xc000
	ds_read_b128 v[188:191], v150
	ds_read_b128 v[192:195], v150 offset:1024
	ds_read_b128 v[196:199], v150 offset:2048
	ds_read_b128 v[200:203], v150 offset:3072
	ds_read_b128 v[204:207], v150 offset:4096
	ds_read_b128 v[208:211], v150 offset:5120
	ds_read_b128 v[212:215], v150 offset:6144
	ds_read_b128 v[216:219], v150 offset:7168
	global_load_lds_dwordx4 v[168:169], off
	v_lshl_add_u64 v[168:169], s[20:21], 0, v[138:139]
	s_add_i32 m0, s19, 0xe000
	s_nop 0
	global_load_lds_dwordx4 v[168:169], off
	s_waitcnt vmcnt(8)
	s_waitcnt lgkmcnt(0)
	s_barrier
	s_waitcnt lgkmcnt(0)
	v_mfma_f32_16x16x32_bf16 v[124:127], v[152:155], v[188:191], v[124:127]
	v_mfma_f32_16x16x32_bf16 v[120:123], v[160:163], v[188:191], v[120:123]
	v_mfma_f32_16x16x32_bf16 v[116:119], v[152:155], v[196:199], v[116:119]
	v_mfma_f32_16x16x32_bf16 v[108:111], v[160:163], v[196:199], v[108:111]
	v_mfma_f32_16x16x32_bf16 v[100:103], v[152:155], v[204:207], v[100:103]
	v_mfma_f32_16x16x32_bf16 v[92:95], v[160:163], v[204:207], v[92:95]
	v_mfma_f32_16x16x32_bf16 v[84:87], v[152:155], v[212:215], v[84:87]
	v_mfma_f32_16x16x32_bf16 v[76:79], v[160:163], v[212:215], v[76:79]
	v_mfma_f32_16x16x32_bf16 v[124:127], v[156:159], v[192:195], v[124:127]
	v_mfma_f32_16x16x32_bf16 v[120:123], v[164:167], v[192:195], v[120:123]
	v_mfma_f32_16x16x32_bf16 v[116:119], v[156:159], v[200:203], v[116:119]
	v_mfma_f32_16x16x32_bf16 v[108:111], v[164:167], v[200:203], v[108:111]
	v_mfma_f32_16x16x32_bf16 v[100:103], v[156:159], v[208:211], v[100:103]
	v_mfma_f32_16x16x32_bf16 v[92:95], v[164:167], v[208:211], v[92:95]
	v_mfma_f32_16x16x32_bf16 v[84:87], v[156:159], v[216:219], v[84:87]
	v_mfma_f32_16x16x32_bf16 v[76:79], v[164:167], v[216:219], v[76:79]
	v_mfma_f32_16x16x32_bf16 v[112:115], v[172:175], v[188:191], v[112:115]
	v_mfma_f32_16x16x32_bf16 v[104:107], v[180:183], v[188:191], v[104:107]
	v_mfma_f32_16x16x32_bf16 v[96:99], v[172:175], v[196:199], v[96:99]
	v_mfma_f32_16x16x32_bf16 v[88:91], v[180:183], v[196:199], v[88:91]
	v_mfma_f32_16x16x32_bf16 v[80:83], v[172:175], v[204:207], v[80:83]
	v_mfma_f32_16x16x32_bf16 v[72:75], v[180:183], v[204:207], v[72:75]
	v_mfma_f32_16x16x32_bf16 v[68:71], v[172:175], v[212:215], v[68:71]
	v_mfma_f32_16x16x32_bf16 v[64:67], v[180:183], v[212:215], v[64:67]
	v_mfma_f32_16x16x32_bf16 v[112:115], v[176:179], v[192:195], v[112:115]
	v_mfma_f32_16x16x32_bf16 v[104:107], v[184:187], v[192:195], v[104:107]
	v_mfma_f32_16x16x32_bf16 v[96:99], v[176:179], v[200:203], v[96:99]
	v_mfma_f32_16x16x32_bf16 v[88:91], v[184:187], v[200:203], v[88:91]
	v_mfma_f32_16x16x32_bf16 v[80:83], v[176:179], v[208:211], v[80:83]
	v_mfma_f32_16x16x32_bf16 v[72:75], v[184:187], v[208:211], v[72:75]
	v_mfma_f32_16x16x32_bf16 v[68:71], v[176:179], v[216:219], v[68:71]
	v_mfma_f32_16x16x32_bf16 v[64:67], v[184:187], v[216:219], v[64:67]
	s_barrier
	s_add_i32 s47, s38, s26
	v_lshl_add_u64 v[168:169], s[22:23], 0, v[130:131]
	s_mov_b32 m0, s47
	ds_read_b128 v[188:191], v150 offset:16384
	ds_read_b128 v[192:195], v150 offset:17408
	ds_read_b128 v[196:199], v150 offset:18432
	ds_read_b128 v[200:203], v150 offset:19456
	ds_read_b128 v[204:207], v150 offset:20480
	ds_read_b128 v[208:211], v150 offset:21504
	ds_read_b128 v[212:215], v150 offset:22528
	ds_read_b128 v[216:219], v150 offset:23552
	global_load_lds_dwordx4 v[168:169], off
	s_add_i32 m0, s47, 0x2000
	s_add_u32 s48, s22, 0x40000
	v_lshl_add_u64 v[220:221], s[22:23], 0, v[134:135]
	s_addc_u32 s49, s23, 0
	s_add_i32 s47, s39, s26
	global_load_lds_dwordx4 v[220:221], off
	v_lshl_add_u64 v[222:223], s[48:49], 0, v[130:131]
	s_mov_b32 m0, s47
	v_lshl_add_u64 v[224:225], s[24:25], 0, v[132:133]
	global_load_lds_dwordx4 v[222:223], off
	v_lshl_add_u64 v[222:223], s[48:49], 0, v[134:135]
	s_add_i32 m0, s47, 0x2000
	s_nop 0
	global_load_lds_dwordx4 v[222:223], off
	v_lshl_add_u64 v[222:223], s[24:25], 0, v[128:129]
	s_mov_b32 m0, s19
	s_nop 0
	global_load_lds_dwordx4 v[222:223], off
	s_mov_b32 m0, s29
	s_nop 0
	global_load_lds_dwordx4 v[224:225], off
	s_waitcnt vmcnt(8)
	s_waitcnt lgkmcnt(0)
	s_barrier
	s_waitcnt lgkmcnt(0)
	v_mfma_f32_16x16x32_bf16 v[60:63], v[152:155], v[188:191], v[60:63]
	v_mfma_f32_16x16x32_bf16 v[56:59], v[160:163], v[188:191], v[56:59]
	v_mfma_f32_16x16x32_bf16 v[52:55], v[152:155], v[196:199], v[52:55]
	v_mfma_f32_16x16x32_bf16 v[44:47], v[160:163], v[196:199], v[44:47]
	v_mfma_f32_16x16x32_bf16 v[36:39], v[152:155], v[204:207], v[36:39]
	v_mfma_f32_16x16x32_bf16 v[28:31], v[160:163], v[204:207], v[28:31]
	v_mfma_f32_16x16x32_bf16 v[20:23], v[152:155], v[212:215], v[20:23]
	v_mfma_f32_16x16x32_bf16 v[12:15], v[160:163], v[212:215], v[12:15]
	v_mfma_f32_16x16x32_bf16 v[60:63], v[156:159], v[192:195], v[60:63]
	v_mfma_f32_16x16x32_bf16 v[56:59], v[164:167], v[192:195], v[56:59]
	v_mfma_f32_16x16x32_bf16 v[52:55], v[156:159], v[200:203], v[52:55]
	v_mfma_f32_16x16x32_bf16 v[44:47], v[164:167], v[200:203], v[44:47]
	v_mfma_f32_16x16x32_bf16 v[36:39], v[156:159], v[208:211], v[36:39]
	v_mfma_f32_16x16x32_bf16 v[28:31], v[164:167], v[208:211], v[28:31]
	v_mfma_f32_16x16x32_bf16 v[20:23], v[156:159], v[216:219], v[20:23]
	v_mfma_f32_16x16x32_bf16 v[12:15], v[164:167], v[216:219], v[12:15]
	v_mfma_f32_16x16x32_bf16 v[48:51], v[172:175], v[188:191], v[48:51]
	v_mfma_f32_16x16x32_bf16 v[40:43], v[180:183], v[188:191], v[40:43]
	v_mfma_f32_16x16x32_bf16 v[32:35], v[172:175], v[196:199], v[32:35]
	v_mfma_f32_16x16x32_bf16 v[24:27], v[180:183], v[196:199], v[24:27]
	v_mfma_f32_16x16x32_bf16 v[16:19], v[172:175], v[204:207], v[16:19]
	v_mfma_f32_16x16x32_bf16 v[8:11], v[180:183], v[204:207], v[8:11]
	v_mfma_f32_16x16x32_bf16 v[4:7], v[172:175], v[212:215], v[4:7]
	v_mfma_f32_16x16x32_bf16 v[0:3], v[180:183], v[212:215], v[0:3]
	v_mfma_f32_16x16x32_bf16 v[48:51], v[176:179], v[192:195], v[48:51]
	v_mfma_f32_16x16x32_bf16 v[40:43], v[184:187], v[192:195], v[40:43]
	v_mfma_f32_16x16x32_bf16 v[32:35], v[176:179], v[200:203], v[32:35]
	v_mfma_f32_16x16x32_bf16 v[24:27], v[184:187], v[200:203], v[24:27]
	v_mfma_f32_16x16x32_bf16 v[16:19], v[176:179], v[208:211], v[16:19]
	v_mfma_f32_16x16x32_bf16 v[8:11], v[184:187], v[208:211], v[8:11]
	v_mfma_f32_16x16x32_bf16 v[4:7], v[176:179], v[216:219], v[4:7]
	v_mfma_f32_16x16x32_bf16 v[0:3], v[184:187], v[216:219], v[0:3]
	s_barrier
	s_add_i32 s47, 0, 0x18000
	v_add_u32_e32 v144, s47, v146
	s_add_i32 s48, 0, 0x1c000
	ds_read_b128 v[152:155], v144
	ds_read_b128 v[156:159], v144 offset:1024
	ds_read_b128 v[160:163], v144 offset:2048
	ds_read_b128 v[164:167], v144 offset:3072
	v_add_u32_e32 v144, s48, v146
	ds_read_b128 v[172:175], v144
	ds_read_b128 v[176:179], v144 offset:1024
	ds_read_b128 v[180:183], v144 offset:2048
	ds_read_b128 v[184:187], v144 offset:3072
	s_add_u32 s24, s24, 0x40000
	s_addc_u32 s25, s25, 0
	s_mov_b32 m0, s30
	v_lshl_add_u64 v[226:227], s[24:25], 0, v[128:129]
	ds_read_b128 v[188:191], v150 offset:32768
	ds_read_b128 v[192:195], v150 offset:33792
	ds_read_b128 v[196:199], v150 offset:34816
	ds_read_b128 v[200:203], v150 offset:35840
	ds_read_b128 v[204:207], v150 offset:36864
	ds_read_b128 v[208:211], v150 offset:37888
	ds_read_b128 v[212:215], v150 offset:38912
	ds_read_b128 v[216:219], v150 offset:39936
	global_load_lds_dwordx4 v[226:227], off
	v_lshl_add_u64 v[226:227], s[24:25], 0, v[132:133]
	s_mov_b32 m0, s31
	s_nop 0
	global_load_lds_dwordx4 v[226:227], off
	s_waitcnt vmcnt(8)
	s_waitcnt lgkmcnt(0)
	s_barrier
	s_waitcnt lgkmcnt(0)
	v_mfma_f32_16x16x32_bf16 v[124:127], v[152:155], v[188:191], v[124:127]
	v_mfma_f32_16x16x32_bf16 v[120:123], v[160:163], v[188:191], v[120:123]
	v_mfma_f32_16x16x32_bf16 v[116:119], v[152:155], v[196:199], v[116:119]
	v_mfma_f32_16x16x32_bf16 v[108:111], v[160:163], v[196:199], v[108:111]
	v_mfma_f32_16x16x32_bf16 v[100:103], v[152:155], v[204:207], v[100:103]
	v_mfma_f32_16x16x32_bf16 v[92:95], v[160:163], v[204:207], v[92:95]
	v_mfma_f32_16x16x32_bf16 v[84:87], v[152:155], v[212:215], v[84:87]
	v_mfma_f32_16x16x32_bf16 v[76:79], v[160:163], v[212:215], v[76:79]
	v_mfma_f32_16x16x32_bf16 v[124:127], v[156:159], v[192:195], v[124:127]
	v_mfma_f32_16x16x32_bf16 v[120:123], v[164:167], v[192:195], v[120:123]
	v_mfma_f32_16x16x32_bf16 v[116:119], v[156:159], v[200:203], v[116:119]
	v_mfma_f32_16x16x32_bf16 v[108:111], v[164:167], v[200:203], v[108:111]
	v_mfma_f32_16x16x32_bf16 v[100:103], v[156:159], v[208:211], v[100:103]
	v_mfma_f32_16x16x32_bf16 v[92:95], v[164:167], v[208:211], v[92:95]
	v_mfma_f32_16x16x32_bf16 v[84:87], v[156:159], v[216:219], v[84:87]
	v_mfma_f32_16x16x32_bf16 v[76:79], v[164:167], v[216:219], v[76:79]
	v_mfma_f32_16x16x32_bf16 v[112:115], v[172:175], v[188:191], v[112:115]
	v_mfma_f32_16x16x32_bf16 v[104:107], v[180:183], v[188:191], v[104:107]
	v_mfma_f32_16x16x32_bf16 v[96:99], v[172:175], v[196:199], v[96:99]
	v_mfma_f32_16x16x32_bf16 v[88:91], v[180:183], v[196:199], v[88:91]
	v_mfma_f32_16x16x32_bf16 v[80:83], v[172:175], v[204:207], v[80:83]
	v_mfma_f32_16x16x32_bf16 v[72:75], v[180:183], v[204:207], v[72:75]
	v_mfma_f32_16x16x32_bf16 v[68:71], v[172:175], v[212:215], v[68:71]
	v_mfma_f32_16x16x32_bf16 v[64:67], v[180:183], v[212:215], v[64:67]
	v_mfma_f32_16x16x32_bf16 v[112:115], v[176:179], v[192:195], v[112:115]
	v_mfma_f32_16x16x32_bf16 v[104:107], v[184:187], v[192:195], v[104:107]
	v_mfma_f32_16x16x32_bf16 v[96:99], v[176:179], v[200:203], v[96:99]
	v_mfma_f32_16x16x32_bf16 v[88:91], v[184:187], v[200:203], v[88:91]
	v_mfma_f32_16x16x32_bf16 v[80:83], v[176:179], v[208:211], v[80:83]
	v_mfma_f32_16x16x32_bf16 v[72:75], v[184:187], v[208:211], v[72:75]
	v_mfma_f32_16x16x32_bf16 v[68:71], v[176:179], v[216:219], v[68:71]
	v_mfma_f32_16x16x32_bf16 v[64:67], v[184:187], v[216:219], v[64:67]
	s_barrier
	s_add_i32 s24, s47, s26
	v_lshl_add_u64 v[168:169], v[168:169], 0, s[6:7]
	s_mov_b32 m0, s24
	ds_read_b128 v[188:191], v150 offset:49152
	ds_read_b128 v[192:195], v150 offset:50176
	ds_read_b128 v[196:199], v150 offset:51200
	ds_read_b128 v[200:203], v150 offset:52224
	ds_read_b128 v[204:207], v150 offset:53248
	ds_read_b128 v[208:211], v150 offset:54272
	ds_read_b128 v[212:215], v150 offset:55296
	ds_read_b128 v[216:219], v150 offset:56320
	global_load_lds_dwordx4 v[168:169], off
	s_add_i32 m0, s24, 0x2000
	s_add_u32 s22, s22, 0x40080
	v_lshl_add_u64 v[168:169], v[220:221], 0, s[6:7]
	s_addc_u32 s23, s23, 0
	s_add_i32 s24, s48, s26
	global_load_lds_dwordx4 v[168:169], off
	v_lshl_add_u64 v[168:169], s[22:23], 0, v[130:131]
	s_mov_b32 m0, s24
	s_nop 0
	global_load_lds_dwordx4 v[168:169], off
	v_lshl_add_u64 v[168:169], s[22:23], 0, v[134:135]
	s_add_i32 m0, s24, 0x2000
	s_nop 0
	global_load_lds_dwordx4 v[168:169], off
	v_lshl_add_u64 v[168:169], v[222:223], 0, s[6:7]
	s_mov_b32 m0, s35
	s_nop 0
	global_load_lds_dwordx4 v[168:169], off
	v_lshl_add_u64 v[168:169], v[224:225], 0, s[6:7]
	s_mov_b32 m0, s36
	s_nop 0
	global_load_lds_dwordx4 v[168:169], off
	s_waitcnt vmcnt(8)
	s_waitcnt lgkmcnt(0)
	s_barrier
	s_waitcnt lgkmcnt(0)
	v_mfma_f32_16x16x32_bf16 v[60:63], v[152:155], v[188:191], v[60:63]
	v_mfma_f32_16x16x32_bf16 v[56:59], v[160:163], v[188:191], v[56:59]
	v_mfma_f32_16x16x32_bf16 v[52:55], v[152:155], v[196:199], v[52:55]
	v_mfma_f32_16x16x32_bf16 v[44:47], v[160:163], v[196:199], v[44:47]
	v_mfma_f32_16x16x32_bf16 v[36:39], v[152:155], v[204:207], v[36:39]
	v_mfma_f32_16x16x32_bf16 v[28:31], v[160:163], v[204:207], v[28:31]
	v_mfma_f32_16x16x32_bf16 v[20:23], v[152:155], v[212:215], v[20:23]
	v_mfma_f32_16x16x32_bf16 v[12:15], v[160:163], v[212:215], v[12:15]
	v_mfma_f32_16x16x32_bf16 v[60:63], v[156:159], v[192:195], v[60:63]
	v_mfma_f32_16x16x32_bf16 v[56:59], v[164:167], v[192:195], v[56:59]
	v_mfma_f32_16x16x32_bf16 v[52:55], v[156:159], v[200:203], v[52:55]
	v_mfma_f32_16x16x32_bf16 v[44:47], v[164:167], v[200:203], v[44:47]
	v_mfma_f32_16x16x32_bf16 v[36:39], v[156:159], v[208:211], v[36:39]
	v_mfma_f32_16x16x32_bf16 v[28:31], v[164:167], v[208:211], v[28:31]
	v_mfma_f32_16x16x32_bf16 v[20:23], v[156:159], v[216:219], v[20:23]
	v_mfma_f32_16x16x32_bf16 v[12:15], v[164:167], v[216:219], v[12:15]
	v_mfma_f32_16x16x32_bf16 v[48:51], v[172:175], v[188:191], v[48:51]
	v_mfma_f32_16x16x32_bf16 v[40:43], v[180:183], v[188:191], v[40:43]
	v_mfma_f32_16x16x32_bf16 v[32:35], v[172:175], v[196:199], v[32:35]
	v_mfma_f32_16x16x32_bf16 v[24:27], v[180:183], v[196:199], v[24:27]
	v_mfma_f32_16x16x32_bf16 v[16:19], v[172:175], v[204:207], v[16:19]
	v_mfma_f32_16x16x32_bf16 v[8:11], v[180:183], v[204:207], v[8:11]
	v_mfma_f32_16x16x32_bf16 v[4:7], v[172:175], v[212:215], v[4:7]
	v_mfma_f32_16x16x32_bf16 v[0:3], v[180:183], v[212:215], v[0:3]
	v_mfma_f32_16x16x32_bf16 v[48:51], v[176:179], v[192:195], v[48:51]
	v_mfma_f32_16x16x32_bf16 v[40:43], v[184:187], v[192:195], v[40:43]
	v_mfma_f32_16x16x32_bf16 v[32:35], v[176:179], v[200:203], v[32:35]
	v_mfma_f32_16x16x32_bf16 v[24:27], v[184:187], v[200:203], v[24:27]
	v_mfma_f32_16x16x32_bf16 v[16:19], v[176:179], v[208:211], v[16:19]
	v_mfma_f32_16x16x32_bf16 v[8:11], v[184:187], v[208:211], v[8:11]
	v_mfma_f32_16x16x32_bf16 v[4:7], v[176:179], v[216:219], v[4:7]
	v_mfma_f32_16x16x32_bf16 v[0:3], v[184:187], v[216:219], v[0:3]
	s_barrier
	s_add_i32 s46, s46, 2
	s_add_u32 s20, s20, 0x100
	s_addc_u32 s21, s21, 0
	s_add_u32 s44, s44, 0x100
	s_addc_u32 s45, s45, 0
	s_cmp_gt_u32 s46, 13
	s_cbranch_scc0 .LBB0_457
	s_and_b64 vcc, exec, s[8:9]
	s_cbranch_vccz .LBB0_460
	s_barrier

.LBB0_646:
	ds_read_b128 v[134:137], v156
	ds_read_b128 v[160:163], v156 offset:1024
	ds_read_b128 v[164:167], v156 offset:2048
	ds_read_b128 v[184:187], v156 offset:3072
	ds_read_b128 v[188:191], v157
	ds_read_b128 v[192:195], v157 offset:1024
	ds_read_b128 v[196:199], v157 offset:2048
	ds_read_b128 v[200:203], v157 offset:3072
	s_add_u32 s28, s26, 0xfffc0080
	s_addc_u32 s29, s27, -1
	s_cmp_eq_u32 s54, 12
	s_cselect_b32 s35, s17, s29
	s_cselect_b32 s34, s50, s28
	s_cselect_b32 s29, s19, s53
	s_cselect_b32 s28, s51, s52
	v_lshl_add_u64 v[138:139], s[26:27], 0, v[128:129]
	s_add_i32 m0, s25, 0xc000
	ds_read_b128 v[204:207], v158
	ds_read_b128 v[208:211], v158 offset:1024
	ds_read_b128 v[212:215], v158 offset:2048
	ds_read_b128 v[216:219], v158 offset:3072
	ds_read_b128 v[220:223], v158 offset:4096
	ds_read_b128 v[224:227], v158 offset:5120
	ds_read_b128 v[228:231], v158 offset:6144
	ds_read_b128 v[232:235], v158 offset:7168
	global_load_lds_dwordx4 v[138:139], off
	v_lshl_add_u64 v[138:139], s[26:27], 0, v[132:133]
	s_add_i32 m0, s25, 0xe000
	s_nop 0
	global_load_lds_dwordx4 v[138:139], off
	s_waitcnt vmcnt(8)
	s_waitcnt lgkmcnt(0)
	s_barrier
	s_waitcnt lgkmcnt(0)
	v_mfma_f32_16x16x32_bf16 v[124:127], v[134:137], v[204:207], v[124:127]
	v_mfma_f32_16x16x32_bf16 v[120:123], v[164:167], v[204:207], v[120:123]
	v_mfma_f32_16x16x32_bf16 v[108:111], v[134:137], v[212:215], v[108:111]
	v_mfma_f32_16x16x32_bf16 v[104:107], v[164:167], v[212:215], v[104:107]
	v_mfma_f32_16x16x32_bf16 v[92:95], v[134:137], v[220:223], v[92:95]
	v_mfma_f32_16x16x32_bf16 v[88:91], v[164:167], v[220:223], v[88:91]
	v_mfma_f32_16x16x32_bf16 v[76:79], v[134:137], v[228:231], v[76:79]
	v_mfma_f32_16x16x32_bf16 v[72:75], v[164:167], v[228:231], v[72:75]
	v_mfma_f32_16x16x32_bf16 v[124:127], v[160:163], v[208:211], v[124:127]
	v_mfma_f32_16x16x32_bf16 v[120:123], v[184:187], v[208:211], v[120:123]
	v_mfma_f32_16x16x32_bf16 v[108:111], v[160:163], v[216:219], v[108:111]
	v_mfma_f32_16x16x32_bf16 v[104:107], v[184:187], v[216:219], v[104:107]
	v_mfma_f32_16x16x32_bf16 v[92:95], v[160:163], v[224:227], v[92:95]
	v_mfma_f32_16x16x32_bf16 v[88:91], v[184:187], v[224:227], v[88:91]
	v_mfma_f32_16x16x32_bf16 v[76:79], v[160:163], v[232:235], v[76:79]
	v_mfma_f32_16x16x32_bf16 v[72:75], v[184:187], v[232:235], v[72:75]
	v_mfma_f32_16x16x32_bf16 v[116:119], v[188:191], v[204:207], v[116:119]
	v_mfma_f32_16x16x32_bf16 v[112:115], v[196:199], v[204:207], v[112:115]
	v_mfma_f32_16x16x32_bf16 v[100:103], v[188:191], v[212:215], v[100:103]
	v_mfma_f32_16x16x32_bf16 v[96:99], v[196:199], v[212:215], v[96:99]
	v_mfma_f32_16x16x32_bf16 v[84:87], v[188:191], v[220:223], v[84:87]
	v_mfma_f32_16x16x32_bf16 v[80:83], v[196:199], v[220:223], v[80:83]
	v_mfma_f32_16x16x32_bf16 v[68:71], v[188:191], v[228:231], v[68:71]
	v_mfma_f32_16x16x32_bf16 v[64:67], v[196:199], v[228:231], v[64:67]
	v_mfma_f32_16x16x32_bf16 v[116:119], v[192:195], v[208:211], v[116:119]
	v_mfma_f32_16x16x32_bf16 v[112:115], v[200:203], v[208:211], v[112:115]
	v_mfma_f32_16x16x32_bf16 v[100:103], v[192:195], v[216:219], v[100:103]
	v_mfma_f32_16x16x32_bf16 v[96:99], v[200:203], v[216:219], v[96:99]
	v_mfma_f32_16x16x32_bf16 v[84:87], v[192:195], v[224:227], v[84:87]
	v_mfma_f32_16x16x32_bf16 v[80:83], v[200:203], v[224:227], v[80:83]
	v_mfma_f32_16x16x32_bf16 v[68:71], v[192:195], v[232:235], v[68:71]
	v_mfma_f32_16x16x32_bf16 v[64:67], v[200:203], v[232:235], v[64:67]
	s_barrier
	s_add_i32 s55, s47, s41
	v_lshl_add_u64 v[138:139], s[28:29], 0, v[142:143]
	s_mov_b32 m0, s55
	ds_read_b128 v[204:207], v158 offset:16384
	ds_read_b128 v[208:211], v158 offset:17408
	ds_read_b128 v[212:215], v158 offset:18432
	ds_read_b128 v[216:219], v158 offset:19456
	ds_read_b128 v[220:223], v158 offset:20480
	ds_read_b128 v[224:227], v158 offset:21504
	ds_read_b128 v[228:231], v158 offset:22528
	ds_read_b128 v[232:235], v158 offset:23552
	global_load_lds_dwordx4 v[138:139], off
	s_add_i32 m0, s55, 0x2000
	s_add_u32 s56, s28, 0x40000
	v_lshl_add_u64 v[168:169], s[28:29], 0, v[146:147]
	s_addc_u32 s57, s29, 0
	s_add_i32 s55, s48, s41
	global_load_lds_dwordx4 v[168:169], off
	v_lshl_add_u64 v[236:237], s[56:57], 0, v[142:143]
	s_mov_b32 m0, s55
	v_lshl_add_u64 v[238:239], s[34:35], 0, v[144:145]
	global_load_lds_dwordx4 v[236:237], off
	v_lshl_add_u64 v[236:237], s[56:57], 0, v[146:147]
	s_add_i32 m0, s55, 0x2000
	s_nop 0
	global_load_lds_dwordx4 v[236:237], off
	v_lshl_add_u64 v[236:237], s[34:35], 0, v[140:141]
	s_mov_b32 m0, s25
	s_nop 0
	global_load_lds_dwordx4 v[236:237], off
	s_mov_b32 m0, s42
	s_nop 0
	global_load_lds_dwordx4 v[238:239], off
	s_waitcnt vmcnt(8)
	s_waitcnt lgkmcnt(0)
	s_barrier
	s_waitcnt lgkmcnt(0)
	v_mfma_f32_16x16x32_bf16 v[60:63], v[134:137], v[204:207], v[60:63]
	v_mfma_f32_16x16x32_bf16 v[56:59], v[164:167], v[204:207], v[56:59]
	v_mfma_f32_16x16x32_bf16 v[44:47], v[134:137], v[212:215], v[44:47]
	v_mfma_f32_16x16x32_bf16 v[40:43], v[164:167], v[212:215], v[40:43]
	v_mfma_f32_16x16x32_bf16 v[28:31], v[134:137], v[220:223], v[28:31]
	v_mfma_f32_16x16x32_bf16 v[24:27], v[164:167], v[220:223], v[24:27]
	v_mfma_f32_16x16x32_bf16 v[12:15], v[134:137], v[228:231], v[12:15]
	v_mfma_f32_16x16x32_bf16 v[8:11], v[164:167], v[228:231], v[8:11]
	v_mfma_f32_16x16x32_bf16 v[60:63], v[160:163], v[208:211], v[60:63]
	v_mfma_f32_16x16x32_bf16 v[56:59], v[184:187], v[208:211], v[56:59]
	v_mfma_f32_16x16x32_bf16 v[44:47], v[160:163], v[216:219], v[44:47]
	v_mfma_f32_16x16x32_bf16 v[40:43], v[184:187], v[216:219], v[40:43]
	v_mfma_f32_16x16x32_bf16 v[28:31], v[160:163], v[224:227], v[28:31]
	v_mfma_f32_16x16x32_bf16 v[24:27], v[184:187], v[224:227], v[24:27]
	v_mfma_f32_16x16x32_bf16 v[12:15], v[160:163], v[232:235], v[12:15]
	v_mfma_f32_16x16x32_bf16 v[8:11], v[184:187], v[232:235], v[8:11]
	v_mfma_f32_16x16x32_bf16 v[52:55], v[188:191], v[204:207], v[52:55]
	v_mfma_f32_16x16x32_bf16 v[48:51], v[196:199], v[204:207], v[48:51]
	v_mfma_f32_16x16x32_bf16 v[36:39], v[188:191], v[212:215], v[36:39]
	v_mfma_f32_16x16x32_bf16 v[32:35], v[196:199], v[212:215], v[32:35]
	v_mfma_f32_16x16x32_bf16 v[20:23], v[188:191], v[220:223], v[20:23]
	v_mfma_f32_16x16x32_bf16 v[16:19], v[196:199], v[220:223], v[16:19]
	v_mfma_f32_16x16x32_bf16 v[4:7], v[188:191], v[228:231], v[4:7]
	v_mfma_f32_16x16x32_bf16 v[0:3], v[196:199], v[228:231], v[0:3]
	v_mfma_f32_16x16x32_bf16 v[52:55], v[192:195], v[208:211], v[52:55]
	v_mfma_f32_16x16x32_bf16 v[48:51], v[200:203], v[208:211], v[48:51]
	v_mfma_f32_16x16x32_bf16 v[36:39], v[192:195], v[216:219], v[36:39]
	v_mfma_f32_16x16x32_bf16 v[32:35], v[200:203], v[216:219], v[32:35]
	v_mfma_f32_16x16x32_bf16 v[20:23], v[192:195], v[224:227], v[20:23]
	v_mfma_f32_16x16x32_bf16 v[16:19], v[200:203], v[224:227], v[16:19]
	v_mfma_f32_16x16x32_bf16 v[4:7], v[192:195], v[232:235], v[4:7]
	v_mfma_f32_16x16x32_bf16 v[0:3], v[200:203], v[232:235], v[0:3]
	s_barrier
	s_add_i32 s55, 0, 0x18000
	v_add_u32_e32 v130, s55, v154
	s_add_i32 s56, 0, 0x1c000
	ds_read_b128 v[134:137], v130
	ds_read_b128 v[160:163], v130 offset:1024
	ds_read_b128 v[164:167], v130 offset:2048
	ds_read_b128 v[184:187], v130 offset:3072
	v_add_u32_e32 v130, s56, v154
	ds_read_b128 v[188:191], v130
	ds_read_b128 v[192:195], v130 offset:1024
	ds_read_b128 v[196:199], v130 offset:2048
	ds_read_b128 v[200:203], v130 offset:3072
	s_add_u32 s34, s34, 0x40000
	s_addc_u32 s35, s35, 0
	s_mov_b32 m0, s43
	v_lshl_add_u64 v[240:241], s[34:35], 0, v[140:141]
	ds_read_b128 v[204:207], v158 offset:32768
	ds_read_b128 v[208:211], v158 offset:33792
	ds_read_b128 v[212:215], v158 offset:34816
	ds_read_b128 v[216:219], v158 offset:35840
	ds_read_b128 v[220:223], v158 offset:36864
	ds_read_b128 v[224:227], v158 offset:37888
	ds_read_b128 v[228:231], v158 offset:38912
	ds_read_b128 v[232:235], v158 offset:39936
	global_load_lds_dwordx4 v[240:241], off
	v_lshl_add_u64 v[240:241], s[34:35], 0, v[144:145]
	s_mov_b32 m0, s44
	s_nop 0
	global_load_lds_dwordx4 v[240:241], off
	s_waitcnt vmcnt(8)
	s_waitcnt lgkmcnt(0)
	s_barrier
	s_waitcnt lgkmcnt(0)
	v_mfma_f32_16x16x32_bf16 v[124:127], v[134:137], v[204:207], v[124:127]
	v_mfma_f32_16x16x32_bf16 v[120:123], v[164:167], v[204:207], v[120:123]
	v_mfma_f32_16x16x32_bf16 v[108:111], v[134:137], v[212:215], v[108:111]
	v_mfma_f32_16x16x32_bf16 v[104:107], v[164:167], v[212:215], v[104:107]
	v_mfma_f32_16x16x32_bf16 v[92:95], v[134:137], v[220:223], v[92:95]
	v_mfma_f32_16x16x32_bf16 v[88:91], v[164:167], v[220:223], v[88:91]
	v_mfma_f32_16x16x32_bf16 v[76:79], v[134:137], v[228:231], v[76:79]
	v_mfma_f32_16x16x32_bf16 v[72:75], v[164:167], v[228:231], v[72:75]
	v_mfma_f32_16x16x32_bf16 v[124:127], v[160:163], v[208:211], v[124:127]
	v_mfma_f32_16x16x32_bf16 v[120:123], v[184:187], v[208:211], v[120:123]
	v_mfma_f32_16x16x32_bf16 v[108:111], v[160:163], v[216:219], v[108:111]
	v_mfma_f32_16x16x32_bf16 v[104:107], v[184:187], v[216:219], v[104:107]
	v_mfma_f32_16x16x32_bf16 v[92:95], v[160:163], v[224:227], v[92:95]
	v_mfma_f32_16x16x32_bf16 v[88:91], v[184:187], v[224:227], v[88:91]
	v_mfma_f32_16x16x32_bf16 v[76:79], v[160:163], v[232:235], v[76:79]
	v_mfma_f32_16x16x32_bf16 v[72:75], v[184:187], v[232:235], v[72:75]
	v_mfma_f32_16x16x32_bf16 v[116:119], v[188:191], v[204:207], v[116:119]
	v_mfma_f32_16x16x32_bf16 v[112:115], v[196:199], v[204:207], v[112:115]
	v_mfma_f32_16x16x32_bf16 v[100:103], v[188:191], v[212:215], v[100:103]
	v_mfma_f32_16x16x32_bf16 v[96:99], v[196:199], v[212:215], v[96:99]
	v_mfma_f32_16x16x32_bf16 v[84:87], v[188:191], v[220:223], v[84:87]
	v_mfma_f32_16x16x32_bf16 v[80:83], v[196:199], v[220:223], v[80:83]
	v_mfma_f32_16x16x32_bf16 v[68:71], v[188:191], v[228:231], v[68:71]
	v_mfma_f32_16x16x32_bf16 v[64:67], v[196:199], v[228:231], v[64:67]
	v_mfma_f32_16x16x32_bf16 v[116:119], v[192:195], v[208:211], v[116:119]
	v_mfma_f32_16x16x32_bf16 v[112:115], v[200:203], v[208:211], v[112:115]
	v_mfma_f32_16x16x32_bf16 v[100:103], v[192:195], v[216:219], v[100:103]
	v_mfma_f32_16x16x32_bf16 v[96:99], v[200:203], v[216:219], v[96:99]
	v_mfma_f32_16x16x32_bf16 v[84:87], v[192:195], v[224:227], v[84:87]
	v_mfma_f32_16x16x32_bf16 v[80:83], v[200:203], v[224:227], v[80:83]
	v_mfma_f32_16x16x32_bf16 v[68:71], v[192:195], v[232:235], v[68:71]
	v_mfma_f32_16x16x32_bf16 v[64:67], v[200:203], v[232:235], v[64:67]
	s_barrier
	s_add_i32 s34, s55, s41
	v_lshl_add_u64 v[138:139], v[138:139], 0, s[12:13]
	s_mov_b32 m0, s34
	ds_read_b128 v[204:207], v158 offset:49152
	ds_read_b128 v[208:211], v158 offset:50176
	ds_read_b128 v[212:215], v158 offset:51200
	ds_read_b128 v[216:219], v158 offset:52224
	ds_read_b128 v[220:223], v158 offset:53248
	ds_read_b128 v[224:227], v158 offset:54272
	ds_read_b128 v[228:231], v158 offset:55296
	ds_read_b128 v[232:235], v158 offset:56320
	global_load_lds_dwordx4 v[138:139], off
	s_add_i32 m0, s34, 0x2000
	s_add_u32 s28, s28, 0x40080
	v_lshl_add_u64 v[138:139], v[168:169], 0, s[12:13]
	s_addc_u32 s29, s29, 0
	s_add_i32 s34, s56, s41
	global_load_lds_dwordx4 v[138:139], off
	v_lshl_add_u64 v[138:139], s[28:29], 0, v[142:143]
	s_mov_b32 m0, s34
	s_nop 0
	global_load_lds_dwordx4 v[138:139], off
	v_lshl_add_u64 v[138:139], s[28:29], 0, v[146:147]
	s_add_i32 m0, s34, 0x2000
	s_nop 0
	global_load_lds_dwordx4 v[138:139], off
	v_lshl_add_u64 v[138:139], v[236:237], 0, s[12:13]
	s_mov_b32 m0, s45
	s_nop 0
	global_load_lds_dwordx4 v[138:139], off
	v_lshl_add_u64 v[138:139], v[238:239], 0, s[12:13]
	s_mov_b32 m0, s46
	s_nop 0
	global_load_lds_dwordx4 v[138:139], off
	s_waitcnt vmcnt(8)
	s_waitcnt lgkmcnt(0)
	s_barrier
	s_waitcnt lgkmcnt(0)
	v_mfma_f32_16x16x32_bf16 v[60:63], v[134:137], v[204:207], v[60:63]
	v_mfma_f32_16x16x32_bf16 v[56:59], v[164:167], v[204:207], v[56:59]
	v_mfma_f32_16x16x32_bf16 v[44:47], v[134:137], v[212:215], v[44:47]
	v_mfma_f32_16x16x32_bf16 v[40:43], v[164:167], v[212:215], v[40:43]
	v_mfma_f32_16x16x32_bf16 v[28:31], v[134:137], v[220:223], v[28:31]
	v_mfma_f32_16x16x32_bf16 v[24:27], v[164:167], v[220:223], v[24:27]
	v_mfma_f32_16x16x32_bf16 v[12:15], v[134:137], v[228:231], v[12:15]
	v_mfma_f32_16x16x32_bf16 v[8:11], v[164:167], v[228:231], v[8:11]
	v_mfma_f32_16x16x32_bf16 v[60:63], v[160:163], v[208:211], v[60:63]
	v_mfma_f32_16x16x32_bf16 v[56:59], v[184:187], v[208:211], v[56:59]
	v_mfma_f32_16x16x32_bf16 v[44:47], v[160:163], v[216:219], v[44:47]
	v_mfma_f32_16x16x32_bf16 v[40:43], v[184:187], v[216:219], v[40:43]
	v_mfma_f32_16x16x32_bf16 v[28:31], v[160:163], v[224:227], v[28:31]
	v_mfma_f32_16x16x32_bf16 v[24:27], v[184:187], v[224:227], v[24:27]
	v_mfma_f32_16x16x32_bf16 v[12:15], v[160:163], v[232:235], v[12:15]
	v_mfma_f32_16x16x32_bf16 v[8:11], v[184:187], v[232:235], v[8:11]
	v_mfma_f32_16x16x32_bf16 v[52:55], v[188:191], v[204:207], v[52:55]
	v_mfma_f32_16x16x32_bf16 v[48:51], v[196:199], v[204:207], v[48:51]
	v_mfma_f32_16x16x32_bf16 v[36:39], v[188:191], v[212:215], v[36:39]
	v_mfma_f32_16x16x32_bf16 v[32:35], v[196:199], v[212:215], v[32:35]
	v_mfma_f32_16x16x32_bf16 v[20:23], v[188:191], v[220:223], v[20:23]
	v_mfma_f32_16x16x32_bf16 v[16:19], v[196:199], v[220:223], v[16:19]
	v_mfma_f32_16x16x32_bf16 v[4:7], v[188:191], v[228:231], v[4:7]
	v_mfma_f32_16x16x32_bf16 v[0:3], v[196:199], v[228:231], v[0:3]
	v_mfma_f32_16x16x32_bf16 v[52:55], v[192:195], v[208:211], v[52:55]
	v_mfma_f32_16x16x32_bf16 v[48:51], v[200:203], v[208:211], v[48:51]
	v_mfma_f32_16x16x32_bf16 v[36:39], v[192:195], v[216:219], v[36:39]
	v_mfma_f32_16x16x32_bf16 v[32:35], v[200:203], v[216:219], v[32:35]
	v_mfma_f32_16x16x32_bf16 v[20:23], v[192:195], v[224:227], v[20:23]
	v_mfma_f32_16x16x32_bf16 v[16:19], v[200:203], v[224:227], v[16:19]
	v_mfma_f32_16x16x32_bf16 v[4:7], v[192:195], v[232:235], v[4:7]
	v_mfma_f32_16x16x32_bf16 v[0:3], v[200:203], v[232:235], v[0:3]
	s_barrier
	s_add_i32 s54, s54, 2
	s_add_u32 s26, s26, 0x100
	s_addc_u32 s27, s27, 0
	s_add_u32 s52, s52, 0x100
	s_addc_u32 s53, s53, 0
	s_cmp_gt_u32 s54, 13
	s_cbranch_scc0 .LBB0_646
	s_and_b64 vcc, exec, s[14:15]
	s_cbranch_vccz .LBB0_649
	s_barrier

.LBB0_666:
	ds_read_b128 v[128:131], v187
	ds_read_b128 v[132:135], v187 offset:1024
	ds_read_b128 v[136:139], v187 offset:2048
	ds_read_b128 v[164:167], v187 offset:3072
	ds_read_b128 v[190:193], v188
	ds_read_b128 v[194:197], v188 offset:1024
	ds_read_b128 v[198:201], v188 offset:2048
	ds_read_b128 v[202:205], v188 offset:3072
	s_add_u32 s28, s26, 0xfffe0080
	s_addc_u32 s29, s27, -1
	s_cmp_eq_u32 s54, 4
	s_cselect_b32 s35, s19, s29
	s_cselect_b32 s34, s50, s28
	s_cselect_b32 s29, s17, s53
	s_cselect_b32 s28, s51, s52
	v_lshl_add_u64 v[168:169], s[26:27], 0, v[156:157]
	s_add_i32 m0, s25, 0xc000
	ds_read_b128 v[206:209], v189
	ds_read_b128 v[210:213], v189 offset:1024
	ds_read_b128 v[214:217], v189 offset:2048
	ds_read_b128 v[218:221], v189 offset:3072
	ds_read_b128 v[222:225], v189 offset:4096
	ds_read_b128 v[226:229], v189 offset:5120
	ds_read_b128 v[230:233], v189 offset:6144
	ds_read_b128 v[234:237], v189 offset:7168
	global_load_lds_dwordx4 v[168:169], off
	v_lshl_add_u64 v[168:169], s[26:27], 0, v[158:159]
	s_add_i32 m0, s25, 0xe000
	s_nop 0
	global_load_lds_dwordx4 v[168:169], off
	s_waitcnt vmcnt(8)
	s_waitcnt lgkmcnt(0)
	s_barrier
	s_waitcnt lgkmcnt(0)
	v_mfma_f32_16x16x32_bf16 v[124:127], v[128:131], v[206:209], v[124:127]
	v_mfma_f32_16x16x32_bf16 v[120:123], v[136:139], v[206:209], v[120:123]
	v_mfma_f32_16x16x32_bf16 v[112:115], v[128:131], v[214:217], v[112:115]
	v_mfma_f32_16x16x32_bf16 v[104:107], v[136:139], v[214:217], v[104:107]
	v_mfma_f32_16x16x32_bf16 v[92:95], v[128:131], v[222:225], v[92:95]
	v_mfma_f32_16x16x32_bf16 v[88:91], v[136:139], v[222:225], v[88:91]
	v_mfma_f32_16x16x32_bf16 v[76:79], v[128:131], v[230:233], v[76:79]
	v_mfma_f32_16x16x32_bf16 v[72:75], v[136:139], v[230:233], v[72:75]
	v_mfma_f32_16x16x32_bf16 v[124:127], v[132:135], v[210:213], v[124:127]
	v_mfma_f32_16x16x32_bf16 v[120:123], v[164:167], v[210:213], v[120:123]
	v_mfma_f32_16x16x32_bf16 v[112:115], v[132:135], v[218:221], v[112:115]
	v_mfma_f32_16x16x32_bf16 v[104:107], v[164:167], v[218:221], v[104:107]
	v_mfma_f32_16x16x32_bf16 v[92:95], v[132:135], v[226:229], v[92:95]
	v_mfma_f32_16x16x32_bf16 v[88:91], v[164:167], v[226:229], v[88:91]
	v_mfma_f32_16x16x32_bf16 v[76:79], v[132:135], v[234:237], v[76:79]
	v_mfma_f32_16x16x32_bf16 v[72:75], v[164:167], v[234:237], v[72:75]
	v_mfma_f32_16x16x32_bf16 v[116:119], v[190:193], v[206:209], v[116:119]
	v_mfma_f32_16x16x32_bf16 v[108:111], v[198:201], v[206:209], v[108:111]
	v_mfma_f32_16x16x32_bf16 v[100:103], v[190:193], v[214:217], v[100:103]
	v_mfma_f32_16x16x32_bf16 v[96:99], v[198:201], v[214:217], v[96:99]
	v_mfma_f32_16x16x32_bf16 v[84:87], v[190:193], v[222:225], v[84:87]
	v_mfma_f32_16x16x32_bf16 v[80:83], v[198:201], v[222:225], v[80:83]
	v_mfma_f32_16x16x32_bf16 v[68:71], v[190:193], v[230:233], v[68:71]
	v_mfma_f32_16x16x32_bf16 v[64:67], v[198:201], v[230:233], v[64:67]
	v_mfma_f32_16x16x32_bf16 v[116:119], v[194:197], v[210:213], v[116:119]
	v_mfma_f32_16x16x32_bf16 v[108:111], v[202:205], v[210:213], v[108:111]
	v_mfma_f32_16x16x32_bf16 v[100:103], v[194:197], v[218:221], v[100:103]
	v_mfma_f32_16x16x32_bf16 v[96:99], v[202:205], v[218:221], v[96:99]
	v_mfma_f32_16x16x32_bf16 v[84:87], v[194:197], v[226:229], v[84:87]
	v_mfma_f32_16x16x32_bf16 v[80:83], v[202:205], v[226:229], v[80:83]
	v_mfma_f32_16x16x32_bf16 v[68:71], v[194:197], v[234:237], v[68:71]
	v_mfma_f32_16x16x32_bf16 v[64:67], v[202:205], v[234:237], v[64:67]
	s_barrier
	s_add_i32 s55, s47, s40
	v_lshl_add_u64 v[168:169], s[28:29], 0, v[150:151]
	s_mov_b32 m0, s55
	ds_read_b128 v[206:209], v189 offset:16384
	ds_read_b128 v[210:213], v189 offset:17408
	ds_read_b128 v[214:217], v189 offset:18432
	ds_read_b128 v[218:221], v189 offset:19456
	ds_read_b128 v[222:225], v189 offset:20480
	ds_read_b128 v[226:229], v189 offset:21504
	ds_read_b128 v[230:233], v189 offset:22528
	ds_read_b128 v[234:237], v189 offset:23552
	global_load_lds_dwordx4 v[168:169], off
	s_add_i32 m0, s55, 0x2000
	s_add_u32 s56, s28, 0x20000
	v_lshl_add_u64 v[238:239], s[28:29], 0, v[154:155]
	s_addc_u32 s57, s29, 0
	s_add_i32 s55, s48, s40
	global_load_lds_dwordx4 v[238:239], off
	v_lshl_add_u64 v[240:241], s[56:57], 0, v[150:151]
	s_mov_b32 m0, s55
	v_lshl_add_u64 v[242:243], s[34:35], 0, v[152:153]
	global_load_lds_dwordx4 v[240:241], off
	v_lshl_add_u64 v[240:241], s[56:57], 0, v[154:155]
	s_add_i32 m0, s55, 0x2000
	s_nop 0
	global_load_lds_dwordx4 v[240:241], off
	v_lshl_add_u64 v[240:241], s[34:35], 0, v[148:149]
	s_mov_b32 m0, s25
	s_nop 0
	global_load_lds_dwordx4 v[240:241], off
	s_mov_b32 m0, s41
	s_nop 0
	global_load_lds_dwordx4 v[242:243], off
	s_waitcnt vmcnt(8)
	s_waitcnt lgkmcnt(0)
	s_barrier
	s_waitcnt lgkmcnt(0)
	v_mfma_f32_16x16x32_bf16 v[60:63], v[128:131], v[206:209], v[60:63]
	v_mfma_f32_16x16x32_bf16 v[56:59], v[136:139], v[206:209], v[56:59]
	v_mfma_f32_16x16x32_bf16 v[44:47], v[128:131], v[214:217], v[44:47]
	v_mfma_f32_16x16x32_bf16 v[40:43], v[136:139], v[214:217], v[40:43]
	v_mfma_f32_16x16x32_bf16 v[36:39], v[128:131], v[222:225], v[36:39]
	v_mfma_f32_16x16x32_bf16 v[32:35], v[136:139], v[222:225], v[32:35]
	v_mfma_f32_16x16x32_bf16 v[20:23], v[128:131], v[230:233], v[20:23]
	v_mfma_f32_16x16x32_bf16 v[16:19], v[136:139], v[230:233], v[16:19]
	v_mfma_f32_16x16x32_bf16 v[60:63], v[132:135], v[210:213], v[60:63]
	v_mfma_f32_16x16x32_bf16 v[56:59], v[164:167], v[210:213], v[56:59]
	v_mfma_f32_16x16x32_bf16 v[44:47], v[132:135], v[218:221], v[44:47]
	v_mfma_f32_16x16x32_bf16 v[40:43], v[164:167], v[218:221], v[40:43]
	v_mfma_f32_16x16x32_bf16 v[36:39], v[132:135], v[226:229], v[36:39]
	v_mfma_f32_16x16x32_bf16 v[32:35], v[164:167], v[226:229], v[32:35]
	v_mfma_f32_16x16x32_bf16 v[20:23], v[132:135], v[234:237], v[20:23]
	v_mfma_f32_16x16x32_bf16 v[16:19], v[164:167], v[234:237], v[16:19]
	v_mfma_f32_16x16x32_bf16 v[52:55], v[190:193], v[206:209], v[52:55]
	v_mfma_f32_16x16x32_bf16 v[48:51], v[198:201], v[206:209], v[48:51]
	v_mfma_f32_16x16x32_bf16 v[28:31], v[190:193], v[214:217], v[28:31]
	v_mfma_f32_16x16x32_bf16 v[24:27], v[198:201], v[214:217], v[24:27]
	v_mfma_f32_16x16x32_bf16 v[12:15], v[190:193], v[222:225], v[12:15]
	v_mfma_f32_16x16x32_bf16 v[8:11], v[198:201], v[222:225], v[8:11]
	v_mfma_f32_16x16x32_bf16 v[4:7], v[190:193], v[230:233], v[4:7]
	v_mfma_f32_16x16x32_bf16 v[0:3], v[198:201], v[230:233], v[0:3]
	v_mfma_f32_16x16x32_bf16 v[52:55], v[194:197], v[210:213], v[52:55]
	v_mfma_f32_16x16x32_bf16 v[48:51], v[202:205], v[210:213], v[48:51]
	v_mfma_f32_16x16x32_bf16 v[28:31], v[194:197], v[218:221], v[28:31]
	v_mfma_f32_16x16x32_bf16 v[24:27], v[202:205], v[218:221], v[24:27]
	v_mfma_f32_16x16x32_bf16 v[12:15], v[194:197], v[226:229], v[12:15]
	v_mfma_f32_16x16x32_bf16 v[8:11], v[202:205], v[226:229], v[8:11]
	v_mfma_f32_16x16x32_bf16 v[4:7], v[194:197], v[234:237], v[4:7]
	v_mfma_f32_16x16x32_bf16 v[0:3], v[202:205], v[234:237], v[0:3]
	s_barrier
	s_add_i32 s55, 0, 0x18000
	s_add_i32 s56, 0, 0x1c000
	v_add_u32_e32 v164, s55, v185
	v_add_u32_e32 v202, s56, v185
	ds_read_b128 v[128:131], v164
	ds_read_b128 v[132:135], v164 offset:1024
	ds_read_b128 v[136:139], v164 offset:2048
	ds_read_b128 v[164:167], v164 offset:3072
	ds_read_b128 v[190:193], v202
	ds_read_b128 v[194:197], v202 offset:1024
	ds_read_b128 v[198:201], v202 offset:2048
	ds_read_b128 v[202:205], v202 offset:3072
	s_add_u32 s34, s34, 0x20000
	s_addc_u32 s35, s35, 0
	s_mov_b32 m0, s42
	v_lshl_add_u64 v[244:245], s[34:35], 0, v[148:149]
	ds_read_b128 v[206:209], v189 offset:32768
	ds_read_b128 v[210:213], v189 offset:33792
	ds_read_b128 v[214:217], v189 offset:34816
	ds_read_b128 v[218:221], v189 offset:35840
	ds_read_b128 v[222:225], v189 offset:36864
	ds_read_b128 v[226:229], v189 offset:37888
	ds_read_b128 v[230:233], v189 offset:38912
	ds_read_b128 v[234:237], v189 offset:39936
	global_load_lds_dwordx4 v[244:245], off
	v_lshl_add_u64 v[244:245], s[34:35], 0, v[152:153]
	s_mov_b32 m0, s43
	s_nop 0
	global_load_lds_dwordx4 v[244:245], off
	s_waitcnt vmcnt(8)
	s_waitcnt lgkmcnt(0)
	s_barrier
	s_waitcnt lgkmcnt(0)
	v_mfma_f32_16x16x32_bf16 v[124:127], v[128:131], v[206:209], v[124:127]
	v_mfma_f32_16x16x32_bf16 v[120:123], v[136:139], v[206:209], v[120:123]
	v_mfma_f32_16x16x32_bf16 v[112:115], v[128:131], v[214:217], v[112:115]
	v_mfma_f32_16x16x32_bf16 v[104:107], v[136:139], v[214:217], v[104:107]
	v_mfma_f32_16x16x32_bf16 v[92:95], v[128:131], v[222:225], v[92:95]
	v_mfma_f32_16x16x32_bf16 v[88:91], v[136:139], v[222:225], v[88:91]
	v_mfma_f32_16x16x32_bf16 v[76:79], v[128:131], v[230:233], v[76:79]
	v_mfma_f32_16x16x32_bf16 v[72:75], v[136:139], v[230:233], v[72:75]
	v_mfma_f32_16x16x32_bf16 v[124:127], v[132:135], v[210:213], v[124:127]
	v_mfma_f32_16x16x32_bf16 v[120:123], v[164:167], v[210:213], v[120:123]
	v_mfma_f32_16x16x32_bf16 v[112:115], v[132:135], v[218:221], v[112:115]
	v_mfma_f32_16x16x32_bf16 v[104:107], v[164:167], v[218:221], v[104:107]
	v_mfma_f32_16x16x32_bf16 v[92:95], v[132:135], v[226:229], v[92:95]
	v_mfma_f32_16x16x32_bf16 v[88:91], v[164:167], v[226:229], v[88:91]
	v_mfma_f32_16x16x32_bf16 v[76:79], v[132:135], v[234:237], v[76:79]
	v_mfma_f32_16x16x32_bf16 v[72:75], v[164:167], v[234:237], v[72:75]
	v_mfma_f32_16x16x32_bf16 v[116:119], v[190:193], v[206:209], v[116:119]
	v_mfma_f32_16x16x32_bf16 v[108:111], v[198:201], v[206:209], v[108:111]
	v_mfma_f32_16x16x32_bf16 v[100:103], v[190:193], v[214:217], v[100:103]
	v_mfma_f32_16x16x32_bf16 v[96:99], v[198:201], v[214:217], v[96:99]
	v_mfma_f32_16x16x32_bf16 v[84:87], v[190:193], v[222:225], v[84:87]
	v_mfma_f32_16x16x32_bf16 v[80:83], v[198:201], v[222:225], v[80:83]
	v_mfma_f32_16x16x32_bf16 v[68:71], v[190:193], v[230:233], v[68:71]
	v_mfma_f32_16x16x32_bf16 v[64:67], v[198:201], v[230:233], v[64:67]
	v_mfma_f32_16x16x32_bf16 v[116:119], v[194:197], v[210:213], v[116:119]
	v_mfma_f32_16x16x32_bf16 v[108:111], v[202:205], v[210:213], v[108:111]
	v_mfma_f32_16x16x32_bf16 v[100:103], v[194:197], v[218:221], v[100:103]
	v_mfma_f32_16x16x32_bf16 v[96:99], v[202:205], v[218:221], v[96:99]
	v_mfma_f32_16x16x32_bf16 v[84:87], v[194:197], v[226:229], v[84:87]
	v_mfma_f32_16x16x32_bf16 v[80:83], v[202:205], v[226:229], v[80:83]
	v_mfma_f32_16x16x32_bf16 v[68:71], v[194:197], v[234:237], v[68:71]
	v_mfma_f32_16x16x32_bf16 v[64:67], v[202:205], v[234:237], v[64:67]
	s_barrier
	s_add_i32 s34, s55, s40
	v_lshl_add_u64 v[168:169], v[168:169], 0, s[12:13]
	s_mov_b32 m0, s34
	ds_read_b128 v[206:209], v189 offset:49152
	ds_read_b128 v[210:213], v189 offset:50176
	ds_read_b128 v[214:217], v189 offset:51200
	ds_read_b128 v[218:221], v189 offset:52224
	ds_read_b128 v[222:225], v189 offset:53248
	ds_read_b128 v[226:229], v189 offset:54272
	ds_read_b128 v[230:233], v189 offset:55296
	ds_read_b128 v[234:237], v189 offset:56320
	global_load_lds_dwordx4 v[168:169], off
	s_add_i32 m0, s34, 0x2000
	s_add_u32 s28, s28, 0x20080
	v_lshl_add_u64 v[168:169], v[238:239], 0, s[12:13]
	s_addc_u32 s29, s29, 0
	s_add_i32 s34, s56, s40
	global_load_lds_dwordx4 v[168:169], off
	v_lshl_add_u64 v[168:169], s[28:29], 0, v[150:151]
	s_mov_b32 m0, s34
	s_nop 0
	global_load_lds_dwordx4 v[168:169], off
	v_lshl_add_u64 v[168:169], s[28:29], 0, v[154:155]
	s_add_i32 m0, s34, 0x2000
	s_nop 0
	global_load_lds_dwordx4 v[168:169], off
	v_lshl_add_u64 v[168:169], v[240:241], 0, s[12:13]
	s_mov_b32 m0, s45
	s_nop 0
	global_load_lds_dwordx4 v[168:169], off
	v_lshl_add_u64 v[168:169], v[242:243], 0, s[12:13]
	s_mov_b32 m0, s46
	s_nop 0
	global_load_lds_dwordx4 v[168:169], off
	s_waitcnt vmcnt(8)
	s_waitcnt lgkmcnt(0)
	s_barrier
	s_waitcnt lgkmcnt(0)
	v_mfma_f32_16x16x32_bf16 v[60:63], v[128:131], v[206:209], v[60:63]
	v_mfma_f32_16x16x32_bf16 v[56:59], v[136:139], v[206:209], v[56:59]
	v_mfma_f32_16x16x32_bf16 v[44:47], v[128:131], v[214:217], v[44:47]
	v_mfma_f32_16x16x32_bf16 v[40:43], v[136:139], v[214:217], v[40:43]
	v_mfma_f32_16x16x32_bf16 v[36:39], v[128:131], v[222:225], v[36:39]
	v_mfma_f32_16x16x32_bf16 v[32:35], v[136:139], v[222:225], v[32:35]
	v_mfma_f32_16x16x32_bf16 v[20:23], v[128:131], v[230:233], v[20:23]
	v_mfma_f32_16x16x32_bf16 v[16:19], v[136:139], v[230:233], v[16:19]
	v_mfma_f32_16x16x32_bf16 v[60:63], v[132:135], v[210:213], v[60:63]
	v_mfma_f32_16x16x32_bf16 v[56:59], v[164:167], v[210:213], v[56:59]
	v_mfma_f32_16x16x32_bf16 v[44:47], v[132:135], v[218:221], v[44:47]
	v_mfma_f32_16x16x32_bf16 v[40:43], v[164:167], v[218:221], v[40:43]
	v_mfma_f32_16x16x32_bf16 v[36:39], v[132:135], v[226:229], v[36:39]
	v_mfma_f32_16x16x32_bf16 v[32:35], v[164:167], v[226:229], v[32:35]
	v_mfma_f32_16x16x32_bf16 v[20:23], v[132:135], v[234:237], v[20:23]
	v_mfma_f32_16x16x32_bf16 v[16:19], v[164:167], v[234:237], v[16:19]
	v_mfma_f32_16x16x32_bf16 v[52:55], v[190:193], v[206:209], v[52:55]
	v_mfma_f32_16x16x32_bf16 v[48:51], v[198:201], v[206:209], v[48:51]
	v_mfma_f32_16x16x32_bf16 v[28:31], v[190:193], v[214:217], v[28:31]
	v_mfma_f32_16x16x32_bf16 v[24:27], v[198:201], v[214:217], v[24:27]
	v_mfma_f32_16x16x32_bf16 v[12:15], v[190:193], v[222:225], v[12:15]
	v_mfma_f32_16x16x32_bf16 v[8:11], v[198:201], v[222:225], v[8:11]
	v_mfma_f32_16x16x32_bf16 v[4:7], v[190:193], v[230:233], v[4:7]
	v_mfma_f32_16x16x32_bf16 v[0:3], v[198:201], v[230:233], v[0:3]
	v_mfma_f32_16x16x32_bf16 v[52:55], v[194:197], v[210:213], v[52:55]
	v_mfma_f32_16x16x32_bf16 v[48:51], v[202:205], v[210:213], v[48:51]
	v_mfma_f32_16x16x32_bf16 v[28:31], v[194:197], v[218:221], v[28:31]
	v_mfma_f32_16x16x32_bf16 v[24:27], v[202:205], v[218:221], v[24:27]
	v_mfma_f32_16x16x32_bf16 v[12:15], v[194:197], v[226:229], v[12:15]
	v_mfma_f32_16x16x32_bf16 v[8:11], v[202:205], v[226:229], v[8:11]
	v_mfma_f32_16x16x32_bf16 v[4:7], v[194:197], v[234:237], v[4:7]
	v_mfma_f32_16x16x32_bf16 v[0:3], v[202:205], v[234:237], v[0:3]
	s_barrier
	s_add_i32 s54, s54, 2
	s_add_u32 s26, s26, 0x100
	s_addc_u32 s27, s27, 0
	s_add_u32 s52, s52, 0x100
	s_addc_u32 s53, s53, 0
	s_cmp_gt_u32 s54, 5
	s_cbranch_scc0 .LBB0_666
	s_and_b64 vcc, exec, s[14:15]
	s_cbranch_vccz .LBB0_669
	s_barrier

.LBB0_686:
	ds_read_b128 v[136:139], v153
	ds_read_b128 v[156:159], v153 offset:1024
	ds_read_b128 v[160:163], v153 offset:2048
	ds_read_b128 v[164:167], v153 offset:3072
	ds_read_b128 v[180:183], v154
	ds_read_b128 v[184:187], v154 offset:1024
	ds_read_b128 v[188:191], v154 offset:2048
	ds_read_b128 v[192:195], v154 offset:3072
	s_add_u32 s34, s30, 0xfffc0080
	s_addc_u32 s35, s31, -1
	s_cmp_eq_u32 s53, 12
	s_cselect_b32 s37, s23, s35
	s_cselect_b32 s36, s49, s34
	s_cselect_b32 s35, s21, s52
	s_cselect_b32 s34, s50, s51
	v_lshl_add_u64 v[148:149], s[30:31], 0, v[128:129]
	s_add_i32 m0, s29, 0xc000
	ds_read_b128 v[196:199], v155
	ds_read_b128 v[200:203], v155 offset:1024
	ds_read_b128 v[204:207], v155 offset:2048
	ds_read_b128 v[208:211], v155 offset:3072
	ds_read_b128 v[212:215], v155 offset:4096
	ds_read_b128 v[216:219], v155 offset:5120
	ds_read_b128 v[220:223], v155 offset:6144
	ds_read_b128 v[224:227], v155 offset:7168
	global_load_lds_dwordx4 v[148:149], off
	v_lshl_add_u64 v[148:149], s[30:31], 0, v[130:131]
	s_add_i32 m0, s29, 0xe000
	s_nop 0
	global_load_lds_dwordx4 v[148:149], off
	s_waitcnt vmcnt(8)
	s_waitcnt lgkmcnt(0)
	s_barrier
	s_waitcnt lgkmcnt(0)
	v_mfma_f32_16x16x32_bf16 v[124:127], v[136:139], v[196:199], v[124:127]
	v_mfma_f32_16x16x32_bf16 v[120:123], v[160:163], v[196:199], v[120:123]
	v_mfma_f32_16x16x32_bf16 v[108:111], v[136:139], v[204:207], v[108:111]
	v_mfma_f32_16x16x32_bf16 v[104:107], v[160:163], v[204:207], v[104:107]
	v_mfma_f32_16x16x32_bf16 v[92:95], v[136:139], v[212:215], v[92:95]
	v_mfma_f32_16x16x32_bf16 v[88:91], v[160:163], v[212:215], v[88:91]
	v_mfma_f32_16x16x32_bf16 v[76:79], v[136:139], v[220:223], v[76:79]
	v_mfma_f32_16x16x32_bf16 v[72:75], v[160:163], v[220:223], v[72:75]
	v_mfma_f32_16x16x32_bf16 v[124:127], v[156:159], v[200:203], v[124:127]
	v_mfma_f32_16x16x32_bf16 v[120:123], v[164:167], v[200:203], v[120:123]
	v_mfma_f32_16x16x32_bf16 v[108:111], v[156:159], v[208:211], v[108:111]
	v_mfma_f32_16x16x32_bf16 v[104:107], v[164:167], v[208:211], v[104:107]
	v_mfma_f32_16x16x32_bf16 v[92:95], v[156:159], v[216:219], v[92:95]
	v_mfma_f32_16x16x32_bf16 v[88:91], v[164:167], v[216:219], v[88:91]
	v_mfma_f32_16x16x32_bf16 v[76:79], v[156:159], v[224:227], v[76:79]
	v_mfma_f32_16x16x32_bf16 v[72:75], v[164:167], v[224:227], v[72:75]
	v_mfma_f32_16x16x32_bf16 v[116:119], v[180:183], v[196:199], v[116:119]
	v_mfma_f32_16x16x32_bf16 v[112:115], v[188:191], v[196:199], v[112:115]
	v_mfma_f32_16x16x32_bf16 v[100:103], v[180:183], v[204:207], v[100:103]
	v_mfma_f32_16x16x32_bf16 v[96:99], v[188:191], v[204:207], v[96:99]
	v_mfma_f32_16x16x32_bf16 v[84:87], v[180:183], v[212:215], v[84:87]
	v_mfma_f32_16x16x32_bf16 v[80:83], v[188:191], v[212:215], v[80:83]
	v_mfma_f32_16x16x32_bf16 v[68:71], v[180:183], v[220:223], v[68:71]
	v_mfma_f32_16x16x32_bf16 v[64:67], v[188:191], v[220:223], v[64:67]
	v_mfma_f32_16x16x32_bf16 v[116:119], v[184:187], v[200:203], v[116:119]
	v_mfma_f32_16x16x32_bf16 v[112:115], v[192:195], v[200:203], v[112:115]
	v_mfma_f32_16x16x32_bf16 v[100:103], v[184:187], v[208:211], v[100:103]
	v_mfma_f32_16x16x32_bf16 v[96:99], v[192:195], v[208:211], v[96:99]
	v_mfma_f32_16x16x32_bf16 v[84:87], v[184:187], v[216:219], v[84:87]
	v_mfma_f32_16x16x32_bf16 v[80:83], v[192:195], v[216:219], v[80:83]
	v_mfma_f32_16x16x32_bf16 v[68:71], v[184:187], v[224:227], v[68:71]
	v_mfma_f32_16x16x32_bf16 v[64:67], v[192:195], v[224:227], v[64:67]
	s_barrier
	s_add_i32 s54, s46, s40
	v_lshl_add_u64 v[148:149], s[34:35], 0, v[142:143]
	s_mov_b32 m0, s54
	ds_read_b128 v[196:199], v155 offset:16384
	ds_read_b128 v[200:203], v155 offset:17408
	ds_read_b128 v[204:207], v155 offset:18432
	ds_read_b128 v[208:211], v155 offset:19456
	ds_read_b128 v[212:215], v155 offset:20480
	ds_read_b128 v[216:219], v155 offset:21504
	ds_read_b128 v[220:223], v155 offset:22528
	ds_read_b128 v[224:227], v155 offset:23552
	global_load_lds_dwordx4 v[148:149], off
	s_add_i32 m0, s54, 0x2000
	s_add_u32 s54, s34, 0x40000
	v_lshl_add_u64 v[168:169], s[34:35], 0, v[146:147]
	s_addc_u32 s55, s35, 0
	s_add_i32 s56, s47, s40
	global_load_lds_dwordx4 v[168:169], off
	v_lshl_add_u64 v[228:229], s[54:55], 0, v[142:143]
	s_mov_b32 m0, s56
	v_lshl_add_u64 v[230:231], s[36:37], 0, v[144:145]
	global_load_lds_dwordx4 v[228:229], off
	v_lshl_add_u64 v[228:229], s[54:55], 0, v[146:147]
	s_add_i32 m0, s56, 0x2000
	s_nop 0
	global_load_lds_dwordx4 v[228:229], off
	v_lshl_add_u64 v[228:229], s[36:37], 0, v[140:141]
	s_mov_b32 m0, s29
	s_nop 0
	global_load_lds_dwordx4 v[228:229], off
	s_mov_b32 m0, s39
	s_nop 0
	global_load_lds_dwordx4 v[230:231], off
	s_waitcnt vmcnt(8)
	s_waitcnt lgkmcnt(0)
	s_barrier
	s_waitcnt lgkmcnt(0)
	v_mfma_f32_16x16x32_bf16 v[60:63], v[136:139], v[196:199], v[60:63]
	v_mfma_f32_16x16x32_bf16 v[56:59], v[160:163], v[196:199], v[56:59]
	v_mfma_f32_16x16x32_bf16 v[44:47], v[136:139], v[204:207], v[44:47]
	v_mfma_f32_16x16x32_bf16 v[40:43], v[160:163], v[204:207], v[40:43]
	v_mfma_f32_16x16x32_bf16 v[28:31], v[136:139], v[212:215], v[28:31]
	v_mfma_f32_16x16x32_bf16 v[24:27], v[160:163], v[212:215], v[24:27]
	v_mfma_f32_16x16x32_bf16 v[12:15], v[136:139], v[220:223], v[12:15]
	v_mfma_f32_16x16x32_bf16 v[8:11], v[160:163], v[220:223], v[8:11]
	v_mfma_f32_16x16x32_bf16 v[60:63], v[156:159], v[200:203], v[60:63]
	v_mfma_f32_16x16x32_bf16 v[56:59], v[164:167], v[200:203], v[56:59]
	v_mfma_f32_16x16x32_bf16 v[44:47], v[156:159], v[208:211], v[44:47]
	v_mfma_f32_16x16x32_bf16 v[40:43], v[164:167], v[208:211], v[40:43]
	v_mfma_f32_16x16x32_bf16 v[28:31], v[156:159], v[216:219], v[28:31]
	v_mfma_f32_16x16x32_bf16 v[24:27], v[164:167], v[216:219], v[24:27]
	v_mfma_f32_16x16x32_bf16 v[12:15], v[156:159], v[224:227], v[12:15]
	v_mfma_f32_16x16x32_bf16 v[8:11], v[164:167], v[224:227], v[8:11]
	v_mfma_f32_16x16x32_bf16 v[52:55], v[180:183], v[196:199], v[52:55]
	v_mfma_f32_16x16x32_bf16 v[48:51], v[188:191], v[196:199], v[48:51]
	v_mfma_f32_16x16x32_bf16 v[36:39], v[180:183], v[204:207], v[36:39]
	v_mfma_f32_16x16x32_bf16 v[32:35], v[188:191], v[204:207], v[32:35]
	v_mfma_f32_16x16x32_bf16 v[20:23], v[180:183], v[212:215], v[20:23]
	v_mfma_f32_16x16x32_bf16 v[16:19], v[188:191], v[212:215], v[16:19]
	v_mfma_f32_16x16x32_bf16 v[4:7], v[180:183], v[220:223], v[4:7]
	v_mfma_f32_16x16x32_bf16 v[0:3], v[188:191], v[220:223], v[0:3]
	v_mfma_f32_16x16x32_bf16 v[52:55], v[184:187], v[200:203], v[52:55]
	v_mfma_f32_16x16x32_bf16 v[48:51], v[192:195], v[200:203], v[48:51]
	v_mfma_f32_16x16x32_bf16 v[36:39], v[184:187], v[208:211], v[36:39]
	v_mfma_f32_16x16x32_bf16 v[32:35], v[192:195], v[208:211], v[32:35]
	v_mfma_f32_16x16x32_bf16 v[20:23], v[184:187], v[216:219], v[20:23]
	v_mfma_f32_16x16x32_bf16 v[16:19], v[192:195], v[216:219], v[16:19]
	v_mfma_f32_16x16x32_bf16 v[4:7], v[184:187], v[224:227], v[4:7]
	v_mfma_f32_16x16x32_bf16 v[0:3], v[192:195], v[224:227], v[0:3]
	s_barrier
	s_add_i32 s54, 0, 0x18000
	s_add_i32 s55, 0, 0x1c000
	v_add_u32_e32 v164, s54, v151
	v_add_u32_e32 v179, s55, v151
	ds_read_b128 v[136:139], v164
	ds_read_b128 v[156:159], v164 offset:1024
	ds_read_b128 v[160:163], v164 offset:2048
	ds_read_b128 v[164:167], v164 offset:3072
	ds_read_b128 v[180:183], v179
	ds_read_b128 v[184:187], v179 offset:1024
	ds_read_b128 v[188:191], v179 offset:2048
	ds_read_b128 v[192:195], v179 offset:3072
	s_add_u32 s36, s36, 0x40000
	s_addc_u32 s37, s37, 0
	s_mov_b32 m0, s41
	v_lshl_add_u64 v[232:233], s[36:37], 0, v[140:141]
	ds_read_b128 v[196:199], v155 offset:32768
	ds_read_b128 v[200:203], v155 offset:33792
	ds_read_b128 v[204:207], v155 offset:34816
	ds_read_b128 v[208:211], v155 offset:35840
	ds_read_b128 v[212:215], v155 offset:36864
	ds_read_b128 v[216:219], v155 offset:37888
	ds_read_b128 v[220:223], v155 offset:38912
	ds_read_b128 v[224:227], v155 offset:39936
	global_load_lds_dwordx4 v[232:233], off
	v_lshl_add_u64 v[232:233], s[36:37], 0, v[144:145]
	s_mov_b32 m0, s42
	s_nop 0
	global_load_lds_dwordx4 v[232:233], off
	s_waitcnt vmcnt(8)
	s_waitcnt lgkmcnt(0)
	s_barrier
	s_waitcnt lgkmcnt(0)
	v_mfma_f32_16x16x32_bf16 v[124:127], v[136:139], v[196:199], v[124:127]
	v_mfma_f32_16x16x32_bf16 v[120:123], v[160:163], v[196:199], v[120:123]
	v_mfma_f32_16x16x32_bf16 v[108:111], v[136:139], v[204:207], v[108:111]
	v_mfma_f32_16x16x32_bf16 v[104:107], v[160:163], v[204:207], v[104:107]
	v_mfma_f32_16x16x32_bf16 v[92:95], v[136:139], v[212:215], v[92:95]
	v_mfma_f32_16x16x32_bf16 v[88:91], v[160:163], v[212:215], v[88:91]
	v_mfma_f32_16x16x32_bf16 v[76:79], v[136:139], v[220:223], v[76:79]
	v_mfma_f32_16x16x32_bf16 v[72:75], v[160:163], v[220:223], v[72:75]
	v_mfma_f32_16x16x32_bf16 v[124:127], v[156:159], v[200:203], v[124:127]
	v_mfma_f32_16x16x32_bf16 v[120:123], v[164:167], v[200:203], v[120:123]
	v_mfma_f32_16x16x32_bf16 v[108:111], v[156:159], v[208:211], v[108:111]
	v_mfma_f32_16x16x32_bf16 v[104:107], v[164:167], v[208:211], v[104:107]
	v_mfma_f32_16x16x32_bf16 v[92:95], v[156:159], v[216:219], v[92:95]
	v_mfma_f32_16x16x32_bf16 v[88:91], v[164:167], v[216:219], v[88:91]
	v_mfma_f32_16x16x32_bf16 v[76:79], v[156:159], v[224:227], v[76:79]
	v_mfma_f32_16x16x32_bf16 v[72:75], v[164:167], v[224:227], v[72:75]
	v_mfma_f32_16x16x32_bf16 v[116:119], v[180:183], v[196:199], v[116:119]
	v_mfma_f32_16x16x32_bf16 v[112:115], v[188:191], v[196:199], v[112:115]
	v_mfma_f32_16x16x32_bf16 v[100:103], v[180:183], v[204:207], v[100:103]
	v_mfma_f32_16x16x32_bf16 v[96:99], v[188:191], v[204:207], v[96:99]
	v_mfma_f32_16x16x32_bf16 v[84:87], v[180:183], v[212:215], v[84:87]
	v_mfma_f32_16x16x32_bf16 v[80:83], v[188:191], v[212:215], v[80:83]
	v_mfma_f32_16x16x32_bf16 v[68:71], v[180:183], v[220:223], v[68:71]
	v_mfma_f32_16x16x32_bf16 v[64:67], v[188:191], v[220:223], v[64:67]
	v_mfma_f32_16x16x32_bf16 v[116:119], v[184:187], v[200:203], v[116:119]
	v_mfma_f32_16x16x32_bf16 v[112:115], v[192:195], v[200:203], v[112:115]
	v_mfma_f32_16x16x32_bf16 v[100:103], v[184:187], v[208:211], v[100:103]
	v_mfma_f32_16x16x32_bf16 v[96:99], v[192:195], v[208:211], v[96:99]
	v_mfma_f32_16x16x32_bf16 v[84:87], v[184:187], v[216:219], v[84:87]
	v_mfma_f32_16x16x32_bf16 v[80:83], v[192:195], v[216:219], v[80:83]
	v_mfma_f32_16x16x32_bf16 v[68:71], v[184:187], v[224:227], v[68:71]
	v_mfma_f32_16x16x32_bf16 v[64:67], v[192:195], v[224:227], v[64:67]
	s_barrier
	s_add_i32 s36, s54, s40
	v_lshl_add_u64 v[148:149], v[148:149], 0, s[10:11]
	s_mov_b32 m0, s36
	ds_read_b128 v[196:199], v155 offset:49152
	ds_read_b128 v[200:203], v155 offset:50176
	ds_read_b128 v[204:207], v155 offset:51200
	ds_read_b128 v[208:211], v155 offset:52224
	ds_read_b128 v[212:215], v155 offset:53248
	ds_read_b128 v[216:219], v155 offset:54272
	ds_read_b128 v[220:223], v155 offset:55296
	ds_read_b128 v[224:227], v155 offset:56320
	global_load_lds_dwordx4 v[148:149], off
	s_add_i32 m0, s36, 0x2000
	s_add_u32 s34, s34, 0x40080
	v_lshl_add_u64 v[148:149], v[168:169], 0, s[10:11]
	s_addc_u32 s35, s35, 0
	s_add_i32 s36, s55, s40
	global_load_lds_dwordx4 v[148:149], off
	v_lshl_add_u64 v[148:149], s[34:35], 0, v[142:143]
	s_mov_b32 m0, s36
	s_nop 0
	global_load_lds_dwordx4 v[148:149], off
	v_lshl_add_u64 v[148:149], s[34:35], 0, v[146:147]
	s_add_i32 m0, s36, 0x2000
	s_nop 0
	global_load_lds_dwordx4 v[148:149], off
	v_lshl_add_u64 v[148:149], v[228:229], 0, s[10:11]
	s_mov_b32 m0, s44
	s_nop 0
	global_load_lds_dwordx4 v[148:149], off
	v_lshl_add_u64 v[148:149], v[230:231], 0, s[10:11]
	s_mov_b32 m0, s45
	s_nop 0
	global_load_lds_dwordx4 v[148:149], off
	s_waitcnt vmcnt(8)
	s_waitcnt lgkmcnt(0)
	s_barrier
	s_waitcnt lgkmcnt(0)
	v_mfma_f32_16x16x32_bf16 v[60:63], v[136:139], v[196:199], v[60:63]
	v_mfma_f32_16x16x32_bf16 v[56:59], v[160:163], v[196:199], v[56:59]
	v_mfma_f32_16x16x32_bf16 v[44:47], v[136:139], v[204:207], v[44:47]
	v_mfma_f32_16x16x32_bf16 v[40:43], v[160:163], v[204:207], v[40:43]
	v_mfma_f32_16x16x32_bf16 v[28:31], v[136:139], v[212:215], v[28:31]
	v_mfma_f32_16x16x32_bf16 v[24:27], v[160:163], v[212:215], v[24:27]
	v_mfma_f32_16x16x32_bf16 v[12:15], v[136:139], v[220:223], v[12:15]
	v_mfma_f32_16x16x32_bf16 v[8:11], v[160:163], v[220:223], v[8:11]
	v_mfma_f32_16x16x32_bf16 v[60:63], v[156:159], v[200:203], v[60:63]
	v_mfma_f32_16x16x32_bf16 v[56:59], v[164:167], v[200:203], v[56:59]
	v_mfma_f32_16x16x32_bf16 v[44:47], v[156:159], v[208:211], v[44:47]
	v_mfma_f32_16x16x32_bf16 v[40:43], v[164:167], v[208:211], v[40:43]
	v_mfma_f32_16x16x32_bf16 v[28:31], v[156:159], v[216:219], v[28:31]
	v_mfma_f32_16x16x32_bf16 v[24:27], v[164:167], v[216:219], v[24:27]
	v_mfma_f32_16x16x32_bf16 v[12:15], v[156:159], v[224:227], v[12:15]
	v_mfma_f32_16x16x32_bf16 v[8:11], v[164:167], v[224:227], v[8:11]
	v_mfma_f32_16x16x32_bf16 v[52:55], v[180:183], v[196:199], v[52:55]
	v_mfma_f32_16x16x32_bf16 v[48:51], v[188:191], v[196:199], v[48:51]
	v_mfma_f32_16x16x32_bf16 v[36:39], v[180:183], v[204:207], v[36:39]
	v_mfma_f32_16x16x32_bf16 v[32:35], v[188:191], v[204:207], v[32:35]
	v_mfma_f32_16x16x32_bf16 v[20:23], v[180:183], v[212:215], v[20:23]
	v_mfma_f32_16x16x32_bf16 v[16:19], v[188:191], v[212:215], v[16:19]
	v_mfma_f32_16x16x32_bf16 v[4:7], v[180:183], v[220:223], v[4:7]
	v_mfma_f32_16x16x32_bf16 v[0:3], v[188:191], v[220:223], v[0:3]
	v_mfma_f32_16x16x32_bf16 v[52:55], v[184:187], v[200:203], v[52:55]
	v_mfma_f32_16x16x32_bf16 v[48:51], v[192:195], v[200:203], v[48:51]
	v_mfma_f32_16x16x32_bf16 v[36:39], v[184:187], v[208:211], v[36:39]
	v_mfma_f32_16x16x32_bf16 v[32:35], v[192:195], v[208:211], v[32:35]
	v_mfma_f32_16x16x32_bf16 v[20:23], v[184:187], v[216:219], v[20:23]
	v_mfma_f32_16x16x32_bf16 v[16:19], v[192:195], v[216:219], v[16:19]
	v_mfma_f32_16x16x32_bf16 v[4:7], v[184:187], v[224:227], v[4:7]
	v_mfma_f32_16x16x32_bf16 v[0:3], v[192:195], v[224:227], v[0:3]
	s_barrier
	s_add_i32 s53, s53, 2
	s_add_u32 s30, s30, 0x100
	s_addc_u32 s31, s31, 0
	s_add_u32 s51, s51, 0x100
	s_addc_u32 s52, s52, 0
	s_cmp_gt_u32 s53, 13
	s_cbranch_scc0 .LBB0_686
	s_and_b64 vcc, exec, s[12:13]
	s_cbranch_vccz .LBB0_689
	s_barrier

.LBB0_758:
	ds_read_b128 v[140:143], v183
	ds_read_b128 v[144:147], v183 offset:1024
	ds_read_b128 v[148:151], v183 offset:2048
	ds_read_b128 v[152:155], v183 offset:3072
	ds_read_b128 v[156:159], v184
	ds_read_b128 v[160:163], v184 offset:1024
	ds_read_b128 v[164:167], v184 offset:2048
	ds_read_b128 v[186:189], v184 offset:3072
	s_add_u32 s36, s34, 0xfffc0080
	s_addc_u32 s37, s35, -1
	s_cmp_eq_u32 s60, 12
	s_cselect_b32 s39, s25, s37
	s_cselect_b32 s38, s54, s36
	s_cselect_b32 s37, s23, s57
	s_cselect_b32 s36, s55, s56
	v_lshl_add_u64 v[222:223], s[34:35], 0, v[132:133]
	s_add_i32 m0, s31, 0xc000
	ds_read_b128 v[190:193], v185
	ds_read_b128 v[194:197], v185 offset:1024
	ds_read_b128 v[198:201], v185 offset:2048
	ds_read_b128 v[202:205], v185 offset:3072
	ds_read_b128 v[206:209], v185 offset:4096
	ds_read_b128 v[210:213], v185 offset:5120
	ds_read_b128 v[214:217], v185 offset:6144
	ds_read_b128 v[218:221], v185 offset:7168
	global_load_lds_dwordx4 v[222:223], off
	v_lshl_add_u64 v[222:223], s[34:35], 0, v[134:135]
	s_add_i32 m0, s31, 0xe000
	s_nop 0
	global_load_lds_dwordx4 v[222:223], off
	s_waitcnt vmcnt(8)
	s_waitcnt lgkmcnt(0)
	s_barrier
	s_waitcnt lgkmcnt(0)
	v_mfma_f32_16x16x32_bf16 v[124:127], v[140:143], v[190:193], v[124:127]
	v_mfma_f32_16x16x32_bf16 v[120:123], v[148:151], v[190:193], v[120:123]
	v_mfma_f32_16x16x32_bf16 v[108:111], v[140:143], v[198:201], v[108:111]
	v_mfma_f32_16x16x32_bf16 v[104:107], v[148:151], v[198:201], v[104:107]
	v_mfma_f32_16x16x32_bf16 v[92:95], v[140:143], v[206:209], v[92:95]
	v_mfma_f32_16x16x32_bf16 v[88:91], v[148:151], v[206:209], v[88:91]
	v_mfma_f32_16x16x32_bf16 v[76:79], v[140:143], v[214:217], v[76:79]
	v_mfma_f32_16x16x32_bf16 v[72:75], v[148:151], v[214:217], v[72:75]
	v_mfma_f32_16x16x32_bf16 v[124:127], v[144:147], v[194:197], v[124:127]
	v_mfma_f32_16x16x32_bf16 v[120:123], v[152:155], v[194:197], v[120:123]
	v_mfma_f32_16x16x32_bf16 v[108:111], v[144:147], v[202:205], v[108:111]
	v_mfma_f32_16x16x32_bf16 v[104:107], v[152:155], v[202:205], v[104:107]
	v_mfma_f32_16x16x32_bf16 v[92:95], v[144:147], v[210:213], v[92:95]
	v_mfma_f32_16x16x32_bf16 v[88:91], v[152:155], v[210:213], v[88:91]
	v_mfma_f32_16x16x32_bf16 v[76:79], v[144:147], v[218:221], v[76:79]
	v_mfma_f32_16x16x32_bf16 v[72:75], v[152:155], v[218:221], v[72:75]
	v_mfma_f32_16x16x32_bf16 v[116:119], v[156:159], v[190:193], v[116:119]
	v_mfma_f32_16x16x32_bf16 v[112:115], v[164:167], v[190:193], v[112:115]
	v_mfma_f32_16x16x32_bf16 v[100:103], v[156:159], v[198:201], v[100:103]
	v_mfma_f32_16x16x32_bf16 v[96:99], v[164:167], v[198:201], v[96:99]
	v_mfma_f32_16x16x32_bf16 v[84:87], v[156:159], v[206:209], v[84:87]
	v_mfma_f32_16x16x32_bf16 v[80:83], v[164:167], v[206:209], v[80:83]
	v_mfma_f32_16x16x32_bf16 v[68:71], v[156:159], v[214:217], v[68:71]
	v_mfma_f32_16x16x32_bf16 v[64:67], v[164:167], v[214:217], v[64:67]
	v_mfma_f32_16x16x32_bf16 v[116:119], v[160:163], v[194:197], v[116:119]
	v_mfma_f32_16x16x32_bf16 v[112:115], v[186:189], v[194:197], v[112:115]
	v_mfma_f32_16x16x32_bf16 v[100:103], v[160:163], v[202:205], v[100:103]
	v_mfma_f32_16x16x32_bf16 v[96:99], v[186:189], v[202:205], v[96:99]
	v_mfma_f32_16x16x32_bf16 v[84:87], v[160:163], v[210:213], v[84:87]
	v_mfma_f32_16x16x32_bf16 v[80:83], v[186:189], v[210:213], v[80:83]
	v_mfma_f32_16x16x32_bf16 v[68:71], v[160:163], v[218:221], v[68:71]
	v_mfma_f32_16x16x32_bf16 v[64:67], v[186:189], v[218:221], v[64:67]
	s_barrier
	s_add_i32 s61, s51, s42
	v_lshl_add_u64 v[222:223], s[36:37], 0, v[128:129]
	s_mov_b32 m0, s61
	ds_read_b128 v[190:193], v185 offset:16384
	ds_read_b128 v[194:197], v185 offset:17408
	ds_read_b128 v[198:201], v185 offset:18432
	ds_read_b128 v[202:205], v185 offset:19456
	ds_read_b128 v[206:209], v185 offset:20480
	ds_read_b128 v[210:213], v185 offset:21504
	ds_read_b128 v[214:217], v185 offset:22528
	ds_read_b128 v[218:221], v185 offset:23552
	global_load_lds_dwordx4 v[222:223], off
	s_add_i32 m0, s61, 0x2000
	s_add_u32 s62, s36, 0x40000
	v_lshl_add_u64 v[224:225], s[36:37], 0, v[130:131]
	s_addc_u32 s63, s37, 0
	s_add_i32 s61, s52, s42
	global_load_lds_dwordx4 v[224:225], off
	v_lshl_add_u64 v[226:227], s[62:63], 0, v[128:129]
	s_mov_b32 m0, s61
	v_lshl_add_u64 v[228:229], s[38:39], 0, v[130:131]
	global_load_lds_dwordx4 v[226:227], off
	v_lshl_add_u64 v[226:227], s[62:63], 0, v[130:131]
	s_add_i32 m0, s61, 0x2000
	s_nop 0
	global_load_lds_dwordx4 v[226:227], off
	v_lshl_add_u64 v[226:227], s[38:39], 0, v[128:129]
	s_mov_b32 m0, s31
	s_nop 0
	global_load_lds_dwordx4 v[226:227], off
	s_mov_b32 m0, s43
	s_nop 0
	global_load_lds_dwordx4 v[228:229], off
	s_waitcnt vmcnt(8)
	s_waitcnt lgkmcnt(0)
	s_barrier
	s_waitcnt lgkmcnt(0)
	v_mfma_f32_16x16x32_bf16 v[60:63], v[140:143], v[190:193], v[60:63]
	v_mfma_f32_16x16x32_bf16 v[56:59], v[148:151], v[190:193], v[56:59]
	v_mfma_f32_16x16x32_bf16 v[44:47], v[140:143], v[198:201], v[44:47]
	v_mfma_f32_16x16x32_bf16 v[40:43], v[148:151], v[198:201], v[40:43]
	v_mfma_f32_16x16x32_bf16 v[28:31], v[140:143], v[206:209], v[28:31]
	v_mfma_f32_16x16x32_bf16 v[24:27], v[148:151], v[206:209], v[24:27]
	v_mfma_f32_16x16x32_bf16 v[12:15], v[140:143], v[214:217], v[12:15]
	v_mfma_f32_16x16x32_bf16 v[8:11], v[148:151], v[214:217], v[8:11]
	v_mfma_f32_16x16x32_bf16 v[60:63], v[144:147], v[194:197], v[60:63]
	v_mfma_f32_16x16x32_bf16 v[56:59], v[152:155], v[194:197], v[56:59]
	v_mfma_f32_16x16x32_bf16 v[44:47], v[144:147], v[202:205], v[44:47]
	v_mfma_f32_16x16x32_bf16 v[40:43], v[152:155], v[202:205], v[40:43]
	v_mfma_f32_16x16x32_bf16 v[28:31], v[144:147], v[210:213], v[28:31]
	v_mfma_f32_16x16x32_bf16 v[24:27], v[152:155], v[210:213], v[24:27]
	v_mfma_f32_16x16x32_bf16 v[12:15], v[144:147], v[218:221], v[12:15]
	v_mfma_f32_16x16x32_bf16 v[8:11], v[152:155], v[218:221], v[8:11]
	v_mfma_f32_16x16x32_bf16 v[52:55], v[156:159], v[190:193], v[52:55]
	v_mfma_f32_16x16x32_bf16 v[48:51], v[164:167], v[190:193], v[48:51]
	v_mfma_f32_16x16x32_bf16 v[36:39], v[156:159], v[198:201], v[36:39]
	v_mfma_f32_16x16x32_bf16 v[32:35], v[164:167], v[198:201], v[32:35]
	v_mfma_f32_16x16x32_bf16 v[20:23], v[156:159], v[206:209], v[20:23]
	v_mfma_f32_16x16x32_bf16 v[16:19], v[164:167], v[206:209], v[16:19]
	v_mfma_f32_16x16x32_bf16 v[4:7], v[156:159], v[214:217], v[4:7]
	v_mfma_f32_16x16x32_bf16 v[0:3], v[164:167], v[214:217], v[0:3]
	v_mfma_f32_16x16x32_bf16 v[52:55], v[160:163], v[194:197], v[52:55]
	v_mfma_f32_16x16x32_bf16 v[48:51], v[186:189], v[194:197], v[48:51]
	v_mfma_f32_16x16x32_bf16 v[36:39], v[160:163], v[202:205], v[36:39]
	v_mfma_f32_16x16x32_bf16 v[32:35], v[186:189], v[202:205], v[32:35]
	v_mfma_f32_16x16x32_bf16 v[20:23], v[160:163], v[210:213], v[20:23]
	v_mfma_f32_16x16x32_bf16 v[16:19], v[186:189], v[210:213], v[16:19]
	v_mfma_f32_16x16x32_bf16 v[4:7], v[160:163], v[218:221], v[4:7]
	v_mfma_f32_16x16x32_bf16 v[0:3], v[186:189], v[218:221], v[0:3]
	s_barrier
	s_add_i32 s61, 0, 0x18000
	s_add_i32 s62, 0, 0x1c000
	v_add_u32_e32 v152, s61, v181
	v_add_u32_e32 v186, s62, v181
	ds_read_b128 v[140:143], v152
	ds_read_b128 v[144:147], v152 offset:1024
	ds_read_b128 v[148:151], v152 offset:2048
	ds_read_b128 v[152:155], v152 offset:3072
	ds_read_b128 v[156:159], v186
	ds_read_b128 v[160:163], v186 offset:1024
	ds_read_b128 v[164:167], v186 offset:2048
	ds_read_b128 v[186:189], v186 offset:3072
	s_add_u32 s38, s38, 0x40000
	s_addc_u32 s39, s39, 0
	s_mov_b32 m0, s44
	v_lshl_add_u64 v[230:231], s[38:39], 0, v[128:129]
	ds_read_b128 v[190:193], v185 offset:32768
	ds_read_b128 v[194:197], v185 offset:33792
	ds_read_b128 v[198:201], v185 offset:34816
	ds_read_b128 v[202:205], v185 offset:35840
	ds_read_b128 v[206:209], v185 offset:36864
	ds_read_b128 v[210:213], v185 offset:37888
	ds_read_b128 v[214:217], v185 offset:38912
	ds_read_b128 v[218:221], v185 offset:39936
	global_load_lds_dwordx4 v[230:231], off
	v_lshl_add_u64 v[230:231], s[38:39], 0, v[130:131]
	s_mov_b32 m0, s45
	s_nop 0
	global_load_lds_dwordx4 v[230:231], off
	s_waitcnt vmcnt(8)
	s_waitcnt lgkmcnt(0)
	s_barrier
	s_waitcnt lgkmcnt(0)
	v_mfma_f32_16x16x32_bf16 v[124:127], v[140:143], v[190:193], v[124:127]
	v_mfma_f32_16x16x32_bf16 v[120:123], v[148:151], v[190:193], v[120:123]
	v_mfma_f32_16x16x32_bf16 v[108:111], v[140:143], v[198:201], v[108:111]
	v_mfma_f32_16x16x32_bf16 v[104:107], v[148:151], v[198:201], v[104:107]
	v_mfma_f32_16x16x32_bf16 v[92:95], v[140:143], v[206:209], v[92:95]
	v_mfma_f32_16x16x32_bf16 v[88:91], v[148:151], v[206:209], v[88:91]
	v_mfma_f32_16x16x32_bf16 v[76:79], v[140:143], v[214:217], v[76:79]
	v_mfma_f32_16x16x32_bf16 v[72:75], v[148:151], v[214:217], v[72:75]
	v_mfma_f32_16x16x32_bf16 v[124:127], v[144:147], v[194:197], v[124:127]
	v_mfma_f32_16x16x32_bf16 v[120:123], v[152:155], v[194:197], v[120:123]
	v_mfma_f32_16x16x32_bf16 v[108:111], v[144:147], v[202:205], v[108:111]
	v_mfma_f32_16x16x32_bf16 v[104:107], v[152:155], v[202:205], v[104:107]
	v_mfma_f32_16x16x32_bf16 v[92:95], v[144:147], v[210:213], v[92:95]
	v_mfma_f32_16x16x32_bf16 v[88:91], v[152:155], v[210:213], v[88:91]
	v_mfma_f32_16x16x32_bf16 v[76:79], v[144:147], v[218:221], v[76:79]
	v_mfma_f32_16x16x32_bf16 v[72:75], v[152:155], v[218:221], v[72:75]
	v_mfma_f32_16x16x32_bf16 v[116:119], v[156:159], v[190:193], v[116:119]
	v_mfma_f32_16x16x32_bf16 v[112:115], v[164:167], v[190:193], v[112:115]
	v_mfma_f32_16x16x32_bf16 v[100:103], v[156:159], v[198:201], v[100:103]
	v_mfma_f32_16x16x32_bf16 v[96:99], v[164:167], v[198:201], v[96:99]
	v_mfma_f32_16x16x32_bf16 v[84:87], v[156:159], v[206:209], v[84:87]
	v_mfma_f32_16x16x32_bf16 v[80:83], v[164:167], v[206:209], v[80:83]
	v_mfma_f32_16x16x32_bf16 v[68:71], v[156:159], v[214:217], v[68:71]
	v_mfma_f32_16x16x32_bf16 v[64:67], v[164:167], v[214:217], v[64:67]
	v_mfma_f32_16x16x32_bf16 v[116:119], v[160:163], v[194:197], v[116:119]
	v_mfma_f32_16x16x32_bf16 v[112:115], v[186:189], v[194:197], v[112:115]
	v_mfma_f32_16x16x32_bf16 v[100:103], v[160:163], v[202:205], v[100:103]
	v_mfma_f32_16x16x32_bf16 v[96:99], v[186:189], v[202:205], v[96:99]
	v_mfma_f32_16x16x32_bf16 v[84:87], v[160:163], v[210:213], v[84:87]
	v_mfma_f32_16x16x32_bf16 v[80:83], v[186:189], v[210:213], v[80:83]
	v_mfma_f32_16x16x32_bf16 v[68:71], v[160:163], v[218:221], v[68:71]
	v_mfma_f32_16x16x32_bf16 v[64:67], v[186:189], v[218:221], v[64:67]
	s_barrier
	s_add_i32 s38, s61, s42
	v_lshl_add_u64 v[222:223], v[222:223], 0, s[12:13]
	s_mov_b32 m0, s38
	ds_read_b128 v[190:193], v185 offset:49152
	ds_read_b128 v[194:197], v185 offset:50176
	ds_read_b128 v[198:201], v185 offset:51200
	ds_read_b128 v[202:205], v185 offset:52224
	ds_read_b128 v[206:209], v185 offset:53248
	ds_read_b128 v[210:213], v185 offset:54272
	ds_read_b128 v[214:217], v185 offset:55296
	ds_read_b128 v[218:221], v185 offset:56320
	global_load_lds_dwordx4 v[222:223], off
	s_add_i32 m0, s38, 0x2000
	s_add_u32 s36, s36, 0x40080
	v_lshl_add_u64 v[222:223], v[224:225], 0, s[12:13]
	s_addc_u32 s37, s37, 0
	s_add_i32 s38, s62, s42
	global_load_lds_dwordx4 v[222:223], off
	v_lshl_add_u64 v[222:223], s[36:37], 0, v[128:129]
	s_mov_b32 m0, s38
	s_nop 0
	global_load_lds_dwordx4 v[222:223], off
	v_lshl_add_u64 v[222:223], s[36:37], 0, v[130:131]
	s_add_i32 m0, s38, 0x2000
	s_nop 0
	global_load_lds_dwordx4 v[222:223], off
	v_lshl_add_u64 v[222:223], v[226:227], 0, s[12:13]
	s_mov_b32 m0, s48
	s_nop 0
	global_load_lds_dwordx4 v[222:223], off
	v_lshl_add_u64 v[222:223], v[228:229], 0, s[12:13]
	s_mov_b32 m0, s49
	s_nop 0
	global_load_lds_dwordx4 v[222:223], off
	s_waitcnt vmcnt(8)
	s_waitcnt lgkmcnt(0)
	s_barrier
	s_waitcnt lgkmcnt(0)
	v_mfma_f32_16x16x32_bf16 v[60:63], v[140:143], v[190:193], v[60:63]
	v_mfma_f32_16x16x32_bf16 v[56:59], v[148:151], v[190:193], v[56:59]
	v_mfma_f32_16x16x32_bf16 v[44:47], v[140:143], v[198:201], v[44:47]
	v_mfma_f32_16x16x32_bf16 v[40:43], v[148:151], v[198:201], v[40:43]
	v_mfma_f32_16x16x32_bf16 v[28:31], v[140:143], v[206:209], v[28:31]
	v_mfma_f32_16x16x32_bf16 v[24:27], v[148:151], v[206:209], v[24:27]
	v_mfma_f32_16x16x32_bf16 v[12:15], v[140:143], v[214:217], v[12:15]
	v_mfma_f32_16x16x32_bf16 v[8:11], v[148:151], v[214:217], v[8:11]
	v_mfma_f32_16x16x32_bf16 v[60:63], v[144:147], v[194:197], v[60:63]
	v_mfma_f32_16x16x32_bf16 v[56:59], v[152:155], v[194:197], v[56:59]
	v_mfma_f32_16x16x32_bf16 v[44:47], v[144:147], v[202:205], v[44:47]
	v_mfma_f32_16x16x32_bf16 v[40:43], v[152:155], v[202:205], v[40:43]
	v_mfma_f32_16x16x32_bf16 v[28:31], v[144:147], v[210:213], v[28:31]
	v_mfma_f32_16x16x32_bf16 v[24:27], v[152:155], v[210:213], v[24:27]
	v_mfma_f32_16x16x32_bf16 v[12:15], v[144:147], v[218:221], v[12:15]
	v_mfma_f32_16x16x32_bf16 v[8:11], v[152:155], v[218:221], v[8:11]
	v_mfma_f32_16x16x32_bf16 v[52:55], v[156:159], v[190:193], v[52:55]
	v_mfma_f32_16x16x32_bf16 v[48:51], v[164:167], v[190:193], v[48:51]
	v_mfma_f32_16x16x32_bf16 v[36:39], v[156:159], v[198:201], v[36:39]
	v_mfma_f32_16x16x32_bf16 v[32:35], v[164:167], v[198:201], v[32:35]
	v_mfma_f32_16x16x32_bf16 v[20:23], v[156:159], v[206:209], v[20:23]
	v_mfma_f32_16x16x32_bf16 v[16:19], v[164:167], v[206:209], v[16:19]
	v_mfma_f32_16x16x32_bf16 v[4:7], v[156:159], v[214:217], v[4:7]
	v_mfma_f32_16x16x32_bf16 v[0:3], v[164:167], v[214:217], v[0:3]
	v_mfma_f32_16x16x32_bf16 v[52:55], v[160:163], v[194:197], v[52:55]
	v_mfma_f32_16x16x32_bf16 v[48:51], v[186:189], v[194:197], v[48:51]
	v_mfma_f32_16x16x32_bf16 v[36:39], v[160:163], v[202:205], v[36:39]
	v_mfma_f32_16x16x32_bf16 v[32:35], v[186:189], v[202:205], v[32:35]
	v_mfma_f32_16x16x32_bf16 v[20:23], v[160:163], v[210:213], v[20:23]
	v_mfma_f32_16x16x32_bf16 v[16:19], v[186:189], v[210:213], v[16:19]
	v_mfma_f32_16x16x32_bf16 v[4:7], v[160:163], v[218:221], v[4:7]
	v_mfma_f32_16x16x32_bf16 v[0:3], v[186:189], v[218:221], v[0:3]
	s_barrier
	s_add_i32 s60, s60, 2
	s_add_u32 s34, s34, 0x100
	s_addc_u32 s35, s35, 0
	s_add_u32 s56, s56, 0x100
	s_addc_u32 s57, s57, 0
	s_cmp_gt_u32 s60, 13
	s_cbranch_scc0 .LBB0_758
	s_and_b64 vcc, exec, s[14:15]
	s_cbranch_vccz .LBB0_761
	s_barrier

.LBB0_778:
	v_add_u32_e32 v147, s43, v145
	ds_read_b128 v[148:151], v147
	ds_read_b128 v[152:155], v147 offset:1024
	ds_read_b128 v[156:159], v147 offset:2048
	ds_read_b128 v[160:163], v147 offset:3072
	v_add_u32_e32 v147, s44, v145
	s_add_u32 s26, s12, s24
	ds_read_b128 v[164:167], v147
	ds_read_b128 v[180:183], v147 offset:1024
	ds_read_b128 v[184:187], v147 offset:2048
	ds_read_b128 v[188:191], v147 offset:3072
	s_addc_u32 s27, s13, s25
	s_add_u32 s26, s26, 0x100
	s_addc_u32 s27, s27, 0
	s_add_u32 s51, s46, s24
	s_addc_u32 s52, s47, s25
	s_cmpk_eq_i32 s24, 0x700
	s_cselect_b32 s29, s19, s27
	s_cselect_b32 s28, s48, s26
	s_cselect_b32 s27, s17, s52
	s_cselect_b32 s26, s49, s51
	v_lshl_add_u64 v[168:169], v[140:141], 0, s[24:25]
	s_add_i32 m0, s11, 0xc000
	ds_read_b128 v[192:195], v146
	ds_read_b128 v[196:199], v146 offset:1024
	ds_read_b128 v[200:203], v146 offset:2048
	ds_read_b128 v[204:207], v146 offset:3072
	ds_read_b128 v[208:211], v146 offset:4096
	ds_read_b128 v[212:215], v146 offset:5120
	ds_read_b128 v[216:219], v146 offset:6144
	ds_read_b128 v[220:223], v146 offset:7168
	global_load_lds_dwordx4 v[168:169], off
	v_lshl_add_u64 v[168:169], v[142:143], 0, s[24:25]
	s_add_i32 m0, s11, 0xe000
	s_nop 0
	global_load_lds_dwordx4 v[168:169], off
	s_waitcnt vmcnt(8)
	s_waitcnt lgkmcnt(0)
	s_barrier
	s_waitcnt lgkmcnt(0)
	v_mfma_f32_16x16x32_bf16 v[100:103], v[148:151], v[192:195], v[100:103]
	v_mfma_f32_16x16x32_bf16 v[96:99], v[156:159], v[192:195], v[96:99]
	v_mfma_f32_16x16x32_bf16 v[108:111], v[148:151], v[200:203], v[108:111]
	v_mfma_f32_16x16x32_bf16 v[84:87], v[156:159], v[200:203], v[84:87]
	v_mfma_f32_16x16x32_bf16 v[116:119], v[148:151], v[208:211], v[116:119]
	v_mfma_f32_16x16x32_bf16 v[112:115], v[156:159], v[208:211], v[112:115]
	v_mfma_f32_16x16x32_bf16 v[124:127], v[148:151], v[216:219], v[124:127]
	v_mfma_f32_16x16x32_bf16 v[120:123], v[156:159], v[216:219], v[120:123]
	v_mfma_f32_16x16x32_bf16 v[100:103], v[152:155], v[196:199], v[100:103]
	v_mfma_f32_16x16x32_bf16 v[96:99], v[160:163], v[196:199], v[96:99]
	v_mfma_f32_16x16x32_bf16 v[108:111], v[152:155], v[204:207], v[108:111]
	v_mfma_f32_16x16x32_bf16 v[84:87], v[160:163], v[204:207], v[84:87]
	v_mfma_f32_16x16x32_bf16 v[116:119], v[152:155], v[212:215], v[116:119]
	v_mfma_f32_16x16x32_bf16 v[112:115], v[160:163], v[212:215], v[112:115]
	v_mfma_f32_16x16x32_bf16 v[124:127], v[152:155], v[220:223], v[124:127]
	v_mfma_f32_16x16x32_bf16 v[120:123], v[160:163], v[220:223], v[120:123]
	v_mfma_f32_16x16x32_bf16 v[76:79], v[164:167], v[192:195], v[76:79]
	v_mfma_f32_16x16x32_bf16 v[68:71], v[184:187], v[192:195], v[68:71]
	v_mfma_f32_16x16x32_bf16 v[72:75], v[164:167], v[200:203], v[72:75]
	v_mfma_f32_16x16x32_bf16 v[64:67], v[184:187], v[200:203], v[64:67]
	v_mfma_f32_16x16x32_bf16 v[88:91], v[164:167], v[208:211], v[88:91]
	v_mfma_f32_16x16x32_bf16 v[80:83], v[184:187], v[208:211], v[80:83]
	v_mfma_f32_16x16x32_bf16 v[104:107], v[164:167], v[216:219], v[104:107]
	v_mfma_f32_16x16x32_bf16 v[92:95], v[184:187], v[216:219], v[92:95]
	v_mfma_f32_16x16x32_bf16 v[76:79], v[180:183], v[196:199], v[76:79]
	v_mfma_f32_16x16x32_bf16 v[68:71], v[188:191], v[196:199], v[68:71]
	v_mfma_f32_16x16x32_bf16 v[72:75], v[180:183], v[204:207], v[72:75]
	v_mfma_f32_16x16x32_bf16 v[64:67], v[188:191], v[204:207], v[64:67]
	v_mfma_f32_16x16x32_bf16 v[88:91], v[180:183], v[212:215], v[88:91]
	v_mfma_f32_16x16x32_bf16 v[80:83], v[188:191], v[212:215], v[80:83]
	v_mfma_f32_16x16x32_bf16 v[104:107], v[180:183], v[220:223], v[104:107]
	v_mfma_f32_16x16x32_bf16 v[92:95], v[188:191], v[220:223], v[92:95]
	s_barrier
	s_add_i32 s51, s43, s35
	v_lshl_add_u64 v[168:169], s[26:27], 0, v[128:129]
	s_mov_b32 m0, s51
	ds_read_b128 v[192:195], v146 offset:16384
	ds_read_b128 v[196:199], v146 offset:17408
	ds_read_b128 v[200:203], v146 offset:18432
	ds_read_b128 v[204:207], v146 offset:19456
	ds_read_b128 v[208:211], v146 offset:20480
	ds_read_b128 v[212:215], v146 offset:21504
	ds_read_b128 v[216:219], v146 offset:22528
	ds_read_b128 v[220:223], v146 offset:23552
	global_load_lds_dwordx4 v[168:169], off
	s_add_i32 m0, s51, 0x2000
	s_add_u32 s52, s26, 0x40000
	v_lshl_add_u64 v[224:225], s[26:27], 0, v[130:131]
	s_addc_u32 s53, s27, 0
	s_add_i32 s51, s44, s35
	global_load_lds_dwordx4 v[224:225], off
	v_lshl_add_u64 v[226:227], s[52:53], 0, v[128:129]
	s_mov_b32 m0, s51
	v_lshl_add_u64 v[228:229], s[28:29], 0, v[130:131]
	global_load_lds_dwordx4 v[226:227], off
	v_lshl_add_u64 v[226:227], s[52:53], 0, v[130:131]
	s_add_i32 m0, s51, 0x2000
	s_nop 0
	global_load_lds_dwordx4 v[226:227], off
	v_lshl_add_u64 v[226:227], s[28:29], 0, v[128:129]
	s_mov_b32 m0, s11
	s_nop 0
	global_load_lds_dwordx4 v[226:227], off
	s_mov_b32 m0, s36
	s_nop 0
	global_load_lds_dwordx4 v[228:229], off
	s_waitcnt vmcnt(8)
	s_waitcnt lgkmcnt(0)
	s_barrier
	s_waitcnt lgkmcnt(0)
	v_mfma_f32_16x16x32_bf16 v[60:63], v[148:151], v[192:195], v[60:63]
	v_mfma_f32_16x16x32_bf16 v[56:59], v[156:159], v[192:195], v[56:59]
	v_mfma_f32_16x16x32_bf16 v[44:47], v[148:151], v[200:203], v[44:47]
	v_mfma_f32_16x16x32_bf16 v[40:43], v[156:159], v[200:203], v[40:43]
	v_mfma_f32_16x16x32_bf16 v[28:31], v[148:151], v[208:211], v[28:31]
	v_mfma_f32_16x16x32_bf16 v[24:27], v[156:159], v[208:211], v[24:27]
	v_mfma_f32_16x16x32_bf16 v[12:15], v[148:151], v[216:219], v[12:15]
	v_mfma_f32_16x16x32_bf16 v[8:11], v[156:159], v[216:219], v[8:11]
	v_mfma_f32_16x16x32_bf16 v[60:63], v[152:155], v[196:199], v[60:63]
	v_mfma_f32_16x16x32_bf16 v[56:59], v[160:163], v[196:199], v[56:59]
	v_mfma_f32_16x16x32_bf16 v[44:47], v[152:155], v[204:207], v[44:47]
	v_mfma_f32_16x16x32_bf16 v[40:43], v[160:163], v[204:207], v[40:43]
	v_mfma_f32_16x16x32_bf16 v[28:31], v[152:155], v[212:215], v[28:31]
	v_mfma_f32_16x16x32_bf16 v[24:27], v[160:163], v[212:215], v[24:27]
	v_mfma_f32_16x16x32_bf16 v[12:15], v[152:155], v[220:223], v[12:15]
	v_mfma_f32_16x16x32_bf16 v[8:11], v[160:163], v[220:223], v[8:11]
	v_mfma_f32_16x16x32_bf16 v[52:55], v[164:167], v[192:195], v[52:55]
	v_mfma_f32_16x16x32_bf16 v[48:51], v[184:187], v[192:195], v[48:51]
	v_mfma_f32_16x16x32_bf16 v[36:39], v[164:167], v[200:203], v[36:39]
	v_mfma_f32_16x16x32_bf16 v[32:35], v[184:187], v[200:203], v[32:35]
	v_mfma_f32_16x16x32_bf16 v[20:23], v[164:167], v[208:211], v[20:23]
	v_mfma_f32_16x16x32_bf16 v[16:19], v[184:187], v[208:211], v[16:19]
	v_mfma_f32_16x16x32_bf16 v[4:7], v[164:167], v[216:219], v[4:7]
	v_mfma_f32_16x16x32_bf16 v[0:3], v[184:187], v[216:219], v[0:3]
	v_mfma_f32_16x16x32_bf16 v[52:55], v[180:183], v[196:199], v[52:55]
	v_mfma_f32_16x16x32_bf16 v[48:51], v[188:191], v[196:199], v[48:51]
	v_mfma_f32_16x16x32_bf16 v[36:39], v[180:183], v[204:207], v[36:39]
	v_mfma_f32_16x16x32_bf16 v[32:35], v[188:191], v[204:207], v[32:35]
	v_mfma_f32_16x16x32_bf16 v[20:23], v[180:183], v[212:215], v[20:23]
	v_mfma_f32_16x16x32_bf16 v[16:19], v[188:191], v[212:215], v[16:19]
	v_mfma_f32_16x16x32_bf16 v[4:7], v[180:183], v[220:223], v[4:7]
	v_mfma_f32_16x16x32_bf16 v[0:3], v[188:191], v[220:223], v[0:3]
	s_barrier
	s_add_i32 s51, 0, 0x18000
	v_add_u32_e32 v147, s51, v145
	s_add_i32 s52, 0, 0x1c000
	ds_read_b128 v[148:151], v147
	ds_read_b128 v[152:155], v147 offset:1024
	ds_read_b128 v[156:159], v147 offset:2048
	ds_read_b128 v[160:163], v147 offset:3072
	v_add_u32_e32 v147, s52, v145
	ds_read_b128 v[164:167], v147
	ds_read_b128 v[180:183], v147 offset:1024
	ds_read_b128 v[184:187], v147 offset:2048
	ds_read_b128 v[188:191], v147 offset:3072
	s_add_u32 s28, s28, 0x40000
	s_addc_u32 s29, s29, 0
	s_mov_b32 m0, s37
	v_lshl_add_u64 v[230:231], s[28:29], 0, v[128:129]
	ds_read_b128 v[192:195], v146 offset:32768
	ds_read_b128 v[196:199], v146 offset:33792
	ds_read_b128 v[200:203], v146 offset:34816
	ds_read_b128 v[204:207], v146 offset:35840
	ds_read_b128 v[208:211], v146 offset:36864
	ds_read_b128 v[212:215], v146 offset:37888
	ds_read_b128 v[216:219], v146 offset:38912
	ds_read_b128 v[220:223], v146 offset:39936
	global_load_lds_dwordx4 v[230:231], off
	v_lshl_add_u64 v[230:231], s[28:29], 0, v[130:131]
	s_mov_b32 m0, s38
	s_nop 0
	global_load_lds_dwordx4 v[230:231], off
	s_waitcnt vmcnt(8)
	s_waitcnt lgkmcnt(0)
	s_barrier
	s_waitcnt lgkmcnt(0)
	v_mfma_f32_16x16x32_bf16 v[100:103], v[148:151], v[192:195], v[100:103]
	v_mfma_f32_16x16x32_bf16 v[96:99], v[156:159], v[192:195], v[96:99]
	v_mfma_f32_16x16x32_bf16 v[108:111], v[148:151], v[200:203], v[108:111]
	v_mfma_f32_16x16x32_bf16 v[84:87], v[156:159], v[200:203], v[84:87]
	v_mfma_f32_16x16x32_bf16 v[116:119], v[148:151], v[208:211], v[116:119]
	v_mfma_f32_16x16x32_bf16 v[112:115], v[156:159], v[208:211], v[112:115]
	v_mfma_f32_16x16x32_bf16 v[124:127], v[148:151], v[216:219], v[124:127]
	v_mfma_f32_16x16x32_bf16 v[120:123], v[156:159], v[216:219], v[120:123]
	v_mfma_f32_16x16x32_bf16 v[100:103], v[152:155], v[196:199], v[100:103]
	v_mfma_f32_16x16x32_bf16 v[96:99], v[160:163], v[196:199], v[96:99]
	v_mfma_f32_16x16x32_bf16 v[108:111], v[152:155], v[204:207], v[108:111]
	v_mfma_f32_16x16x32_bf16 v[84:87], v[160:163], v[204:207], v[84:87]
	v_mfma_f32_16x16x32_bf16 v[116:119], v[152:155], v[212:215], v[116:119]
	v_mfma_f32_16x16x32_bf16 v[112:115], v[160:163], v[212:215], v[112:115]
	v_mfma_f32_16x16x32_bf16 v[124:127], v[152:155], v[220:223], v[124:127]
	v_mfma_f32_16x16x32_bf16 v[120:123], v[160:163], v[220:223], v[120:123]
	v_mfma_f32_16x16x32_bf16 v[76:79], v[164:167], v[192:195], v[76:79]
	v_mfma_f32_16x16x32_bf16 v[68:71], v[184:187], v[192:195], v[68:71]
	v_mfma_f32_16x16x32_bf16 v[72:75], v[164:167], v[200:203], v[72:75]
	v_mfma_f32_16x16x32_bf16 v[64:67], v[184:187], v[200:203], v[64:67]
	v_mfma_f32_16x16x32_bf16 v[88:91], v[164:167], v[208:211], v[88:91]
	v_mfma_f32_16x16x32_bf16 v[80:83], v[184:187], v[208:211], v[80:83]
	v_mfma_f32_16x16x32_bf16 v[104:107], v[164:167], v[216:219], v[104:107]
	v_mfma_f32_16x16x32_bf16 v[92:95], v[184:187], v[216:219], v[92:95]
	v_mfma_f32_16x16x32_bf16 v[76:79], v[180:183], v[196:199], v[76:79]
	v_mfma_f32_16x16x32_bf16 v[68:71], v[188:191], v[196:199], v[68:71]
	v_mfma_f32_16x16x32_bf16 v[72:75], v[180:183], v[204:207], v[72:75]
	v_mfma_f32_16x16x32_bf16 v[64:67], v[188:191], v[204:207], v[64:67]
	v_mfma_f32_16x16x32_bf16 v[88:91], v[180:183], v[212:215], v[88:91]
	v_mfma_f32_16x16x32_bf16 v[80:83], v[188:191], v[212:215], v[80:83]
	v_mfma_f32_16x16x32_bf16 v[104:107], v[180:183], v[220:223], v[104:107]
	v_mfma_f32_16x16x32_bf16 v[92:95], v[188:191], v[220:223], v[92:95]
	s_barrier
	s_add_i32 s28, s51, s35
	v_lshl_add_u64 v[168:169], v[168:169], 0, s[14:15]
	s_mov_b32 m0, s28
	ds_read_b128 v[192:195], v146 offset:49152
	ds_read_b128 v[196:199], v146 offset:50176
	ds_read_b128 v[200:203], v146 offset:51200
	ds_read_b128 v[204:207], v146 offset:52224
	ds_read_b128 v[208:211], v146 offset:53248
	ds_read_b128 v[212:215], v146 offset:54272
	ds_read_b128 v[216:219], v146 offset:55296
	ds_read_b128 v[220:223], v146 offset:56320
	global_load_lds_dwordx4 v[168:169], off
	s_add_i32 m0, s28, 0x2000
	s_add_u32 s26, s26, 0x40080
	v_lshl_add_u64 v[168:169], v[224:225], 0, s[14:15]
	s_addc_u32 s27, s27, 0
	s_add_i32 s28, s52, s35
	global_load_lds_dwordx4 v[168:169], off
	v_lshl_add_u64 v[168:169], s[26:27], 0, v[128:129]
	s_mov_b32 m0, s28
	s_nop 0
	global_load_lds_dwordx4 v[168:169], off
	v_lshl_add_u64 v[168:169], s[26:27], 0, v[130:131]
	s_add_i32 m0, s28, 0x2000
	s_nop 0
	global_load_lds_dwordx4 v[168:169], off
	v_lshl_add_u64 v[168:169], v[226:227], 0, s[14:15]
	s_mov_b32 m0, s41
	s_nop 0
	global_load_lds_dwordx4 v[168:169], off
	v_lshl_add_u64 v[168:169], v[228:229], 0, s[14:15]
	s_mov_b32 m0, s42
	s_nop 0
	global_load_lds_dwordx4 v[168:169], off
	s_waitcnt vmcnt(8)
	s_waitcnt lgkmcnt(0)
	s_barrier
	s_waitcnt lgkmcnt(0)
	v_mfma_f32_16x16x32_bf16 v[60:63], v[148:151], v[192:195], v[60:63]
	v_mfma_f32_16x16x32_bf16 v[56:59], v[156:159], v[192:195], v[56:59]
	v_mfma_f32_16x16x32_bf16 v[44:47], v[148:151], v[200:203], v[44:47]
	v_mfma_f32_16x16x32_bf16 v[40:43], v[156:159], v[200:203], v[40:43]
	v_mfma_f32_16x16x32_bf16 v[28:31], v[148:151], v[208:211], v[28:31]
	v_mfma_f32_16x16x32_bf16 v[24:27], v[156:159], v[208:211], v[24:27]
	v_mfma_f32_16x16x32_bf16 v[12:15], v[148:151], v[216:219], v[12:15]
	v_mfma_f32_16x16x32_bf16 v[8:11], v[156:159], v[216:219], v[8:11]
	v_mfma_f32_16x16x32_bf16 v[60:63], v[152:155], v[196:199], v[60:63]
	v_mfma_f32_16x16x32_bf16 v[56:59], v[160:163], v[196:199], v[56:59]
	v_mfma_f32_16x16x32_bf16 v[44:47], v[152:155], v[204:207], v[44:47]
	v_mfma_f32_16x16x32_bf16 v[40:43], v[160:163], v[204:207], v[40:43]
	v_mfma_f32_16x16x32_bf16 v[28:31], v[152:155], v[212:215], v[28:31]
	v_mfma_f32_16x16x32_bf16 v[24:27], v[160:163], v[212:215], v[24:27]
	v_mfma_f32_16x16x32_bf16 v[12:15], v[152:155], v[220:223], v[12:15]
	v_mfma_f32_16x16x32_bf16 v[8:11], v[160:163], v[220:223], v[8:11]
	v_mfma_f32_16x16x32_bf16 v[52:55], v[164:167], v[192:195], v[52:55]
	v_mfma_f32_16x16x32_bf16 v[48:51], v[184:187], v[192:195], v[48:51]
	v_mfma_f32_16x16x32_bf16 v[36:39], v[164:167], v[200:203], v[36:39]
	v_mfma_f32_16x16x32_bf16 v[32:35], v[184:187], v[200:203], v[32:35]
	v_mfma_f32_16x16x32_bf16 v[20:23], v[164:167], v[208:211], v[20:23]
	v_mfma_f32_16x16x32_bf16 v[16:19], v[184:187], v[208:211], v[16:19]
	v_mfma_f32_16x16x32_bf16 v[4:7], v[164:167], v[216:219], v[4:7]
	v_mfma_f32_16x16x32_bf16 v[0:3], v[184:187], v[216:219], v[0:3]
	v_mfma_f32_16x16x32_bf16 v[52:55], v[180:183], v[196:199], v[52:55]
	v_mfma_f32_16x16x32_bf16 v[48:51], v[188:191], v[196:199], v[48:51]
	v_mfma_f32_16x16x32_bf16 v[36:39], v[180:183], v[204:207], v[36:39]
	v_mfma_f32_16x16x32_bf16 v[32:35], v[188:191], v[204:207], v[32:35]
	v_mfma_f32_16x16x32_bf16 v[20:23], v[180:183], v[212:215], v[20:23]
	v_mfma_f32_16x16x32_bf16 v[16:19], v[188:191], v[212:215], v[16:19]
	v_mfma_f32_16x16x32_bf16 v[4:7], v[180:183], v[220:223], v[4:7]
	v_mfma_f32_16x16x32_bf16 v[0:3], v[188:191], v[220:223], v[0:3]
	s_barrier
	s_add_i32 s50, s50, 2
	s_add_u32 s24, s24, 0x100
	s_addc_u32 s25, s25, 0
	s_cmp_gt_u32 s50, 13
	s_cbranch_scc0 .LBB0_778
	s_add_u32 s24, s46, 0xffffff00
	s_addc_u32 s25, s47, -1
	s_andn2_b64 vcc, exec, s[2:3]
	s_cbranch_vccnz .LBB0_781
	v_mov_b32_e32 v0, 0
	s_mov_b32 s4, s16
	s_mov_b32 s10, s18
	s_mov_b64 s[12:13], s[22:23]
	s_mov_b32 s40, s45
	v_mov_b32_e32 v1, v0
	v_mov_b32_e32 v2, v0
	v_mov_b32_e32 v3, v0
	v_mov_b32_e32 v4, v0
	v_mov_b32_e32 v5, v0
	v_mov_b32_e32 v6, v0
	v_mov_b32_e32 v7, v0
	v_mov_b32_e32 v16, v0
	v_mov_b32_e32 v17, v0
	v_mov_b32_e32 v18, v0
	v_mov_b32_e32 v19, v0
	v_mov_b32_e32 v20, v0
	v_mov_b32_e32 v21, v0
	v_mov_b32_e32 v22, v0
	v_mov_b32_e32 v23, v0
	v_mov_b32_e32 v32, v0
	v_mov_b32_e32 v33, v0
	v_mov_b32_e32 v34, v0
	v_mov_b32_e32 v35, v0
	v_mov_b32_e32 v36, v0
	v_mov_b32_e32 v37, v0
	v_mov_b32_e32 v38, v0
	v_mov_b32_e32 v39, v0
	v_mov_b32_e32 v48, v0
	v_mov_b32_e32 v49, v0
	v_mov_b32_e32 v50, v0
	v_mov_b32_e32 v51, v0
	v_mov_b32_e32 v52, v0
	v_mov_b32_e32 v53, v0
	v_mov_b32_e32 v54, v0
	v_mov_b32_e32 v55, v0
	v_mov_b32_e32 v8, v0
	v_mov_b32_e32 v9, v0
	v_mov_b32_e32 v10, v0
	v_mov_b32_e32 v11, v0
	v_mov_b32_e32 v12, v0
	v_mov_b32_e32 v13, v0
	v_mov_b32_e32 v14, v0
	v_mov_b32_e32 v15, v0
	v_mov_b32_e32 v24, v0
	v_mov_b32_e32 v25, v0
	v_mov_b32_e32 v26, v0
	v_mov_b32_e32 v27, v0
	v_mov_b32_e32 v28, v0
	v_mov_b32_e32 v29, v0
	v_mov_b32_e32 v30, v0
	v_mov_b32_e32 v31, v0
	v_mov_b32_e32 v40, v0
	v_mov_b32_e32 v41, v0
	v_mov_b32_e32 v42, v0
	v_mov_b32_e32 v43, v0
	v_mov_b32_e32 v44, v0
	v_mov_b32_e32 v45, v0
	v_mov_b32_e32 v46, v0
	v_mov_b32_e32 v47, v0
	v_mov_b32_e32 v56, v0
	v_mov_b32_e32 v57, v0
	v_mov_b32_e32 v58, v0
	v_mov_b32_e32 v59, v0
	v_mov_b32_e32 v60, v0
	v_mov_b32_e32 v61, v0
	v_mov_b32_e32 v62, v0
	v_mov_b32_e32 v63, v0
	v_mov_b32_e32 v92, v0
	v_mov_b32_e32 v93, v0
	v_mov_b32_e32 v94, v0
	v_mov_b32_e32 v95, v0
	v_mov_b32_e32 v104, v0
	v_mov_b32_e32 v105, v0
	v_mov_b32_e32 v106, v0
	v_mov_b32_e32 v107, v0
	v_mov_b32_e32 v80, v0
	v_mov_b32_e32 v81, v0
	v_mov_b32_e32 v82, v0
	v_mov_b32_e32 v83, v0
	v_mov_b32_e32 v88, v0
	v_mov_b32_e32 v89, v0
	v_mov_b32_e32 v90, v0
	v_mov_b32_e32 v91, v0
	v_mov_b32_e32 v64, v0
	v_mov_b32_e32 v65, v0
	v_mov_b32_e32 v66, v0
	v_mov_b32_e32 v67, v0
	v_mov_b32_e32 v72, v0
	v_mov_b32_e32 v73, v0
	v_mov_b32_e32 v74, v0
	v_mov_b32_e32 v75, v0
	v_mov_b32_e32 v68, v0
	v_mov_b32_e32 v69, v0
	v_mov_b32_e32 v70, v0
	v_mov_b32_e32 v71, v0
	v_mov_b32_e32 v76, v0
	v_mov_b32_e32 v77, v0
	v_mov_b32_e32 v78, v0
	v_mov_b32_e32 v79, v0
	v_mov_b32_e32 v120, v0
	v_mov_b32_e32 v121, v0
	v_mov_b32_e32 v122, v0
	v_mov_b32_e32 v123, v0
	v_mov_b32_e32 v124, v0
	v_mov_b32_e32 v125, v0
	v_mov_b32_e32 v126, v0
	v_mov_b32_e32 v127, v0
	v_mov_b32_e32 v112, v0
	v_mov_b32_e32 v113, v0
	v_mov_b32_e32 v114, v0
	v_mov_b32_e32 v115, v0
	v_mov_b32_e32 v116, v0
	v_mov_b32_e32 v117, v0
	v_mov_b32_e32 v118, v0
	v_mov_b32_e32 v119, v0
	v_mov_b32_e32 v84, v0
	v_mov_b32_e32 v85, v0
	v_mov_b32_e32 v86, v0
	v_mov_b32_e32 v87, v0
	v_mov_b32_e32 v108, v0
	v_mov_b32_e32 v109, v0
	v_mov_b32_e32 v110, v0
	v_mov_b32_e32 v111, v0
	v_mov_b32_e32 v96, v0
	v_mov_b32_e32 v97, v0
	v_mov_b32_e32 v98, v0
	v_mov_b32_e32 v99, v0
	v_mov_b32_e32 v100, v0
	v_mov_b32_e32 v101, v0
	v_mov_b32_e32 v102, v0
	v_mov_b32_e32 v103, v0
	s_branch .LBB0_782

.LBB0_942:
	ds_read_b128 v[150:153], v147
	ds_read_b128 v[154:157], v147 offset:1024
	ds_read_b128 v[158:161], v147 offset:2048
	ds_read_b128 v[162:165], v147 offset:3072
	ds_read_b128 v[166:169], v148
	ds_read_b128 v[180:183], v148 offset:1024
	ds_read_b128 v[184:187], v148 offset:2048
	ds_read_b128 v[188:191], v148 offset:3072
	s_add_u32 s24, s22, 0xfffc0080
	s_addc_u32 s25, s23, -1
	s_cmp_eq_u32 s48, 12
	s_cselect_b32 s27, s15, s25
	s_cselect_b32 s26, s44, s24
	s_cselect_b32 s25, s13, s47
	s_cselect_b32 s24, s45, s46
	v_lshl_add_u64 v[224:225], s[22:23], 0, v[136:137]
	s_add_i32 m0, s21, 0xc000
	ds_read_b128 v[192:195], v149
	ds_read_b128 v[196:199], v149 offset:1024
	ds_read_b128 v[200:203], v149 offset:2048
	ds_read_b128 v[204:207], v149 offset:3072
	ds_read_b128 v[208:211], v149 offset:4096
	ds_read_b128 v[212:215], v149 offset:5120
	ds_read_b128 v[216:219], v149 offset:6144
	ds_read_b128 v[220:223], v149 offset:7168
	global_load_lds_dwordx4 v[224:225], off
	v_lshl_add_u64 v[224:225], s[22:23], 0, v[138:139]
	s_add_i32 m0, s21, 0xe000
	s_nop 0
	global_load_lds_dwordx4 v[224:225], off
	s_waitcnt vmcnt(8)
	s_waitcnt lgkmcnt(0)
	s_barrier
	s_waitcnt lgkmcnt(0)
	v_mfma_f32_16x16x32_bf16 v[124:127], v[150:153], v[192:195], v[124:127]
	v_mfma_f32_16x16x32_bf16 v[120:123], v[158:161], v[192:195], v[120:123]
	v_mfma_f32_16x16x32_bf16 v[108:111], v[150:153], v[200:203], v[108:111]
	v_mfma_f32_16x16x32_bf16 v[104:107], v[158:161], v[200:203], v[104:107]
	v_mfma_f32_16x16x32_bf16 v[92:95], v[150:153], v[208:211], v[92:95]
	v_mfma_f32_16x16x32_bf16 v[88:91], v[158:161], v[208:211], v[88:91]
	v_mfma_f32_16x16x32_bf16 v[76:79], v[150:153], v[216:219], v[76:79]
	v_mfma_f32_16x16x32_bf16 v[72:75], v[158:161], v[216:219], v[72:75]
	v_mfma_f32_16x16x32_bf16 v[124:127], v[154:157], v[196:199], v[124:127]
	v_mfma_f32_16x16x32_bf16 v[120:123], v[162:165], v[196:199], v[120:123]
	v_mfma_f32_16x16x32_bf16 v[108:111], v[154:157], v[204:207], v[108:111]
	v_mfma_f32_16x16x32_bf16 v[104:107], v[162:165], v[204:207], v[104:107]
	v_mfma_f32_16x16x32_bf16 v[92:95], v[154:157], v[212:215], v[92:95]
	v_mfma_f32_16x16x32_bf16 v[88:91], v[162:165], v[212:215], v[88:91]
	v_mfma_f32_16x16x32_bf16 v[76:79], v[154:157], v[220:223], v[76:79]
	v_mfma_f32_16x16x32_bf16 v[72:75], v[162:165], v[220:223], v[72:75]
	v_mfma_f32_16x16x32_bf16 v[116:119], v[166:169], v[192:195], v[116:119]
	v_mfma_f32_16x16x32_bf16 v[112:115], v[184:187], v[192:195], v[112:115]
	v_mfma_f32_16x16x32_bf16 v[100:103], v[166:169], v[200:203], v[100:103]
	v_mfma_f32_16x16x32_bf16 v[96:99], v[184:187], v[200:203], v[96:99]
	v_mfma_f32_16x16x32_bf16 v[84:87], v[166:169], v[208:211], v[84:87]
	v_mfma_f32_16x16x32_bf16 v[80:83], v[184:187], v[208:211], v[80:83]
	v_mfma_f32_16x16x32_bf16 v[68:71], v[166:169], v[216:219], v[68:71]
	v_mfma_f32_16x16x32_bf16 v[64:67], v[184:187], v[216:219], v[64:67]
	v_mfma_f32_16x16x32_bf16 v[116:119], v[180:183], v[196:199], v[116:119]
	v_mfma_f32_16x16x32_bf16 v[112:115], v[188:191], v[196:199], v[112:115]
	v_mfma_f32_16x16x32_bf16 v[100:103], v[180:183], v[204:207], v[100:103]
	v_mfma_f32_16x16x32_bf16 v[96:99], v[188:191], v[204:207], v[96:99]
	v_mfma_f32_16x16x32_bf16 v[84:87], v[180:183], v[212:215], v[84:87]
	v_mfma_f32_16x16x32_bf16 v[80:83], v[188:191], v[212:215], v[80:83]
	v_mfma_f32_16x16x32_bf16 v[68:71], v[180:183], v[220:223], v[68:71]
	v_mfma_f32_16x16x32_bf16 v[64:67], v[188:191], v[220:223], v[64:67]
	s_barrier
	s_add_i32 s49, s40, s28
	v_lshl_add_u64 v[224:225], s[24:25], 0, v[130:131]
	s_mov_b32 m0, s49
	ds_read_b128 v[192:195], v149 offset:16384
	ds_read_b128 v[196:199], v149 offset:17408
	ds_read_b128 v[200:203], v149 offset:18432
	ds_read_b128 v[204:207], v149 offset:19456
	ds_read_b128 v[208:211], v149 offset:20480
	ds_read_b128 v[212:215], v149 offset:21504
	ds_read_b128 v[216:219], v149 offset:22528
	ds_read_b128 v[220:223], v149 offset:23552
	global_load_lds_dwordx4 v[224:225], off
	s_add_i32 m0, s49, 0x2000
	s_add_u32 s50, s24, 0x40000
	v_lshl_add_u64 v[226:227], s[24:25], 0, v[134:135]
	s_addc_u32 s51, s25, 0
	s_add_i32 s49, s41, s28
	global_load_lds_dwordx4 v[226:227], off
	v_lshl_add_u64 v[228:229], s[50:51], 0, v[130:131]
	s_mov_b32 m0, s49
	v_lshl_add_u64 v[230:231], s[26:27], 0, v[132:133]
	global_load_lds_dwordx4 v[228:229], off
	v_lshl_add_u64 v[228:229], s[50:51], 0, v[134:135]
	s_add_i32 m0, s49, 0x2000
	s_nop 0
	global_load_lds_dwordx4 v[228:229], off
	v_lshl_add_u64 v[228:229], s[26:27], 0, v[128:129]
	s_mov_b32 m0, s21
	s_nop 0
	global_load_lds_dwordx4 v[228:229], off
	s_mov_b32 m0, s31
	s_nop 0
	global_load_lds_dwordx4 v[230:231], off
	s_waitcnt vmcnt(8)
	s_waitcnt lgkmcnt(0)
	s_barrier
	s_waitcnt lgkmcnt(0)
	v_mfma_f32_16x16x32_bf16 v[60:63], v[150:153], v[192:195], v[60:63]
	v_mfma_f32_16x16x32_bf16 v[56:59], v[158:161], v[192:195], v[56:59]
	v_mfma_f32_16x16x32_bf16 v[44:47], v[150:153], v[200:203], v[44:47]
	v_mfma_f32_16x16x32_bf16 v[40:43], v[158:161], v[200:203], v[40:43]
	v_mfma_f32_16x16x32_bf16 v[28:31], v[150:153], v[208:211], v[28:31]
	v_mfma_f32_16x16x32_bf16 v[24:27], v[158:161], v[208:211], v[24:27]
	v_mfma_f32_16x16x32_bf16 v[12:15], v[150:153], v[216:219], v[12:15]
	v_mfma_f32_16x16x32_bf16 v[8:11], v[158:161], v[216:219], v[8:11]
	v_mfma_f32_16x16x32_bf16 v[60:63], v[154:157], v[196:199], v[60:63]
	v_mfma_f32_16x16x32_bf16 v[56:59], v[162:165], v[196:199], v[56:59]
	v_mfma_f32_16x16x32_bf16 v[44:47], v[154:157], v[204:207], v[44:47]
	v_mfma_f32_16x16x32_bf16 v[40:43], v[162:165], v[204:207], v[40:43]
	v_mfma_f32_16x16x32_bf16 v[28:31], v[154:157], v[212:215], v[28:31]
	v_mfma_f32_16x16x32_bf16 v[24:27], v[162:165], v[212:215], v[24:27]
	v_mfma_f32_16x16x32_bf16 v[12:15], v[154:157], v[220:223], v[12:15]
	v_mfma_f32_16x16x32_bf16 v[8:11], v[162:165], v[220:223], v[8:11]
	v_mfma_f32_16x16x32_bf16 v[52:55], v[166:169], v[192:195], v[52:55]
	v_mfma_f32_16x16x32_bf16 v[48:51], v[184:187], v[192:195], v[48:51]
	v_mfma_f32_16x16x32_bf16 v[36:39], v[166:169], v[200:203], v[36:39]
	v_mfma_f32_16x16x32_bf16 v[32:35], v[184:187], v[200:203], v[32:35]
	v_mfma_f32_16x16x32_bf16 v[20:23], v[166:169], v[208:211], v[20:23]
	v_mfma_f32_16x16x32_bf16 v[16:19], v[184:187], v[208:211], v[16:19]
	v_mfma_f32_16x16x32_bf16 v[4:7], v[166:169], v[216:219], v[4:7]
	v_mfma_f32_16x16x32_bf16 v[0:3], v[184:187], v[216:219], v[0:3]
	v_mfma_f32_16x16x32_bf16 v[52:55], v[180:183], v[196:199], v[52:55]
	v_mfma_f32_16x16x32_bf16 v[48:51], v[188:191], v[196:199], v[48:51]
	v_mfma_f32_16x16x32_bf16 v[36:39], v[180:183], v[204:207], v[36:39]
	v_mfma_f32_16x16x32_bf16 v[32:35], v[188:191], v[204:207], v[32:35]
	v_mfma_f32_16x16x32_bf16 v[20:23], v[180:183], v[212:215], v[20:23]
	v_mfma_f32_16x16x32_bf16 v[16:19], v[188:191], v[212:215], v[16:19]
	v_mfma_f32_16x16x32_bf16 v[4:7], v[180:183], v[220:223], v[4:7]
	v_mfma_f32_16x16x32_bf16 v[0:3], v[188:191], v[220:223], v[0:3]
	s_barrier
	s_add_i32 s49, 0, 0x18000
	s_add_i32 s50, 0, 0x1c000
	v_add_u32_e32 v162, s49, v145
	v_add_u32_e32 v179, s50, v145
	ds_read_b128 v[150:153], v162
	ds_read_b128 v[154:157], v162 offset:1024
	ds_read_b128 v[158:161], v162 offset:2048
	ds_read_b128 v[162:165], v162 offset:3072
	ds_read_b128 v[166:169], v179
	ds_read_b128 v[180:183], v179 offset:1024
	ds_read_b128 v[184:187], v179 offset:2048
	ds_read_b128 v[188:191], v179 offset:3072
	s_add_u32 s26, s26, 0x40000
	s_addc_u32 s27, s27, 0
	s_mov_b32 m0, s33
	v_lshl_add_u64 v[232:233], s[26:27], 0, v[128:129]
	ds_read_b128 v[192:195], v149 offset:32768
	ds_read_b128 v[196:199], v149 offset:33792
	ds_read_b128 v[200:203], v149 offset:34816
	ds_read_b128 v[204:207], v149 offset:35840
	ds_read_b128 v[208:211], v149 offset:36864
	ds_read_b128 v[212:215], v149 offset:37888
	ds_read_b128 v[216:219], v149 offset:38912
	ds_read_b128 v[220:223], v149 offset:39936
	global_load_lds_dwordx4 v[232:233], off
	v_lshl_add_u64 v[232:233], s[26:27], 0, v[132:133]
	s_mov_b32 m0, s34
	s_nop 0
	global_load_lds_dwordx4 v[232:233], off
	s_waitcnt vmcnt(8)
	s_waitcnt lgkmcnt(0)
	s_barrier
	s_waitcnt lgkmcnt(0)
	v_mfma_f32_16x16x32_bf16 v[124:127], v[150:153], v[192:195], v[124:127]
	v_mfma_f32_16x16x32_bf16 v[120:123], v[158:161], v[192:195], v[120:123]
	v_mfma_f32_16x16x32_bf16 v[108:111], v[150:153], v[200:203], v[108:111]
	v_mfma_f32_16x16x32_bf16 v[104:107], v[158:161], v[200:203], v[104:107]
	v_mfma_f32_16x16x32_bf16 v[92:95], v[150:153], v[208:211], v[92:95]
	v_mfma_f32_16x16x32_bf16 v[88:91], v[158:161], v[208:211], v[88:91]
	v_mfma_f32_16x16x32_bf16 v[76:79], v[150:153], v[216:219], v[76:79]
	v_mfma_f32_16x16x32_bf16 v[72:75], v[158:161], v[216:219], v[72:75]
	v_mfma_f32_16x16x32_bf16 v[124:127], v[154:157], v[196:199], v[124:127]
	v_mfma_f32_16x16x32_bf16 v[120:123], v[162:165], v[196:199], v[120:123]
	v_mfma_f32_16x16x32_bf16 v[108:111], v[154:157], v[204:207], v[108:111]
	v_mfma_f32_16x16x32_bf16 v[104:107], v[162:165], v[204:207], v[104:107]
	v_mfma_f32_16x16x32_bf16 v[92:95], v[154:157], v[212:215], v[92:95]
	v_mfma_f32_16x16x32_bf16 v[88:91], v[162:165], v[212:215], v[88:91]
	v_mfma_f32_16x16x32_bf16 v[76:79], v[154:157], v[220:223], v[76:79]
	v_mfma_f32_16x16x32_bf16 v[72:75], v[162:165], v[220:223], v[72:75]
	v_mfma_f32_16x16x32_bf16 v[116:119], v[166:169], v[192:195], v[116:119]
	v_mfma_f32_16x16x32_bf16 v[112:115], v[184:187], v[192:195], v[112:115]
	v_mfma_f32_16x16x32_bf16 v[100:103], v[166:169], v[200:203], v[100:103]
	v_mfma_f32_16x16x32_bf16 v[96:99], v[184:187], v[200:203], v[96:99]
	v_mfma_f32_16x16x32_bf16 v[84:87], v[166:169], v[208:211], v[84:87]
	v_mfma_f32_16x16x32_bf16 v[80:83], v[184:187], v[208:211], v[80:83]
	v_mfma_f32_16x16x32_bf16 v[68:71], v[166:169], v[216:219], v[68:71]
	v_mfma_f32_16x16x32_bf16 v[64:67], v[184:187], v[216:219], v[64:67]
	v_mfma_f32_16x16x32_bf16 v[116:119], v[180:183], v[196:199], v[116:119]
	v_mfma_f32_16x16x32_bf16 v[112:115], v[188:191], v[196:199], v[112:115]
	v_mfma_f32_16x16x32_bf16 v[100:103], v[180:183], v[204:207], v[100:103]
	v_mfma_f32_16x16x32_bf16 v[96:99], v[188:191], v[204:207], v[96:99]
	v_mfma_f32_16x16x32_bf16 v[84:87], v[180:183], v[212:215], v[84:87]
	v_mfma_f32_16x16x32_bf16 v[80:83], v[188:191], v[212:215], v[80:83]
	v_mfma_f32_16x16x32_bf16 v[68:71], v[180:183], v[220:223], v[68:71]
	v_mfma_f32_16x16x32_bf16 v[64:67], v[188:191], v[220:223], v[64:67]
	s_barrier
	s_add_i32 s26, s49, s28
	v_lshl_add_u64 v[224:225], v[224:225], 0, s[8:9]
	s_mov_b32 m0, s26
	ds_read_b128 v[192:195], v149 offset:49152
	ds_read_b128 v[196:199], v149 offset:50176
	ds_read_b128 v[200:203], v149 offset:51200
	ds_read_b128 v[204:207], v149 offset:52224
	ds_read_b128 v[208:211], v149 offset:53248
	ds_read_b128 v[212:215], v149 offset:54272
	ds_read_b128 v[216:219], v149 offset:55296
	ds_read_b128 v[220:223], v149 offset:56320
	global_load_lds_dwordx4 v[224:225], off
	s_add_i32 m0, s26, 0x2000
	s_add_u32 s24, s24, 0x40080
	v_lshl_add_u64 v[224:225], v[226:227], 0, s[8:9]
	s_addc_u32 s25, s25, 0
	s_add_i32 s26, s50, s28
	global_load_lds_dwordx4 v[224:225], off
	v_lshl_add_u64 v[224:225], s[24:25], 0, v[130:131]
	s_mov_b32 m0, s26
	s_nop 0
	global_load_lds_dwordx4 v[224:225], off
	v_lshl_add_u64 v[224:225], s[24:25], 0, v[134:135]
	s_add_i32 m0, s26, 0x2000
	s_nop 0
	global_load_lds_dwordx4 v[224:225], off
	v_lshl_add_u64 v[224:225], v[228:229], 0, s[8:9]
	s_mov_b32 m0, s37
	s_nop 0
	global_load_lds_dwordx4 v[224:225], off
	v_lshl_add_u64 v[224:225], v[230:231], 0, s[8:9]
	s_mov_b32 m0, s38
	s_nop 0
	global_load_lds_dwordx4 v[224:225], off
	s_waitcnt vmcnt(8)
	s_waitcnt lgkmcnt(0)
	s_barrier
	s_waitcnt lgkmcnt(0)
	v_mfma_f32_16x16x32_bf16 v[60:63], v[150:153], v[192:195], v[60:63]
	v_mfma_f32_16x16x32_bf16 v[56:59], v[158:161], v[192:195], v[56:59]
	v_mfma_f32_16x16x32_bf16 v[44:47], v[150:153], v[200:203], v[44:47]
	v_mfma_f32_16x16x32_bf16 v[40:43], v[158:161], v[200:203], v[40:43]
	v_mfma_f32_16x16x32_bf16 v[28:31], v[150:153], v[208:211], v[28:31]
	v_mfma_f32_16x16x32_bf16 v[24:27], v[158:161], v[208:211], v[24:27]
	v_mfma_f32_16x16x32_bf16 v[12:15], v[150:153], v[216:219], v[12:15]
	v_mfma_f32_16x16x32_bf16 v[8:11], v[158:161], v[216:219], v[8:11]
	v_mfma_f32_16x16x32_bf16 v[60:63], v[154:157], v[196:199], v[60:63]
	v_mfma_f32_16x16x32_bf16 v[56:59], v[162:165], v[196:199], v[56:59]
	v_mfma_f32_16x16x32_bf16 v[44:47], v[154:157], v[204:207], v[44:47]
	v_mfma_f32_16x16x32_bf16 v[40:43], v[162:165], v[204:207], v[40:43]
	v_mfma_f32_16x16x32_bf16 v[28:31], v[154:157], v[212:215], v[28:31]
	v_mfma_f32_16x16x32_bf16 v[24:27], v[162:165], v[212:215], v[24:27]
	v_mfma_f32_16x16x32_bf16 v[12:15], v[154:157], v[220:223], v[12:15]
	v_mfma_f32_16x16x32_bf16 v[8:11], v[162:165], v[220:223], v[8:11]
	v_mfma_f32_16x16x32_bf16 v[52:55], v[166:169], v[192:195], v[52:55]
	v_mfma_f32_16x16x32_bf16 v[48:51], v[184:187], v[192:195], v[48:51]
	v_mfma_f32_16x16x32_bf16 v[36:39], v[166:169], v[200:203], v[36:39]
	v_mfma_f32_16x16x32_bf16 v[32:35], v[184:187], v[200:203], v[32:35]
	v_mfma_f32_16x16x32_bf16 v[20:23], v[166:169], v[208:211], v[20:23]
	v_mfma_f32_16x16x32_bf16 v[16:19], v[184:187], v[208:211], v[16:19]
	v_mfma_f32_16x16x32_bf16 v[4:7], v[166:169], v[216:219], v[4:7]
	v_mfma_f32_16x16x32_bf16 v[0:3], v[184:187], v[216:219], v[0:3]
	v_mfma_f32_16x16x32_bf16 v[52:55], v[180:183], v[196:199], v[52:55]
	v_mfma_f32_16x16x32_bf16 v[48:51], v[188:191], v[196:199], v[48:51]
	v_mfma_f32_16x16x32_bf16 v[36:39], v[180:183], v[204:207], v[36:39]
	v_mfma_f32_16x16x32_bf16 v[32:35], v[188:191], v[204:207], v[32:35]
	v_mfma_f32_16x16x32_bf16 v[20:23], v[180:183], v[212:215], v[20:23]
	v_mfma_f32_16x16x32_bf16 v[16:19], v[188:191], v[212:215], v[16:19]
	v_mfma_f32_16x16x32_bf16 v[4:7], v[180:183], v[220:223], v[4:7]
	v_mfma_f32_16x16x32_bf16 v[0:3], v[188:191], v[220:223], v[0:3]
	s_barrier
	s_add_i32 s48, s48, 2
	s_add_u32 s22, s22, 0x100
	s_addc_u32 s23, s23, 0
	s_add_u32 s46, s46, 0x100
	s_addc_u32 s47, s47, 0
	s_cmp_gt_u32 s48, 13
	s_cbranch_scc0 .LBB0_942
	s_and_b64 vcc, exec, s[10:11]
	s_cbranch_vccz .LBB0_945
	s_barrier

.LBB0_1018:
	ds_read_b128 v[152:155], v149
	ds_read_b128 v[156:159], v149 offset:1024
	ds_read_b128 v[160:163], v149 offset:2048
	ds_read_b128 v[164:167], v149 offset:3072
	ds_read_b128 v[174:177], v150
	ds_read_b128 v[178:181], v150 offset:1024
	ds_read_b128 v[182:185], v150 offset:2048
	ds_read_b128 v[186:189], v150 offset:3072
	s_add_u32 s34, s30, 0xfff50080
	s_addc_u32 s35, s31, -1
	s_cmp_eq_u32 s60, 40
	s_cselect_b32 s37, s5, s35
	s_cselect_b32 s36, s4, s34
	s_cselect_b32 s35, s29, s57
	s_cselect_b32 s34, s28, s56
	v_lshl_add_u64 v[140:141], s[30:31], 0, v[132:133]
	s_add_i32 m0, s41, 0xc000
	ds_read_b128 v[190:193], v151
	ds_read_b128 v[194:197], v151 offset:1024
	ds_read_b128 v[198:201], v151 offset:2048
	ds_read_b128 v[202:205], v151 offset:3072
	ds_read_b128 v[206:209], v151 offset:4096
	ds_read_b128 v[210:213], v151 offset:5120
	ds_read_b128 v[214:217], v151 offset:6144
	ds_read_b128 v[218:221], v151 offset:7168
	global_load_lds_dwordx4 v[140:141], off
	v_lshl_add_u64 v[140:141], s[30:31], 0, v[134:135]
	s_add_i32 m0, s41, 0xe000
	s_nop 0
	global_load_lds_dwordx4 v[140:141], off
	s_waitcnt vmcnt(8)
	s_waitcnt lgkmcnt(0)
	s_barrier
	s_waitcnt lgkmcnt(0)
	v_mfma_f32_16x16x32_bf16 v[124:127], v[152:155], v[190:193], v[124:127]
	v_mfma_f32_16x16x32_bf16 v[120:123], v[160:163], v[190:193], v[120:123]
	v_mfma_f32_16x16x32_bf16 v[112:115], v[152:155], v[198:201], v[112:115]
	v_mfma_f32_16x16x32_bf16 v[108:111], v[160:163], v[198:201], v[108:111]
	v_mfma_f32_16x16x32_bf16 v[96:99], v[152:155], v[206:209], v[96:99]
	v_mfma_f32_16x16x32_bf16 v[92:95], v[160:163], v[206:209], v[92:95]
	v_mfma_f32_16x16x32_bf16 v[80:83], v[152:155], v[214:217], v[80:83]
	v_mfma_f32_16x16x32_bf16 v[76:79], v[160:163], v[214:217], v[76:79]
	v_mfma_f32_16x16x32_bf16 v[124:127], v[156:159], v[194:197], v[124:127]
	v_mfma_f32_16x16x32_bf16 v[120:123], v[164:167], v[194:197], v[120:123]
	v_mfma_f32_16x16x32_bf16 v[112:115], v[156:159], v[202:205], v[112:115]
	v_mfma_f32_16x16x32_bf16 v[108:111], v[164:167], v[202:205], v[108:111]
	v_mfma_f32_16x16x32_bf16 v[96:99], v[156:159], v[210:213], v[96:99]
	v_mfma_f32_16x16x32_bf16 v[92:95], v[164:167], v[210:213], v[92:95]
	v_mfma_f32_16x16x32_bf16 v[80:83], v[156:159], v[218:221], v[80:83]
	v_mfma_f32_16x16x32_bf16 v[76:79], v[164:167], v[218:221], v[76:79]
	v_mfma_f32_16x16x32_bf16 v[116:119], v[174:177], v[190:193], v[116:119]
	v_mfma_f32_16x16x32_bf16 v[104:107], v[182:185], v[190:193], v[104:107]
	v_mfma_f32_16x16x32_bf16 v[100:103], v[174:177], v[198:201], v[100:103]
	v_mfma_f32_16x16x32_bf16 v[88:91], v[182:185], v[198:201], v[88:91]
	v_mfma_f32_16x16x32_bf16 v[84:87], v[174:177], v[206:209], v[84:87]
	v_mfma_f32_16x16x32_bf16 v[72:75], v[182:185], v[206:209], v[72:75]
	v_mfma_f32_16x16x32_bf16 v[68:71], v[174:177], v[214:217], v[68:71]
	v_mfma_f32_16x16x32_bf16 v[64:67], v[182:185], v[214:217], v[64:67]
	v_mfma_f32_16x16x32_bf16 v[116:119], v[178:181], v[194:197], v[116:119]
	v_mfma_f32_16x16x32_bf16 v[104:107], v[186:189], v[194:197], v[104:107]
	v_mfma_f32_16x16x32_bf16 v[100:103], v[178:181], v[202:205], v[100:103]
	v_mfma_f32_16x16x32_bf16 v[88:91], v[186:189], v[202:205], v[88:91]
	v_mfma_f32_16x16x32_bf16 v[84:87], v[178:181], v[210:213], v[84:87]
	v_mfma_f32_16x16x32_bf16 v[72:75], v[186:189], v[210:213], v[72:75]
	v_mfma_f32_16x16x32_bf16 v[68:71], v[178:181], v[218:221], v[68:71]
	v_mfma_f32_16x16x32_bf16 v[64:67], v[186:189], v[218:221], v[64:67]
	s_barrier
	s_add_i32 s61, s50, s40
	v_lshl_add_u64 v[140:141], s[34:35], 0, v[128:129]
	s_mov_b32 m0, s61
	ds_read_b128 v[190:193], v151 offset:16384
	ds_read_b128 v[194:197], v151 offset:17408
	ds_read_b128 v[198:201], v151 offset:18432
	ds_read_b128 v[202:205], v151 offset:19456
	ds_read_b128 v[206:209], v151 offset:20480
	ds_read_b128 v[210:213], v151 offset:21504
	ds_read_b128 v[214:217], v151 offset:22528
	ds_read_b128 v[218:221], v151 offset:23552
	global_load_lds_dwordx4 v[140:141], off
	s_add_i32 m0, s61, 0x2000
	s_add_u32 s62, s34, 0xb0000
	v_lshl_add_u64 v[168:169], s[34:35], 0, v[130:131]
	s_addc_u32 s63, s35, 0
	s_add_i32 s61, s51, s40
	global_load_lds_dwordx4 v[168:169], off
	v_lshl_add_u64 v[222:223], s[62:63], 0, v[128:129]
	s_mov_b32 m0, s61
	v_lshl_add_u64 v[224:225], s[36:37], 0, v[130:131]
	global_load_lds_dwordx4 v[222:223], off
	v_lshl_add_u64 v[222:223], s[62:63], 0, v[130:131]
	s_add_i32 m0, s61, 0x2000
	s_nop 0
	global_load_lds_dwordx4 v[222:223], off
	v_lshl_add_u64 v[222:223], s[36:37], 0, v[128:129]
	s_mov_b32 m0, s41
	s_nop 0
	global_load_lds_dwordx4 v[222:223], off
	s_mov_b32 m0, s42
	s_nop 0
	global_load_lds_dwordx4 v[224:225], off
	s_waitcnt vmcnt(8)
	s_waitcnt lgkmcnt(0)
	s_barrier
	s_waitcnt lgkmcnt(0)
	v_mfma_f32_16x16x32_bf16 v[60:63], v[152:155], v[190:193], v[60:63]
	v_mfma_f32_16x16x32_bf16 v[56:59], v[160:163], v[190:193], v[56:59]
	v_mfma_f32_16x16x32_bf16 v[48:51], v[152:155], v[198:201], v[48:51]
	v_mfma_f32_16x16x32_bf16 v[44:47], v[160:163], v[198:201], v[44:47]
	v_mfma_f32_16x16x32_bf16 v[32:35], v[152:155], v[206:209], v[32:35]
	v_mfma_f32_16x16x32_bf16 v[28:31], v[160:163], v[206:209], v[28:31]
	v_mfma_f32_16x16x32_bf16 v[16:19], v[152:155], v[214:217], v[16:19]
	v_mfma_f32_16x16x32_bf16 v[8:11], v[160:163], v[214:217], v[8:11]
	v_mfma_f32_16x16x32_bf16 v[60:63], v[156:159], v[194:197], v[60:63]
	v_mfma_f32_16x16x32_bf16 v[56:59], v[164:167], v[194:197], v[56:59]
	v_mfma_f32_16x16x32_bf16 v[48:51], v[156:159], v[202:205], v[48:51]
	v_mfma_f32_16x16x32_bf16 v[44:47], v[164:167], v[202:205], v[44:47]
	v_mfma_f32_16x16x32_bf16 v[32:35], v[156:159], v[210:213], v[32:35]
	v_mfma_f32_16x16x32_bf16 v[28:31], v[164:167], v[210:213], v[28:31]
	v_mfma_f32_16x16x32_bf16 v[16:19], v[156:159], v[218:221], v[16:19]
	v_mfma_f32_16x16x32_bf16 v[8:11], v[164:167], v[218:221], v[8:11]
	v_mfma_f32_16x16x32_bf16 v[52:55], v[174:177], v[190:193], v[52:55]
	v_mfma_f32_16x16x32_bf16 v[40:43], v[182:185], v[190:193], v[40:43]
	v_mfma_f32_16x16x32_bf16 v[36:39], v[174:177], v[198:201], v[36:39]
	v_mfma_f32_16x16x32_bf16 v[24:27], v[182:185], v[198:201], v[24:27]
	v_mfma_f32_16x16x32_bf16 v[20:23], v[174:177], v[206:209], v[20:23]
	v_mfma_f32_16x16x32_bf16 v[12:15], v[182:185], v[206:209], v[12:15]
	v_mfma_f32_16x16x32_bf16 v[4:7], v[174:177], v[214:217], v[4:7]
	v_mfma_f32_16x16x32_bf16 v[0:3], v[182:185], v[214:217], v[0:3]
	v_mfma_f32_16x16x32_bf16 v[52:55], v[178:181], v[194:197], v[52:55]
	v_mfma_f32_16x16x32_bf16 v[40:43], v[186:189], v[194:197], v[40:43]
	v_mfma_f32_16x16x32_bf16 v[36:39], v[178:181], v[202:205], v[36:39]
	v_mfma_f32_16x16x32_bf16 v[24:27], v[186:189], v[202:205], v[24:27]
	v_mfma_f32_16x16x32_bf16 v[20:23], v[178:181], v[210:213], v[20:23]
	v_mfma_f32_16x16x32_bf16 v[12:15], v[186:189], v[210:213], v[12:15]
	v_mfma_f32_16x16x32_bf16 v[4:7], v[178:181], v[218:221], v[4:7]
	v_mfma_f32_16x16x32_bf16 v[0:3], v[186:189], v[218:221], v[0:3]
	s_barrier
	s_add_i32 s61, 0, 0x18000
	s_add_i32 s62, 0, 0x1c000
	v_add_u32_e32 v164, s61, v147
	v_add_u32_e32 v186, s62, v147
	ds_read_b128 v[152:155], v164
	ds_read_b128 v[156:159], v164 offset:1024
	ds_read_b128 v[160:163], v164 offset:2048
	ds_read_b128 v[164:167], v164 offset:3072
	ds_read_b128 v[174:177], v186
	ds_read_b128 v[178:181], v186 offset:1024
	ds_read_b128 v[182:185], v186 offset:2048
	ds_read_b128 v[186:189], v186 offset:3072
	s_add_u32 s36, s36, 0xb0000
	s_addc_u32 s37, s37, 0
	s_mov_b32 m0, s43
	v_lshl_add_u64 v[226:227], s[36:37], 0, v[128:129]
	ds_read_b128 v[190:193], v151 offset:32768
	ds_read_b128 v[194:197], v151 offset:33792
	ds_read_b128 v[198:201], v151 offset:34816
	ds_read_b128 v[202:205], v151 offset:35840
	ds_read_b128 v[206:209], v151 offset:36864
	ds_read_b128 v[210:213], v151 offset:37888
	ds_read_b128 v[214:217], v151 offset:38912
	ds_read_b128 v[218:221], v151 offset:39936
	global_load_lds_dwordx4 v[226:227], off
	v_lshl_add_u64 v[226:227], s[36:37], 0, v[130:131]
	s_mov_b32 m0, s44
	s_nop 0
	global_load_lds_dwordx4 v[226:227], off
	s_waitcnt vmcnt(8)
	s_waitcnt lgkmcnt(0)
	s_barrier
	s_waitcnt lgkmcnt(0)
	v_mfma_f32_16x16x32_bf16 v[124:127], v[152:155], v[190:193], v[124:127]
	v_mfma_f32_16x16x32_bf16 v[120:123], v[160:163], v[190:193], v[120:123]
	v_mfma_f32_16x16x32_bf16 v[112:115], v[152:155], v[198:201], v[112:115]
	v_mfma_f32_16x16x32_bf16 v[108:111], v[160:163], v[198:201], v[108:111]
	v_mfma_f32_16x16x32_bf16 v[96:99], v[152:155], v[206:209], v[96:99]
	v_mfma_f32_16x16x32_bf16 v[92:95], v[160:163], v[206:209], v[92:95]
	v_mfma_f32_16x16x32_bf16 v[80:83], v[152:155], v[214:217], v[80:83]
	v_mfma_f32_16x16x32_bf16 v[76:79], v[160:163], v[214:217], v[76:79]
	v_mfma_f32_16x16x32_bf16 v[124:127], v[156:159], v[194:197], v[124:127]
	v_mfma_f32_16x16x32_bf16 v[120:123], v[164:167], v[194:197], v[120:123]
	v_mfma_f32_16x16x32_bf16 v[112:115], v[156:159], v[202:205], v[112:115]
	v_mfma_f32_16x16x32_bf16 v[108:111], v[164:167], v[202:205], v[108:111]
	v_mfma_f32_16x16x32_bf16 v[96:99], v[156:159], v[210:213], v[96:99]
	v_mfma_f32_16x16x32_bf16 v[92:95], v[164:167], v[210:213], v[92:95]
	v_mfma_f32_16x16x32_bf16 v[80:83], v[156:159], v[218:221], v[80:83]
	v_mfma_f32_16x16x32_bf16 v[76:79], v[164:167], v[218:221], v[76:79]
	v_mfma_f32_16x16x32_bf16 v[116:119], v[174:177], v[190:193], v[116:119]
	v_mfma_f32_16x16x32_bf16 v[104:107], v[182:185], v[190:193], v[104:107]
	v_mfma_f32_16x16x32_bf16 v[100:103], v[174:177], v[198:201], v[100:103]
	v_mfma_f32_16x16x32_bf16 v[88:91], v[182:185], v[198:201], v[88:91]
	v_mfma_f32_16x16x32_bf16 v[84:87], v[174:177], v[206:209], v[84:87]
	v_mfma_f32_16x16x32_bf16 v[72:75], v[182:185], v[206:209], v[72:75]
	v_mfma_f32_16x16x32_bf16 v[68:71], v[174:177], v[214:217], v[68:71]
	v_mfma_f32_16x16x32_bf16 v[64:67], v[182:185], v[214:217], v[64:67]
	v_mfma_f32_16x16x32_bf16 v[116:119], v[178:181], v[194:197], v[116:119]
	v_mfma_f32_16x16x32_bf16 v[104:107], v[186:189], v[194:197], v[104:107]
	v_mfma_f32_16x16x32_bf16 v[100:103], v[178:181], v[202:205], v[100:103]
	v_mfma_f32_16x16x32_bf16 v[88:91], v[186:189], v[202:205], v[88:91]
	v_mfma_f32_16x16x32_bf16 v[84:87], v[178:181], v[210:213], v[84:87]
	v_mfma_f32_16x16x32_bf16 v[72:75], v[186:189], v[210:213], v[72:75]
	v_mfma_f32_16x16x32_bf16 v[68:71], v[178:181], v[218:221], v[68:71]
	v_mfma_f32_16x16x32_bf16 v[64:67], v[186:189], v[218:221], v[64:67]
	s_barrier
	s_add_i32 s36, s61, s40
	v_lshl_add_u64 v[140:141], v[140:141], 0, s[16:17]
	s_mov_b32 m0, s36
	ds_read_b128 v[190:193], v151 offset:49152
	ds_read_b128 v[194:197], v151 offset:50176
	ds_read_b128 v[198:201], v151 offset:51200
	ds_read_b128 v[202:205], v151 offset:52224
	ds_read_b128 v[206:209], v151 offset:53248
	ds_read_b128 v[210:213], v151 offset:54272
	ds_read_b128 v[214:217], v151 offset:55296
	ds_read_b128 v[218:221], v151 offset:56320
	global_load_lds_dwordx4 v[140:141], off
	s_add_i32 m0, s36, 0x2000
	s_add_u32 s34, s34, 0xb0080
	v_lshl_add_u64 v[140:141], v[168:169], 0, s[16:17]
	s_addc_u32 s35, s35, 0
	s_add_i32 s36, s62, s40
	global_load_lds_dwordx4 v[140:141], off
	v_lshl_add_u64 v[140:141], s[34:35], 0, v[128:129]
	s_mov_b32 m0, s36
	s_nop 0
	global_load_lds_dwordx4 v[140:141], off
	v_lshl_add_u64 v[140:141], s[34:35], 0, v[130:131]
	s_add_i32 m0, s36, 0x2000
	s_nop 0
	global_load_lds_dwordx4 v[140:141], off
	v_lshl_add_u64 v[140:141], v[222:223], 0, s[16:17]
	s_mov_b32 m0, s47
	s_nop 0
	global_load_lds_dwordx4 v[140:141], off
	v_lshl_add_u64 v[140:141], v[224:225], 0, s[16:17]
	s_mov_b32 m0, s48
	s_nop 0
	global_load_lds_dwordx4 v[140:141], off
	s_waitcnt vmcnt(8)
	s_waitcnt lgkmcnt(0)
	s_barrier
	s_waitcnt lgkmcnt(0)
	v_mfma_f32_16x16x32_bf16 v[60:63], v[152:155], v[190:193], v[60:63]
	v_mfma_f32_16x16x32_bf16 v[56:59], v[160:163], v[190:193], v[56:59]
	v_mfma_f32_16x16x32_bf16 v[48:51], v[152:155], v[198:201], v[48:51]
	v_mfma_f32_16x16x32_bf16 v[44:47], v[160:163], v[198:201], v[44:47]
	v_mfma_f32_16x16x32_bf16 v[32:35], v[152:155], v[206:209], v[32:35]
	v_mfma_f32_16x16x32_bf16 v[28:31], v[160:163], v[206:209], v[28:31]
	v_mfma_f32_16x16x32_bf16 v[16:19], v[152:155], v[214:217], v[16:19]
	v_mfma_f32_16x16x32_bf16 v[8:11], v[160:163], v[214:217], v[8:11]
	v_mfma_f32_16x16x32_bf16 v[60:63], v[156:159], v[194:197], v[60:63]
	v_mfma_f32_16x16x32_bf16 v[56:59], v[164:167], v[194:197], v[56:59]
	v_mfma_f32_16x16x32_bf16 v[48:51], v[156:159], v[202:205], v[48:51]
	v_mfma_f32_16x16x32_bf16 v[44:47], v[164:167], v[202:205], v[44:47]
	v_mfma_f32_16x16x32_bf16 v[32:35], v[156:159], v[210:213], v[32:35]
	v_mfma_f32_16x16x32_bf16 v[28:31], v[164:167], v[210:213], v[28:31]
	v_mfma_f32_16x16x32_bf16 v[16:19], v[156:159], v[218:221], v[16:19]
	v_mfma_f32_16x16x32_bf16 v[8:11], v[164:167], v[218:221], v[8:11]
	v_mfma_f32_16x16x32_bf16 v[52:55], v[174:177], v[190:193], v[52:55]
	v_mfma_f32_16x16x32_bf16 v[40:43], v[182:185], v[190:193], v[40:43]
	v_mfma_f32_16x16x32_bf16 v[36:39], v[174:177], v[198:201], v[36:39]
	v_mfma_f32_16x16x32_bf16 v[24:27], v[182:185], v[198:201], v[24:27]
	v_mfma_f32_16x16x32_bf16 v[20:23], v[174:177], v[206:209], v[20:23]
	v_mfma_f32_16x16x32_bf16 v[12:15], v[182:185], v[206:209], v[12:15]
	v_mfma_f32_16x16x32_bf16 v[4:7], v[174:177], v[214:217], v[4:7]
	v_mfma_f32_16x16x32_bf16 v[0:3], v[182:185], v[214:217], v[0:3]
	v_mfma_f32_16x16x32_bf16 v[52:55], v[178:181], v[194:197], v[52:55]
	v_mfma_f32_16x16x32_bf16 v[40:43], v[186:189], v[194:197], v[40:43]
	v_mfma_f32_16x16x32_bf16 v[36:39], v[178:181], v[202:205], v[36:39]
	v_mfma_f32_16x16x32_bf16 v[24:27], v[186:189], v[202:205], v[24:27]
	v_mfma_f32_16x16x32_bf16 v[20:23], v[178:181], v[210:213], v[20:23]
	v_mfma_f32_16x16x32_bf16 v[12:15], v[186:189], v[210:213], v[12:15]
	v_mfma_f32_16x16x32_bf16 v[4:7], v[178:181], v[218:221], v[4:7]
	v_mfma_f32_16x16x32_bf16 v[0:3], v[186:189], v[218:221], v[0:3]
	s_barrier
	s_add_i32 s60, s60, 2
	s_add_u32 s30, s30, 0x100
	s_addc_u32 s31, s31, 0
	s_add_u32 s56, s56, 0x100
	s_addc_u32 s57, s57, 0
	s_cmp_gt_u32 s60, 41
	s_cbranch_scc0 .LBB0_1018
	s_and_b64 vcc, exec, s[18:19]
	s_cbranch_vccz .LBB0_1021
	s_barrier

.LBB0_1042:
	v_add_u32_e32 v147, s39, v146
	ds_read_b128 v[148:151], v147
	ds_read_b128 v[152:155], v147 offset:1024
	ds_read_b128 v[156:159], v147 offset:2048
	ds_read_b128 v[164:167], v147 offset:3072
	v_add_u32_e32 v147, s40, v146
	s_add_u32 s20, s12, s18
	ds_read_b128 v[174:177], v147
	ds_read_b128 v[178:181], v147 offset:1024
	ds_read_b128 v[182:185], v147 offset:2048
	ds_read_b128 v[186:189], v147 offset:3072
	s_addc_u32 s21, s13, s19
	s_add_u32 s20, s20, 0x100
	s_addc_u32 s21, s21, 0
	s_add_u32 s47, s44, s18
	s_addc_u32 s48, s45, s19
	s_cmpk_eq_i32 s18, 0x1500
	s_cselect_b32 s23, s17, s21
	s_cselect_b32 s22, s16, s20
	s_cselect_b32 s21, s5, s48
	s_cselect_b32 s20, s4, s47
	v_lshl_add_u64 v[160:161], v[140:141], 0, s[18:19]
	s_add_i32 m0, s29, 0xc000
	ds_read_b128 v[190:193], v144
	ds_read_b128 v[194:197], v144 offset:1024
	ds_read_b128 v[198:201], v144 offset:2048
	ds_read_b128 v[202:205], v144 offset:3072
	ds_read_b128 v[206:209], v144 offset:4096
	ds_read_b128 v[210:213], v144 offset:5120
	ds_read_b128 v[214:217], v144 offset:6144
	ds_read_b128 v[218:221], v144 offset:7168
	global_load_lds_dwordx4 v[160:161], off
	v_lshl_add_u64 v[160:161], v[142:143], 0, s[18:19]
	s_add_i32 m0, s29, 0xe000
	s_nop 0
	global_load_lds_dwordx4 v[160:161], off
	s_waitcnt vmcnt(8)
	s_waitcnt lgkmcnt(0)
	s_barrier
	s_waitcnt lgkmcnt(0)
	v_mfma_f32_16x16x32_bf16 v[124:127], v[148:151], v[190:193], v[124:127]
	v_mfma_f32_16x16x32_bf16 v[120:123], v[156:159], v[190:193], v[120:123]
	v_mfma_f32_16x16x32_bf16 v[116:119], v[148:151], v[198:201], v[116:119]
	v_mfma_f32_16x16x32_bf16 v[100:103], v[156:159], v[198:201], v[100:103]
	v_mfma_f32_16x16x32_bf16 v[104:107], v[148:151], v[206:209], v[104:107]
	v_mfma_f32_16x16x32_bf16 v[92:95], v[156:159], v[206:209], v[92:95]
	v_mfma_f32_16x16x32_bf16 v[96:99], v[148:151], v[214:217], v[96:99]
	v_mfma_f32_16x16x32_bf16 v[76:79], v[156:159], v[214:217], v[76:79]
	v_mfma_f32_16x16x32_bf16 v[124:127], v[152:155], v[194:197], v[124:127]
	v_mfma_f32_16x16x32_bf16 v[120:123], v[164:167], v[194:197], v[120:123]
	v_mfma_f32_16x16x32_bf16 v[116:119], v[152:155], v[202:205], v[116:119]
	v_mfma_f32_16x16x32_bf16 v[100:103], v[164:167], v[202:205], v[100:103]
	v_mfma_f32_16x16x32_bf16 v[104:107], v[152:155], v[210:213], v[104:107]
	v_mfma_f32_16x16x32_bf16 v[92:95], v[164:167], v[210:213], v[92:95]
	v_mfma_f32_16x16x32_bf16 v[96:99], v[152:155], v[218:221], v[96:99]
	v_mfma_f32_16x16x32_bf16 v[76:79], v[164:167], v[218:221], v[76:79]
	v_mfma_f32_16x16x32_bf16 v[112:115], v[174:177], v[190:193], v[112:115]
	v_mfma_f32_16x16x32_bf16 v[108:111], v[182:185], v[190:193], v[108:111]
	v_mfma_f32_16x16x32_bf16 v[88:91], v[174:177], v[198:201], v[88:91]
	v_mfma_f32_16x16x32_bf16 v[80:83], v[182:185], v[198:201], v[80:83]
	v_mfma_f32_16x16x32_bf16 v[84:87], v[174:177], v[206:209], v[84:87]
	v_mfma_f32_16x16x32_bf16 v[72:75], v[182:185], v[206:209], v[72:75]
	v_mfma_f32_16x16x32_bf16 v[68:71], v[174:177], v[214:217], v[68:71]
	v_mfma_f32_16x16x32_bf16 v[64:67], v[182:185], v[214:217], v[64:67]
	v_mfma_f32_16x16x32_bf16 v[112:115], v[178:181], v[194:197], v[112:115]
	v_mfma_f32_16x16x32_bf16 v[108:111], v[186:189], v[194:197], v[108:111]
	v_mfma_f32_16x16x32_bf16 v[88:91], v[178:181], v[202:205], v[88:91]
	v_mfma_f32_16x16x32_bf16 v[80:83], v[186:189], v[202:205], v[80:83]
	v_mfma_f32_16x16x32_bf16 v[84:87], v[178:181], v[210:213], v[84:87]
	v_mfma_f32_16x16x32_bf16 v[72:75], v[186:189], v[210:213], v[72:75]
	v_mfma_f32_16x16x32_bf16 v[68:71], v[178:181], v[218:221], v[68:71]
	v_mfma_f32_16x16x32_bf16 v[64:67], v[186:189], v[218:221], v[64:67]
	s_barrier
	s_add_i32 s47, s39, s28
	v_lshl_add_u64 v[160:161], s[20:21], 0, v[128:129]
	s_mov_b32 m0, s47
	ds_read_b128 v[190:193], v144 offset:16384
	ds_read_b128 v[194:197], v144 offset:17408
	ds_read_b128 v[198:201], v144 offset:18432
	ds_read_b128 v[202:205], v144 offset:19456
	ds_read_b128 v[206:209], v144 offset:20480
	ds_read_b128 v[210:213], v144 offset:21504
	ds_read_b128 v[214:217], v144 offset:22528
	ds_read_b128 v[218:221], v144 offset:23552
	global_load_lds_dwordx4 v[160:161], off
	s_add_i32 m0, s47, 0x2000
	s_add_u32 s48, s20, 0xb0000
	v_lshl_add_u64 v[168:169], s[20:21], 0, v[130:131]
	s_addc_u32 s49, s21, 0
	s_add_i32 s47, s40, s28
	global_load_lds_dwordx4 v[168:169], off
	v_lshl_add_u64 v[222:223], s[48:49], 0, v[128:129]
	s_mov_b32 m0, s47
	v_lshl_add_u64 v[224:225], s[22:23], 0, v[130:131]
	global_load_lds_dwordx4 v[222:223], off
	v_lshl_add_u64 v[222:223], s[48:49], 0, v[130:131]
	s_add_i32 m0, s47, 0x2000
	s_nop 0
	global_load_lds_dwordx4 v[222:223], off
	v_lshl_add_u64 v[222:223], s[22:23], 0, v[128:129]
	s_mov_b32 m0, s29
	s_nop 0
	global_load_lds_dwordx4 v[222:223], off
	s_mov_b32 m0, s30
	s_nop 0
	global_load_lds_dwordx4 v[224:225], off
	s_waitcnt vmcnt(8)
	s_waitcnt lgkmcnt(0)
	s_barrier
	s_waitcnt lgkmcnt(0)
	v_mfma_f32_16x16x32_bf16 v[60:63], v[148:151], v[190:193], v[60:63]
	v_mfma_f32_16x16x32_bf16 v[56:59], v[156:159], v[190:193], v[56:59]
	v_mfma_f32_16x16x32_bf16 v[44:47], v[148:151], v[198:201], v[44:47]
	v_mfma_f32_16x16x32_bf16 v[40:43], v[156:159], v[198:201], v[40:43]
	v_mfma_f32_16x16x32_bf16 v[28:31], v[148:151], v[206:209], v[28:31]
	v_mfma_f32_16x16x32_bf16 v[24:27], v[156:159], v[206:209], v[24:27]
	v_mfma_f32_16x16x32_bf16 v[12:15], v[148:151], v[214:217], v[12:15]
	v_mfma_f32_16x16x32_bf16 v[8:11], v[156:159], v[214:217], v[8:11]
	v_mfma_f32_16x16x32_bf16 v[60:63], v[152:155], v[194:197], v[60:63]
	v_mfma_f32_16x16x32_bf16 v[56:59], v[164:167], v[194:197], v[56:59]
	v_mfma_f32_16x16x32_bf16 v[44:47], v[152:155], v[202:205], v[44:47]
	v_mfma_f32_16x16x32_bf16 v[40:43], v[164:167], v[202:205], v[40:43]
	v_mfma_f32_16x16x32_bf16 v[28:31], v[152:155], v[210:213], v[28:31]
	v_mfma_f32_16x16x32_bf16 v[24:27], v[164:167], v[210:213], v[24:27]
	v_mfma_f32_16x16x32_bf16 v[12:15], v[152:155], v[218:221], v[12:15]
	v_mfma_f32_16x16x32_bf16 v[8:11], v[164:167], v[218:221], v[8:11]
	v_mfma_f32_16x16x32_bf16 v[52:55], v[174:177], v[190:193], v[52:55]
	v_mfma_f32_16x16x32_bf16 v[48:51], v[182:185], v[190:193], v[48:51]
	v_mfma_f32_16x16x32_bf16 v[36:39], v[174:177], v[198:201], v[36:39]
	v_mfma_f32_16x16x32_bf16 v[32:35], v[182:185], v[198:201], v[32:35]
	v_mfma_f32_16x16x32_bf16 v[20:23], v[174:177], v[206:209], v[20:23]
	v_mfma_f32_16x16x32_bf16 v[16:19], v[182:185], v[206:209], v[16:19]
	v_mfma_f32_16x16x32_bf16 v[4:7], v[174:177], v[214:217], v[4:7]
	v_mfma_f32_16x16x32_bf16 v[0:3], v[182:185], v[214:217], v[0:3]
	v_mfma_f32_16x16x32_bf16 v[52:55], v[178:181], v[194:197], v[52:55]
	v_mfma_f32_16x16x32_bf16 v[48:51], v[186:189], v[194:197], v[48:51]
	v_mfma_f32_16x16x32_bf16 v[36:39], v[178:181], v[202:205], v[36:39]
	v_mfma_f32_16x16x32_bf16 v[32:35], v[186:189], v[202:205], v[32:35]
	v_mfma_f32_16x16x32_bf16 v[20:23], v[178:181], v[210:213], v[20:23]
	v_mfma_f32_16x16x32_bf16 v[16:19], v[186:189], v[210:213], v[16:19]
	v_mfma_f32_16x16x32_bf16 v[4:7], v[178:181], v[218:221], v[4:7]
	v_mfma_f32_16x16x32_bf16 v[0:3], v[186:189], v[218:221], v[0:3]
	s_barrier
	s_add_i32 s47, 0, 0x18000
	v_add_u32_e32 v147, s47, v146
	s_add_i32 s48, 0, 0x1c000
	ds_read_b128 v[148:151], v147
	ds_read_b128 v[152:155], v147 offset:1024
	ds_read_b128 v[156:159], v147 offset:2048
	ds_read_b128 v[164:167], v147 offset:3072
	v_add_u32_e32 v147, s48, v146
	ds_read_b128 v[174:177], v147
	ds_read_b128 v[178:181], v147 offset:1024
	ds_read_b128 v[182:185], v147 offset:2048
	ds_read_b128 v[186:189], v147 offset:3072
	s_add_u32 s22, s22, 0xb0000
	s_addc_u32 s23, s23, 0
	s_mov_b32 m0, s31
	v_lshl_add_u64 v[226:227], s[22:23], 0, v[128:129]
	ds_read_b128 v[190:193], v144 offset:32768
	ds_read_b128 v[194:197], v144 offset:33792
	ds_read_b128 v[198:201], v144 offset:34816
	ds_read_b128 v[202:205], v144 offset:35840
	ds_read_b128 v[206:209], v144 offset:36864
	ds_read_b128 v[210:213], v144 offset:37888
	ds_read_b128 v[214:217], v144 offset:38912
	ds_read_b128 v[218:221], v144 offset:39936
	global_load_lds_dwordx4 v[226:227], off
	v_lshl_add_u64 v[226:227], s[22:23], 0, v[130:131]
	s_mov_b32 m0, s34
	s_nop 0
	global_load_lds_dwordx4 v[226:227], off
	s_waitcnt vmcnt(8)
	s_waitcnt lgkmcnt(0)
	s_barrier
	s_waitcnt lgkmcnt(0)
	v_mfma_f32_16x16x32_bf16 v[124:127], v[148:151], v[190:193], v[124:127]
	v_mfma_f32_16x16x32_bf16 v[120:123], v[156:159], v[190:193], v[120:123]
	v_mfma_f32_16x16x32_bf16 v[116:119], v[148:151], v[198:201], v[116:119]
	v_mfma_f32_16x16x32_bf16 v[100:103], v[156:159], v[198:201], v[100:103]
	v_mfma_f32_16x16x32_bf16 v[104:107], v[148:151], v[206:209], v[104:107]
	v_mfma_f32_16x16x32_bf16 v[92:95], v[156:159], v[206:209], v[92:95]
	v_mfma_f32_16x16x32_bf16 v[96:99], v[148:151], v[214:217], v[96:99]
	v_mfma_f32_16x16x32_bf16 v[76:79], v[156:159], v[214:217], v[76:79]
	v_mfma_f32_16x16x32_bf16 v[124:127], v[152:155], v[194:197], v[124:127]
	v_mfma_f32_16x16x32_bf16 v[120:123], v[164:167], v[194:197], v[120:123]
	v_mfma_f32_16x16x32_bf16 v[116:119], v[152:155], v[202:205], v[116:119]
	v_mfma_f32_16x16x32_bf16 v[100:103], v[164:167], v[202:205], v[100:103]
	v_mfma_f32_16x16x32_bf16 v[104:107], v[152:155], v[210:213], v[104:107]
	v_mfma_f32_16x16x32_bf16 v[92:95], v[164:167], v[210:213], v[92:95]
	v_mfma_f32_16x16x32_bf16 v[96:99], v[152:155], v[218:221], v[96:99]
	v_mfma_f32_16x16x32_bf16 v[76:79], v[164:167], v[218:221], v[76:79]
	v_mfma_f32_16x16x32_bf16 v[112:115], v[174:177], v[190:193], v[112:115]
	v_mfma_f32_16x16x32_bf16 v[108:111], v[182:185], v[190:193], v[108:111]
	v_mfma_f32_16x16x32_bf16 v[88:91], v[174:177], v[198:201], v[88:91]
	v_mfma_f32_16x16x32_bf16 v[80:83], v[182:185], v[198:201], v[80:83]
	v_mfma_f32_16x16x32_bf16 v[84:87], v[174:177], v[206:209], v[84:87]
	v_mfma_f32_16x16x32_bf16 v[72:75], v[182:185], v[206:209], v[72:75]
	v_mfma_f32_16x16x32_bf16 v[68:71], v[174:177], v[214:217], v[68:71]
	v_mfma_f32_16x16x32_bf16 v[64:67], v[182:185], v[214:217], v[64:67]
	v_mfma_f32_16x16x32_bf16 v[112:115], v[178:181], v[194:197], v[112:115]
	v_mfma_f32_16x16x32_bf16 v[108:111], v[186:189], v[194:197], v[108:111]
	v_mfma_f32_16x16x32_bf16 v[88:91], v[178:181], v[202:205], v[88:91]
	v_mfma_f32_16x16x32_bf16 v[80:83], v[186:189], v[202:205], v[80:83]
	v_mfma_f32_16x16x32_bf16 v[84:87], v[178:181], v[210:213], v[84:87]
	v_mfma_f32_16x16x32_bf16 v[72:75], v[186:189], v[210:213], v[72:75]
	v_mfma_f32_16x16x32_bf16 v[68:71], v[178:181], v[218:221], v[68:71]
	v_mfma_f32_16x16x32_bf16 v[64:67], v[186:189], v[218:221], v[64:67]
	s_barrier
	s_add_i32 s22, s47, s28
	v_lshl_add_u64 v[160:161], v[160:161], 0, s[14:15]
	s_mov_b32 m0, s22
	ds_read_b128 v[190:193], v144 offset:49152
	ds_read_b128 v[194:197], v144 offset:50176
	ds_read_b128 v[198:201], v144 offset:51200
	ds_read_b128 v[202:205], v144 offset:52224
	ds_read_b128 v[206:209], v144 offset:53248
	ds_read_b128 v[210:213], v144 offset:54272
	ds_read_b128 v[214:217], v144 offset:55296
	ds_read_b128 v[218:221], v144 offset:56320
	global_load_lds_dwordx4 v[160:161], off
	s_add_i32 m0, s22, 0x2000
	s_add_u32 s20, s20, 0xb0080
	v_lshl_add_u64 v[160:161], v[168:169], 0, s[14:15]
	s_addc_u32 s21, s21, 0
	s_add_i32 s22, s48, s28
	global_load_lds_dwordx4 v[160:161], off
	v_lshl_add_u64 v[160:161], s[20:21], 0, v[128:129]
	s_mov_b32 m0, s22
	s_nop 0
	global_load_lds_dwordx4 v[160:161], off
	v_lshl_add_u64 v[160:161], s[20:21], 0, v[130:131]
	s_add_i32 m0, s22, 0x2000
	s_nop 0
	global_load_lds_dwordx4 v[160:161], off
	v_lshl_add_u64 v[160:161], v[222:223], 0, s[14:15]
	s_mov_b32 m0, s37
	s_nop 0
	global_load_lds_dwordx4 v[160:161], off
	v_lshl_add_u64 v[160:161], v[224:225], 0, s[14:15]
	s_mov_b32 m0, s38
	s_nop 0
	global_load_lds_dwordx4 v[160:161], off
	s_waitcnt vmcnt(8)
	s_waitcnt lgkmcnt(0)
	s_barrier
	s_waitcnt lgkmcnt(0)
	v_mfma_f32_16x16x32_bf16 v[60:63], v[148:151], v[190:193], v[60:63]
	v_mfma_f32_16x16x32_bf16 v[56:59], v[156:159], v[190:193], v[56:59]
	v_mfma_f32_16x16x32_bf16 v[44:47], v[148:151], v[198:201], v[44:47]
	v_mfma_f32_16x16x32_bf16 v[40:43], v[156:159], v[198:201], v[40:43]
	v_mfma_f32_16x16x32_bf16 v[28:31], v[148:151], v[206:209], v[28:31]
	v_mfma_f32_16x16x32_bf16 v[24:27], v[156:159], v[206:209], v[24:27]
	v_mfma_f32_16x16x32_bf16 v[12:15], v[148:151], v[214:217], v[12:15]
	v_mfma_f32_16x16x32_bf16 v[8:11], v[156:159], v[214:217], v[8:11]
	v_mfma_f32_16x16x32_bf16 v[60:63], v[152:155], v[194:197], v[60:63]
	v_mfma_f32_16x16x32_bf16 v[56:59], v[164:167], v[194:197], v[56:59]
	v_mfma_f32_16x16x32_bf16 v[44:47], v[152:155], v[202:205], v[44:47]
	v_mfma_f32_16x16x32_bf16 v[40:43], v[164:167], v[202:205], v[40:43]
	v_mfma_f32_16x16x32_bf16 v[28:31], v[152:155], v[210:213], v[28:31]
	v_mfma_f32_16x16x32_bf16 v[24:27], v[164:167], v[210:213], v[24:27]
	v_mfma_f32_16x16x32_bf16 v[12:15], v[152:155], v[218:221], v[12:15]
	v_mfma_f32_16x16x32_bf16 v[8:11], v[164:167], v[218:221], v[8:11]
	v_mfma_f32_16x16x32_bf16 v[52:55], v[174:177], v[190:193], v[52:55]
	v_mfma_f32_16x16x32_bf16 v[48:51], v[182:185], v[190:193], v[48:51]
	v_mfma_f32_16x16x32_bf16 v[36:39], v[174:177], v[198:201], v[36:39]
	v_mfma_f32_16x16x32_bf16 v[32:35], v[182:185], v[198:201], v[32:35]
	v_mfma_f32_16x16x32_bf16 v[20:23], v[174:177], v[206:209], v[20:23]
	v_mfma_f32_16x16x32_bf16 v[16:19], v[182:185], v[206:209], v[16:19]
	v_mfma_f32_16x16x32_bf16 v[4:7], v[174:177], v[214:217], v[4:7]
	v_mfma_f32_16x16x32_bf16 v[0:3], v[182:185], v[214:217], v[0:3]
	v_mfma_f32_16x16x32_bf16 v[52:55], v[178:181], v[194:197], v[52:55]
	v_mfma_f32_16x16x32_bf16 v[48:51], v[186:189], v[194:197], v[48:51]
	v_mfma_f32_16x16x32_bf16 v[36:39], v[178:181], v[202:205], v[36:39]
	v_mfma_f32_16x16x32_bf16 v[32:35], v[186:189], v[202:205], v[32:35]
	v_mfma_f32_16x16x32_bf16 v[20:23], v[178:181], v[210:213], v[20:23]
	v_mfma_f32_16x16x32_bf16 v[16:19], v[186:189], v[210:213], v[16:19]
	v_mfma_f32_16x16x32_bf16 v[4:7], v[178:181], v[218:221], v[4:7]
	v_mfma_f32_16x16x32_bf16 v[0:3], v[186:189], v[218:221], v[0:3]
	s_barrier
	s_add_i32 s46, s46, 2
	s_add_u32 s18, s18, 0x100
	s_addc_u32 s19, s19, 0
	s_cmp_gt_u32 s46, 41
	s_cbranch_scc0 .LBB0_1042
	s_add_u32 s18, s44, 0xffffff00
	s_addc_u32 s19, s45, -1
	s_and_b64 vcc, exec, s[2:3]
	s_cbranch_vccnz .LBB0_1045
	v_mov_b32_e32 v0, 0
	s_mov_b32 s10, s41
	s_mov_b32 s24, s42
	s_mov_b64 s[12:13], s[16:17]
	s_mov_b32 s36, s43
	v_mov_b32_e32 v1, v0
	v_mov_b32_e32 v2, v0
	v_mov_b32_e32 v3, v0
	v_mov_b32_e32 v4, v0
	v_mov_b32_e32 v5, v0
	v_mov_b32_e32 v6, v0
	v_mov_b32_e32 v7, v0
	v_mov_b32_e32 v16, v0
	v_mov_b32_e32 v17, v0
	v_mov_b32_e32 v18, v0
	v_mov_b32_e32 v19, v0
	v_mov_b32_e32 v20, v0
	v_mov_b32_e32 v21, v0
	v_mov_b32_e32 v22, v0
	v_mov_b32_e32 v23, v0
	v_mov_b32_e32 v32, v0
	v_mov_b32_e32 v33, v0
	v_mov_b32_e32 v34, v0
	v_mov_b32_e32 v35, v0
	v_mov_b32_e32 v36, v0
	v_mov_b32_e32 v37, v0
	v_mov_b32_e32 v38, v0
	v_mov_b32_e32 v39, v0
	v_mov_b32_e32 v48, v0
	v_mov_b32_e32 v49, v0
	v_mov_b32_e32 v50, v0
	v_mov_b32_e32 v51, v0
	v_mov_b32_e32 v52, v0
	v_mov_b32_e32 v53, v0
	v_mov_b32_e32 v54, v0
	v_mov_b32_e32 v55, v0
	v_mov_b32_e32 v8, v0
	v_mov_b32_e32 v9, v0
	v_mov_b32_e32 v10, v0
	v_mov_b32_e32 v11, v0
	v_mov_b32_e32 v12, v0
	v_mov_b32_e32 v13, v0
	v_mov_b32_e32 v14, v0
	v_mov_b32_e32 v15, v0
	v_mov_b32_e32 v24, v0
	v_mov_b32_e32 v25, v0
	v_mov_b32_e32 v26, v0
	v_mov_b32_e32 v27, v0
	v_mov_b32_e32 v28, v0
	v_mov_b32_e32 v29, v0
	v_mov_b32_e32 v30, v0
	v_mov_b32_e32 v31, v0
	v_mov_b32_e32 v40, v0
	v_mov_b32_e32 v41, v0
	v_mov_b32_e32 v42, v0
	v_mov_b32_e32 v43, v0
	v_mov_b32_e32 v44, v0
	v_mov_b32_e32 v45, v0
	v_mov_b32_e32 v46, v0
	v_mov_b32_e32 v47, v0
	v_mov_b32_e32 v56, v0
	v_mov_b32_e32 v57, v0
	v_mov_b32_e32 v58, v0
	v_mov_b32_e32 v59, v0
	v_mov_b32_e32 v60, v0
	v_mov_b32_e32 v61, v0
	v_mov_b32_e32 v62, v0
	v_mov_b32_e32 v63, v0
	v_mov_b32_e32 v64, v0
	v_mov_b32_e32 v65, v0
	v_mov_b32_e32 v66, v0
	v_mov_b32_e32 v67, v0
	v_mov_b32_e32 v68, v0
	v_mov_b32_e32 v69, v0
	v_mov_b32_e32 v70, v0
	v_mov_b32_e32 v71, v0
	v_mov_b32_e32 v72, v0
	v_mov_b32_e32 v73, v0
	v_mov_b32_e32 v74, v0
	v_mov_b32_e32 v75, v0
	v_mov_b32_e32 v84, v0
	v_mov_b32_e32 v85, v0
	v_mov_b32_e32 v86, v0
	v_mov_b32_e32 v87, v0
	v_mov_b32_e32 v80, v0
	v_mov_b32_e32 v81, v0
	v_mov_b32_e32 v82, v0
	v_mov_b32_e32 v83, v0
	v_mov_b32_e32 v88, v0
	v_mov_b32_e32 v89, v0
	v_mov_b32_e32 v90, v0
	v_mov_b32_e32 v91, v0
	v_mov_b32_e32 v108, v0
	v_mov_b32_e32 v109, v0
	v_mov_b32_e32 v110, v0
	v_mov_b32_e32 v111, v0
	v_mov_b32_e32 v112, v0
	v_mov_b32_e32 v113, v0
	v_mov_b32_e32 v114, v0
	v_mov_b32_e32 v115, v0
	v_mov_b32_e32 v76, v0
	v_mov_b32_e32 v77, v0
	v_mov_b32_e32 v78, v0
	v_mov_b32_e32 v79, v0
	v_mov_b32_e32 v96, v0
	v_mov_b32_e32 v97, v0
	v_mov_b32_e32 v98, v0
	v_mov_b32_e32 v99, v0
	v_mov_b32_e32 v92, v0
	v_mov_b32_e32 v93, v0
	v_mov_b32_e32 v94, v0
	v_mov_b32_e32 v95, v0
	v_mov_b32_e32 v104, v0
	v_mov_b32_e32 v105, v0
	v_mov_b32_e32 v106, v0
	v_mov_b32_e32 v107, v0
	v_mov_b32_e32 v100, v0
	v_mov_b32_e32 v101, v0
	v_mov_b32_e32 v102, v0
	v_mov_b32_e32 v103, v0
	v_mov_b32_e32 v116, v0
	v_mov_b32_e32 v117, v0
	v_mov_b32_e32 v118, v0
	v_mov_b32_e32 v119, v0
	v_mov_b32_e32 v120, v0
	v_mov_b32_e32 v121, v0
	v_mov_b32_e32 v122, v0
	v_mov_b32_e32 v123, v0
	v_mov_b32_e32 v124, v0
	v_mov_b32_e32 v125, v0
	v_mov_b32_e32 v126, v0
	v_mov_b32_e32 v127, v0
	s_andn2_b64 vcc, exec, s[0:1]
	s_cbranch_vccnz .LBB0_1046
	s_branch .LBB0_1047
